# bundle: P2/P11 4x8 tile rounds + accumulator zeroing by 64-bit moves + MFMA segment edge tightening (setprio outside barriers)
# speedup vs baseline: 1.0113x; 1.0113x over previous
.LBB0_292:
	s_ashr_i32 s13, s12, 31
	s_lshl_b64 s[14:15], s[12:13], 20
	s_add_u32 s14, s19, s14
	s_addc_u32 s15, s22, s15
	s_and_b64 s[16:17], s[2:3], exec
	s_cselect_b32 s13, s15, s41
	s_cselect_b32 s74, s14, s40
	s_ashr_i32 s11, s10, 31
	s_lshl_b64 s[16:17], s[10:11], 20
	s_add_u32 s16, s23, s16
	s_addc_u32 s17, s28, s17
	s_and_b64 s[54:55], s[2:3], exec
	s_cselect_b32 s11, s17, s43
	s_cselect_b32 s75, s16, s42
	s_add_u32 s40, s40, 0x80080
	s_addc_u32 s41, s41, 0
	s_add_u32 s76, s42, 0x100
	v_mov_b32_e32 v2, 0
	v_mov_b32_e32 v3, 0
	s_addc_u32 s77, s43, 0
	s_mov_b32 s78, -2
	v_mov_b64_e32 v[4:5], v[2:3]
	v_mov_b64_e32 v[6:7], v[2:3]
	v_mov_b64_e32 v[8:9], v[2:3]
	v_mov_b64_e32 v[10:11], v[2:3]
	v_mov_b64_e32 v[12:13], v[2:3]
	v_mov_b64_e32 v[14:15], v[2:3]
	v_mov_b64_e32 v[16:17], v[2:3]
	v_mov_b64_e32 v[18:19], v[2:3]
	v_mov_b64_e32 v[20:21], v[2:3]
	v_mov_b64_e32 v[22:23], v[2:3]
	v_mov_b64_e32 v[24:25], v[2:3]
	v_mov_b64_e32 v[26:27], v[2:3]
	v_mov_b64_e32 v[28:29], v[2:3]
	v_mov_b64_e32 v[30:31], v[2:3]
	v_mov_b64_e32 v[32:33], v[2:3]
	v_mov_b64_e32 v[34:35], v[2:3]
	v_mov_b64_e32 v[36:37], v[2:3]
	v_mov_b64_e32 v[38:39], v[2:3]
	v_mov_b64_e32 v[40:41], v[2:3]
	v_mov_b64_e32 v[42:43], v[2:3]
	v_mov_b64_e32 v[44:45], v[2:3]
	v_mov_b64_e32 v[46:47], v[2:3]
	v_mov_b64_e32 v[48:49], v[2:3]
	v_mov_b64_e32 v[50:51], v[2:3]
	v_mov_b64_e32 v[52:53], v[2:3]
	v_mov_b64_e32 v[54:55], v[2:3]
	v_mov_b64_e32 v[56:57], v[2:3]
	v_mov_b64_e32 v[58:59], v[2:3]
	v_mov_b64_e32 v[60:61], v[2:3]
	v_mov_b64_e32 v[62:63], v[2:3]
	v_mov_b64_e32 v[64:65], v[2:3]
	v_mov_b64_e32 v[66:67], v[2:3]
	v_mov_b64_e32 v[68:69], v[2:3]
	v_mov_b64_e32 v[70:71], v[2:3]
	v_mov_b64_e32 v[72:73], v[2:3]
	v_mov_b64_e32 v[74:75], v[2:3]
	v_mov_b64_e32 v[76:77], v[2:3]
	v_mov_b64_e32 v[78:79], v[2:3]
	v_mov_b64_e32 v[80:81], v[2:3]
	v_mov_b64_e32 v[82:83], v[2:3]
	v_mov_b64_e32 v[84:85], v[2:3]
	v_mov_b64_e32 v[86:87], v[2:3]
	v_mov_b64_e32 v[88:89], v[2:3]
	v_mov_b64_e32 v[90:91], v[2:3]
	v_mov_b64_e32 v[92:93], v[2:3]
	v_mov_b64_e32 v[94:95], v[2:3]
	v_mov_b64_e32 v[96:97], v[2:3]
	v_mov_b64_e32 v[98:99], v[2:3]
	v_mov_b64_e32 v[100:101], v[2:3]
	v_mov_b64_e32 v[102:103], v[2:3]
	v_mov_b64_e32 v[104:105], v[2:3]
	v_mov_b64_e32 v[106:107], v[2:3]
	v_mov_b64_e32 v[108:109], v[2:3]
	v_mov_b64_e32 v[110:111], v[2:3]
	v_mov_b64_e32 v[112:113], v[2:3]
	v_mov_b64_e32 v[114:115], v[2:3]
	v_mov_b64_e32 v[116:117], v[2:3]
	v_mov_b64_e32 v[118:119], v[2:3]
	v_mov_b64_e32 v[120:121], v[2:3]
	v_mov_b64_e32 v[122:123], v[2:3]
	v_mov_b64_e32 v[124:125], v[2:3]
	v_mov_b64_e32 v[126:127], v[2:3]
	v_mov_b64_e32 v[128:129], v[2:3]
.LBB0_293:
	ds_read_b128 v[146:149], v153
	ds_read_b128 v[156:159], v153 offset:1024
	ds_read_b128 v[160:163], v153 offset:2048
	ds_read_b128 v[164:167], v153 offset:3072
	ds_read_b128 v[168:171], v154
	ds_read_b128 v[172:175], v154 offset:1024
	ds_read_b128 v[180:183], v154 offset:2048
	ds_read_b128 v[184:187], v154 offset:3072
	s_add_u32 s42, s40, 0xfff80080
	s_addc_u32 s43, s41, -1
	s_cmp_eq_u32 s78, 28
	s_cselect_b32 s55, s13, s43
	s_cselect_b32 s54, s74, s42
	s_cselect_b32 s43, s11, s77
	s_cselect_b32 s42, s75, s76
	v_lshl_add_u64 v[176:177], s[40:41], 0, v[138:139]
	s_add_i32 m0, s35, 0xc000
	ds_read_b128 v[188:191], v155
	ds_read_b128 v[192:195], v155 offset:1024
	ds_read_b128 v[196:199], v155 offset:2048
	ds_read_b128 v[200:203], v155 offset:3072
	ds_read_b128 v[204:207], v155 offset:4096
	ds_read_b128 v[208:211], v155 offset:5120
	ds_read_b128 v[212:215], v155 offset:6144
	ds_read_b128 v[216:219], v155 offset:7168
	global_load_lds_dwordx4 v[176:177], off
	v_lshl_add_u64 v[176:177], s[40:41], 0, v[140:141]
	s_add_i32 m0, s35, 0xe000
	s_nop 0
	global_load_lds_dwordx4 v[176:177], off
	s_waitcnt vmcnt(8)
	s_waitcnt lgkmcnt(0)
	s_setprio 1
	s_barrier
	v_mfma_f32_16x16x32_bf16 v[126:129], v[146:149], v[188:191], v[126:129]
	v_mfma_f32_16x16x32_bf16 v[118:121], v[160:163], v[188:191], v[118:121]
	v_mfma_f32_16x16x32_bf16 v[110:113], v[146:149], v[196:199], v[110:113]
	v_mfma_f32_16x16x32_bf16 v[102:105], v[160:163], v[196:199], v[102:105]
	v_mfma_f32_16x16x32_bf16 v[94:97], v[146:149], v[204:207], v[94:97]
	v_mfma_f32_16x16x32_bf16 v[86:89], v[160:163], v[204:207], v[86:89]
	v_mfma_f32_16x16x32_bf16 v[78:81], v[146:149], v[212:215], v[78:81]
	v_mfma_f32_16x16x32_bf16 v[70:73], v[160:163], v[212:215], v[70:73]
	v_mfma_f32_16x16x32_bf16 v[126:129], v[156:159], v[192:195], v[126:129]
	v_mfma_f32_16x16x32_bf16 v[118:121], v[164:167], v[192:195], v[118:121]
	v_mfma_f32_16x16x32_bf16 v[110:113], v[156:159], v[200:203], v[110:113]
	v_mfma_f32_16x16x32_bf16 v[102:105], v[164:167], v[200:203], v[102:105]
	v_mfma_f32_16x16x32_bf16 v[94:97], v[156:159], v[208:211], v[94:97]
	v_mfma_f32_16x16x32_bf16 v[86:89], v[164:167], v[208:211], v[86:89]
	v_mfma_f32_16x16x32_bf16 v[78:81], v[156:159], v[216:219], v[78:81]
	v_mfma_f32_16x16x32_bf16 v[70:73], v[164:167], v[216:219], v[70:73]
	s_setprio 0
	s_setprio 1
	v_mfma_f32_16x16x32_bf16 v[122:125], v[168:171], v[188:191], v[122:125]
	v_mfma_f32_16x16x32_bf16 v[114:117], v[180:183], v[188:191], v[114:117]
	v_mfma_f32_16x16x32_bf16 v[106:109], v[168:171], v[196:199], v[106:109]
	v_mfma_f32_16x16x32_bf16 v[98:101], v[180:183], v[196:199], v[98:101]
	v_mfma_f32_16x16x32_bf16 v[90:93], v[168:171], v[204:207], v[90:93]
	v_mfma_f32_16x16x32_bf16 v[82:85], v[180:183], v[204:207], v[82:85]
	v_mfma_f32_16x16x32_bf16 v[74:77], v[168:171], v[212:215], v[74:77]
	v_mfma_f32_16x16x32_bf16 v[66:69], v[180:183], v[212:215], v[66:69]
	v_mfma_f32_16x16x32_bf16 v[122:125], v[172:175], v[192:195], v[122:125]
	v_mfma_f32_16x16x32_bf16 v[114:117], v[184:187], v[192:195], v[114:117]
	v_mfma_f32_16x16x32_bf16 v[106:109], v[172:175], v[200:203], v[106:109]
	v_mfma_f32_16x16x32_bf16 v[98:101], v[184:187], v[200:203], v[98:101]
	v_mfma_f32_16x16x32_bf16 v[90:93], v[172:175], v[208:211], v[90:93]
	v_mfma_f32_16x16x32_bf16 v[82:85], v[184:187], v[208:211], v[82:85]
	v_mfma_f32_16x16x32_bf16 v[74:77], v[172:175], v[216:219], v[74:77]
	v_mfma_f32_16x16x32_bf16 v[66:69], v[184:187], v[216:219], v[66:69]
	s_barrier
	s_setprio 0
	s_add_i32 s79, s70, s29
	v_lshl_add_u64 v[176:177], s[42:43], 0, v[134:135]
	s_mov_b32 m0, s79
	ds_read_b128 v[188:191], v155 offset:16384
	ds_read_b128 v[192:195], v155 offset:17408
	ds_read_b128 v[196:199], v155 offset:18432
	ds_read_b128 v[200:203], v155 offset:19456
	ds_read_b128 v[204:207], v155 offset:20480
	ds_read_b128 v[208:211], v155 offset:21504
	ds_read_b128 v[212:215], v155 offset:22528
	ds_read_b128 v[216:219], v155 offset:23552
	global_load_lds_dwordx4 v[176:177], off
	s_add_i32 m0, s79, 0x2000
	s_add_u32 s80, s42, 0x80000
	v_lshl_add_u64 v[220:221], s[42:43], 0, v[130:131]
	s_addc_u32 s81, s43, 0
	s_add_i32 s79, s71, s29
	global_load_lds_dwordx4 v[220:221], off
	v_lshl_add_u64 v[222:223], s[80:81], 0, v[134:135]
	s_mov_b32 m0, s79
	v_lshl_add_u64 v[224:225], s[54:55], 0, v[132:133]
	global_load_lds_dwordx4 v[222:223], off
	v_lshl_add_u64 v[222:223], s[80:81], 0, v[130:131]
	s_add_i32 m0, s79, 0x2000
	s_nop 0
	global_load_lds_dwordx4 v[222:223], off
	v_lshl_add_u64 v[222:223], s[54:55], 0, v[136:137]
	s_mov_b32 m0, s35
	s_nop 0
	global_load_lds_dwordx4 v[222:223], off
	s_mov_b32 m0, s57
	s_nop 0
	global_load_lds_dwordx4 v[224:225], off
	s_waitcnt vmcnt(8)
	s_waitcnt lgkmcnt(0)
	s_setprio 1
	s_barrier
	v_mfma_f32_16x16x32_bf16 v[62:65], v[146:149], v[188:191], v[62:65]
	v_mfma_f32_16x16x32_bf16 v[54:57], v[160:163], v[188:191], v[54:57]
	v_mfma_f32_16x16x32_bf16 v[46:49], v[146:149], v[196:199], v[46:49]
	v_mfma_f32_16x16x32_bf16 v[38:41], v[160:163], v[196:199], v[38:41]
	v_mfma_f32_16x16x32_bf16 v[30:33], v[146:149], v[204:207], v[30:33]
	v_mfma_f32_16x16x32_bf16 v[22:25], v[160:163], v[204:207], v[22:25]
	v_mfma_f32_16x16x32_bf16 v[14:17], v[146:149], v[212:215], v[14:17]
	v_mfma_f32_16x16x32_bf16 v[6:9], v[160:163], v[212:215], v[6:9]
	v_mfma_f32_16x16x32_bf16 v[62:65], v[156:159], v[192:195], v[62:65]
	v_mfma_f32_16x16x32_bf16 v[54:57], v[164:167], v[192:195], v[54:57]
	v_mfma_f32_16x16x32_bf16 v[46:49], v[156:159], v[200:203], v[46:49]
	v_mfma_f32_16x16x32_bf16 v[38:41], v[164:167], v[200:203], v[38:41]
	v_mfma_f32_16x16x32_bf16 v[30:33], v[156:159], v[208:211], v[30:33]
	v_mfma_f32_16x16x32_bf16 v[22:25], v[164:167], v[208:211], v[22:25]
	v_mfma_f32_16x16x32_bf16 v[14:17], v[156:159], v[216:219], v[14:17]
	v_mfma_f32_16x16x32_bf16 v[6:9], v[164:167], v[216:219], v[6:9]
	s_setprio 0
	s_setprio 1
	v_mfma_f32_16x16x32_bf16 v[58:61], v[168:171], v[188:191], v[58:61]
	v_mfma_f32_16x16x32_bf16 v[50:53], v[180:183], v[188:191], v[50:53]
	v_mfma_f32_16x16x32_bf16 v[42:45], v[168:171], v[196:199], v[42:45]
	v_mfma_f32_16x16x32_bf16 v[34:37], v[180:183], v[196:199], v[34:37]
	v_mfma_f32_16x16x32_bf16 v[26:29], v[168:171], v[204:207], v[26:29]
	v_mfma_f32_16x16x32_bf16 v[18:21], v[180:183], v[204:207], v[18:21]
	v_mfma_f32_16x16x32_bf16 v[10:13], v[168:171], v[212:215], v[10:13]
	v_mfma_f32_16x16x32_bf16 v[2:5], v[180:183], v[212:215], v[2:5]
	v_mfma_f32_16x16x32_bf16 v[58:61], v[172:175], v[192:195], v[58:61]
	v_mfma_f32_16x16x32_bf16 v[50:53], v[184:187], v[192:195], v[50:53]
	v_mfma_f32_16x16x32_bf16 v[42:45], v[172:175], v[200:203], v[42:45]
	v_mfma_f32_16x16x32_bf16 v[34:37], v[184:187], v[200:203], v[34:37]
	v_mfma_f32_16x16x32_bf16 v[26:29], v[172:175], v[208:211], v[26:29]
	v_mfma_f32_16x16x32_bf16 v[18:21], v[184:187], v[208:211], v[18:21]
	v_mfma_f32_16x16x32_bf16 v[10:13], v[172:175], v[216:219], v[10:13]
	v_mfma_f32_16x16x32_bf16 v[2:5], v[184:187], v[216:219], v[2:5]
	s_barrier
	s_setprio 0
	s_add_i32 s79, 0, 0x18000
	v_add_u32_e32 v1, s79, v151
	s_add_i32 s80, 0, 0x1c000
	ds_read_b128 v[146:149], v1
	ds_read_b128 v[156:159], v1 offset:1024
	ds_read_b128 v[160:163], v1 offset:2048
	ds_read_b128 v[164:167], v1 offset:3072
	v_add_u32_e32 v1, s80, v151
	ds_read_b128 v[168:171], v1
	ds_read_b128 v[172:175], v1 offset:1024
	ds_read_b128 v[180:183], v1 offset:2048
	ds_read_b128 v[184:187], v1 offset:3072
	s_add_u32 s54, s54, 0x80000
	s_addc_u32 s55, s55, 0
	s_mov_b32 m0, s58
	v_lshl_add_u64 v[226:227], s[54:55], 0, v[136:137]
	ds_read_b128 v[188:191], v155 offset:32768
	ds_read_b128 v[192:195], v155 offset:33792
	ds_read_b128 v[196:199], v155 offset:34816
	ds_read_b128 v[200:203], v155 offset:35840
	ds_read_b128 v[204:207], v155 offset:36864
	ds_read_b128 v[208:211], v155 offset:37888
	ds_read_b128 v[212:215], v155 offset:38912
	ds_read_b128 v[216:219], v155 offset:39936
	global_load_lds_dwordx4 v[226:227], off
	v_lshl_add_u64 v[226:227], s[54:55], 0, v[132:133]
	s_mov_b32 m0, s59
	s_nop 0
	global_load_lds_dwordx4 v[226:227], off
	s_waitcnt vmcnt(8)
	s_waitcnt lgkmcnt(0)
	s_setprio 1
	s_barrier
	v_mfma_f32_16x16x32_bf16 v[126:129], v[146:149], v[188:191], v[126:129]
	v_mfma_f32_16x16x32_bf16 v[118:121], v[160:163], v[188:191], v[118:121]
	v_mfma_f32_16x16x32_bf16 v[110:113], v[146:149], v[196:199], v[110:113]
	v_mfma_f32_16x16x32_bf16 v[102:105], v[160:163], v[196:199], v[102:105]
	v_mfma_f32_16x16x32_bf16 v[94:97], v[146:149], v[204:207], v[94:97]
	v_mfma_f32_16x16x32_bf16 v[86:89], v[160:163], v[204:207], v[86:89]
	v_mfma_f32_16x16x32_bf16 v[78:81], v[146:149], v[212:215], v[78:81]
	v_mfma_f32_16x16x32_bf16 v[70:73], v[160:163], v[212:215], v[70:73]
	v_mfma_f32_16x16x32_bf16 v[126:129], v[156:159], v[192:195], v[126:129]
	v_mfma_f32_16x16x32_bf16 v[118:121], v[164:167], v[192:195], v[118:121]
	v_mfma_f32_16x16x32_bf16 v[110:113], v[156:159], v[200:203], v[110:113]
	v_mfma_f32_16x16x32_bf16 v[102:105], v[164:167], v[200:203], v[102:105]
	v_mfma_f32_16x16x32_bf16 v[94:97], v[156:159], v[208:211], v[94:97]
	v_mfma_f32_16x16x32_bf16 v[86:89], v[164:167], v[208:211], v[86:89]
	v_mfma_f32_16x16x32_bf16 v[78:81], v[156:159], v[216:219], v[78:81]
	v_mfma_f32_16x16x32_bf16 v[70:73], v[164:167], v[216:219], v[70:73]
	s_setprio 0
	s_setprio 1
	v_mfma_f32_16x16x32_bf16 v[122:125], v[168:171], v[188:191], v[122:125]
	v_mfma_f32_16x16x32_bf16 v[114:117], v[180:183], v[188:191], v[114:117]
	v_mfma_f32_16x16x32_bf16 v[106:109], v[168:171], v[196:199], v[106:109]
	v_mfma_f32_16x16x32_bf16 v[98:101], v[180:183], v[196:199], v[98:101]
	v_mfma_f32_16x16x32_bf16 v[90:93], v[168:171], v[204:207], v[90:93]
	v_mfma_f32_16x16x32_bf16 v[82:85], v[180:183], v[204:207], v[82:85]
	v_mfma_f32_16x16x32_bf16 v[74:77], v[168:171], v[212:215], v[74:77]
	v_mfma_f32_16x16x32_bf16 v[66:69], v[180:183], v[212:215], v[66:69]
	v_mfma_f32_16x16x32_bf16 v[122:125], v[172:175], v[192:195], v[122:125]
	v_mfma_f32_16x16x32_bf16 v[114:117], v[184:187], v[192:195], v[114:117]
	v_mfma_f32_16x16x32_bf16 v[106:109], v[172:175], v[200:203], v[106:109]
	v_mfma_f32_16x16x32_bf16 v[98:101], v[184:187], v[200:203], v[98:101]
	v_mfma_f32_16x16x32_bf16 v[90:93], v[172:175], v[208:211], v[90:93]
	v_mfma_f32_16x16x32_bf16 v[82:85], v[184:187], v[208:211], v[82:85]
	v_mfma_f32_16x16x32_bf16 v[74:77], v[172:175], v[216:219], v[74:77]
	v_mfma_f32_16x16x32_bf16 v[66:69], v[184:187], v[216:219], v[66:69]
	s_barrier
	s_setprio 0
	s_add_i32 s54, s79, s29
	v_lshl_add_u64 v[176:177], v[176:177], 0, s[6:7]
	s_mov_b32 m0, s54
	ds_read_b128 v[188:191], v155 offset:49152
	ds_read_b128 v[192:195], v155 offset:50176
	ds_read_b128 v[196:199], v155 offset:51200
	ds_read_b128 v[200:203], v155 offset:52224
	ds_read_b128 v[204:207], v155 offset:53248
	ds_read_b128 v[208:211], v155 offset:54272
	ds_read_b128 v[212:215], v155 offset:55296
	ds_read_b128 v[216:219], v155 offset:56320
	global_load_lds_dwordx4 v[176:177], off
	s_add_i32 m0, s54, 0x2000
	s_add_u32 s42, s42, 0x80080
	v_lshl_add_u64 v[176:177], v[220:221], 0, s[6:7]
	s_addc_u32 s43, s43, 0
	s_add_i32 s54, s80, s29
	global_load_lds_dwordx4 v[176:177], off
	v_lshl_add_u64 v[176:177], s[42:43], 0, v[134:135]
	s_mov_b32 m0, s54
	s_nop 0
	global_load_lds_dwordx4 v[176:177], off
	v_lshl_add_u64 v[176:177], s[42:43], 0, v[130:131]
	s_add_i32 m0, s54, 0x2000
	s_nop 0
	global_load_lds_dwordx4 v[176:177], off
	v_lshl_add_u64 v[176:177], v[222:223], 0, s[6:7]
	s_mov_b32 m0, s64
	s_nop 0
	global_load_lds_dwordx4 v[176:177], off
	v_lshl_add_u64 v[176:177], v[224:225], 0, s[6:7]
	s_mov_b32 m0, s65
	s_nop 0
	global_load_lds_dwordx4 v[176:177], off
	s_waitcnt vmcnt(8)
	s_waitcnt lgkmcnt(0)
	s_setprio 1
	s_barrier
	v_mfma_f32_16x16x32_bf16 v[62:65], v[146:149], v[188:191], v[62:65]
	v_mfma_f32_16x16x32_bf16 v[54:57], v[160:163], v[188:191], v[54:57]
	v_mfma_f32_16x16x32_bf16 v[46:49], v[146:149], v[196:199], v[46:49]
	v_mfma_f32_16x16x32_bf16 v[38:41], v[160:163], v[196:199], v[38:41]
	v_mfma_f32_16x16x32_bf16 v[30:33], v[146:149], v[204:207], v[30:33]
	v_mfma_f32_16x16x32_bf16 v[22:25], v[160:163], v[204:207], v[22:25]
	v_mfma_f32_16x16x32_bf16 v[14:17], v[146:149], v[212:215], v[14:17]
	v_mfma_f32_16x16x32_bf16 v[6:9], v[160:163], v[212:215], v[6:9]
	v_mfma_f32_16x16x32_bf16 v[62:65], v[156:159], v[192:195], v[62:65]
	v_mfma_f32_16x16x32_bf16 v[54:57], v[164:167], v[192:195], v[54:57]
	v_mfma_f32_16x16x32_bf16 v[46:49], v[156:159], v[200:203], v[46:49]
	v_mfma_f32_16x16x32_bf16 v[38:41], v[164:167], v[200:203], v[38:41]
	v_mfma_f32_16x16x32_bf16 v[30:33], v[156:159], v[208:211], v[30:33]
	v_mfma_f32_16x16x32_bf16 v[22:25], v[164:167], v[208:211], v[22:25]
	v_mfma_f32_16x16x32_bf16 v[14:17], v[156:159], v[216:219], v[14:17]
	v_mfma_f32_16x16x32_bf16 v[6:9], v[164:167], v[216:219], v[6:9]
	s_setprio 0
	s_setprio 1
	v_mfma_f32_16x16x32_bf16 v[58:61], v[168:171], v[188:191], v[58:61]
	v_mfma_f32_16x16x32_bf16 v[50:53], v[180:183], v[188:191], v[50:53]
	v_mfma_f32_16x16x32_bf16 v[42:45], v[168:171], v[196:199], v[42:45]
	v_mfma_f32_16x16x32_bf16 v[34:37], v[180:183], v[196:199], v[34:37]
	v_mfma_f32_16x16x32_bf16 v[26:29], v[168:171], v[204:207], v[26:29]
	v_mfma_f32_16x16x32_bf16 v[18:21], v[180:183], v[204:207], v[18:21]
	v_mfma_f32_16x16x32_bf16 v[10:13], v[168:171], v[212:215], v[10:13]
	v_mfma_f32_16x16x32_bf16 v[2:5], v[180:183], v[212:215], v[2:5]
	v_mfma_f32_16x16x32_bf16 v[58:61], v[172:175], v[192:195], v[58:61]
	v_mfma_f32_16x16x32_bf16 v[50:53], v[184:187], v[192:195], v[50:53]
	v_mfma_f32_16x16x32_bf16 v[42:45], v[172:175], v[200:203], v[42:45]
	v_mfma_f32_16x16x32_bf16 v[34:37], v[184:187], v[200:203], v[34:37]
	v_mfma_f32_16x16x32_bf16 v[26:29], v[172:175], v[208:211], v[26:29]
	v_mfma_f32_16x16x32_bf16 v[18:21], v[184:187], v[208:211], v[18:21]
	v_mfma_f32_16x16x32_bf16 v[10:13], v[172:175], v[216:219], v[10:13]
	v_mfma_f32_16x16x32_bf16 v[2:5], v[184:187], v[216:219], v[2:5]
	s_barrier
	s_setprio 0
	s_add_i32 s78, s78, 2
	s_add_u32 s40, s40, 0x100
	s_addc_u32 s41, s41, 0
	s_add_u32 s76, s76, 0x100
	s_addc_u32 s77, s77, 0
	s_cmp_gt_u32 s78, 29
	s_cbranch_scc0 .LBB0_293
	s_and_b64 vcc, exec, s[8:9]
	s_cbranch_vccz .LBB0_296
	s_barrier

.LBB0_378:
	s_add_u32 s12, s58, 0x160080
	s_addc_u32 s13, s59, 0
	s_add_u32 s81, s56, 0x100
	v_mov_b32_e32 v2, 0
	v_mov_b32_e32 v3, 0
	s_addc_u32 s82, s57, 0
	s_mov_b32 s83, -2
	v_mov_b64_e32 v[4:5], v[2:3]
	v_mov_b64_e32 v[6:7], v[2:3]
	v_mov_b64_e32 v[8:9], v[2:3]
	v_mov_b64_e32 v[10:11], v[2:3]
	v_mov_b64_e32 v[12:13], v[2:3]
	v_mov_b64_e32 v[14:15], v[2:3]
	v_mov_b64_e32 v[16:17], v[2:3]
	v_mov_b64_e32 v[18:19], v[2:3]
	v_mov_b64_e32 v[20:21], v[2:3]
	v_mov_b64_e32 v[22:23], v[2:3]
	v_mov_b64_e32 v[24:25], v[2:3]
	v_mov_b64_e32 v[26:27], v[2:3]
	v_mov_b64_e32 v[28:29], v[2:3]
	v_mov_b64_e32 v[30:31], v[2:3]
	v_mov_b64_e32 v[32:33], v[2:3]
	v_mov_b64_e32 v[34:35], v[2:3]
	v_mov_b64_e32 v[36:37], v[2:3]
	v_mov_b64_e32 v[38:39], v[2:3]
	v_mov_b64_e32 v[40:41], v[2:3]
	v_mov_b64_e32 v[42:43], v[2:3]
	v_mov_b64_e32 v[44:45], v[2:3]
	v_mov_b64_e32 v[46:47], v[2:3]
	v_mov_b64_e32 v[48:49], v[2:3]
	v_mov_b64_e32 v[50:51], v[2:3]
	v_mov_b64_e32 v[52:53], v[2:3]
	v_mov_b64_e32 v[54:55], v[2:3]
	v_mov_b64_e32 v[56:57], v[2:3]
	v_mov_b64_e32 v[58:59], v[2:3]
	v_mov_b64_e32 v[60:61], v[2:3]
	v_mov_b64_e32 v[62:63], v[2:3]
	v_mov_b64_e32 v[64:65], v[2:3]
	v_mov_b64_e32 v[66:67], v[2:3]
	v_mov_b64_e32 v[68:69], v[2:3]
	v_mov_b64_e32 v[70:71], v[2:3]
	v_mov_b64_e32 v[72:73], v[2:3]
	v_mov_b64_e32 v[74:75], v[2:3]
	v_mov_b64_e32 v[76:77], v[2:3]
	v_mov_b64_e32 v[78:79], v[2:3]
	v_mov_b64_e32 v[80:81], v[2:3]
	v_mov_b64_e32 v[82:83], v[2:3]
	v_mov_b64_e32 v[84:85], v[2:3]
	v_mov_b64_e32 v[86:87], v[2:3]
	v_mov_b64_e32 v[88:89], v[2:3]
	v_mov_b64_e32 v[90:91], v[2:3]
	v_mov_b64_e32 v[92:93], v[2:3]
	v_mov_b64_e32 v[94:95], v[2:3]
	v_mov_b64_e32 v[96:97], v[2:3]
	v_mov_b64_e32 v[98:99], v[2:3]
	v_mov_b64_e32 v[100:101], v[2:3]
	v_mov_b64_e32 v[102:103], v[2:3]
	v_mov_b64_e32 v[104:105], v[2:3]
	v_mov_b64_e32 v[106:107], v[2:3]
	v_mov_b64_e32 v[108:109], v[2:3]
	v_mov_b64_e32 v[110:111], v[2:3]
	v_mov_b64_e32 v[112:113], v[2:3]
	v_mov_b64_e32 v[114:115], v[2:3]
	v_mov_b64_e32 v[116:117], v[2:3]
	v_mov_b64_e32 v[118:119], v[2:3]
	v_mov_b64_e32 v[120:121], v[2:3]
	v_mov_b64_e32 v[122:123], v[2:3]
	v_mov_b64_e32 v[124:125], v[2:3]
	v_mov_b64_e32 v[126:127], v[2:3]
	v_mov_b64_e32 v[128:129], v[2:3]
.LBB0_379:
	ds_read_b128 v[130:133], v208
	ds_read_b128 v[134:137], v208 offset:1024
	ds_read_b128 v[138:141], v208 offset:2048
	ds_read_b128 v[142:145], v208 offset:3072
	ds_read_b128 v[146:149], v209
	ds_read_b128 v[150:153], v209 offset:1024
	ds_read_b128 v[154:157], v209 offset:2048
	ds_read_b128 v[158:161], v209 offset:3072
	s_add_u32 s56, s12, 0xffea0080
	s_addc_u32 s57, s13, -1
	s_cmpk_eq_i32 s83, 0x54
	s_cselect_b32 s59, s43, s57
	s_cselect_b32 s58, s42, s56
	s_cselect_b32 s57, s55, s82
	s_cselect_b32 s56, s54, s81
	v_lshl_add_u64 v[204:205], s[12:13], 0, v[188:189]
	s_add_i32 m0, s31, 0xc000
	ds_read_b128 v[162:165], v210
	ds_read_b128 v[166:169], v210 offset:1024
	ds_read_b128 v[170:173], v210 offset:2048
	ds_read_b128 v[174:177], v210 offset:3072
	ds_read_b128 v[196:199], v210 offset:4096
	ds_read_b128 v[200:203], v210 offset:5120
	ds_read_b128 v[212:215], v210 offset:6144
	ds_read_b128 v[216:219], v210 offset:7168
	global_load_lds_dwordx4 v[204:205], off
	v_lshl_add_u64 v[204:205], s[12:13], 0, v[190:191]
	s_add_i32 m0, s31, 0xe000
	s_nop 0
	global_load_lds_dwordx4 v[204:205], off
	s_waitcnt vmcnt(8)
	s_waitcnt lgkmcnt(0)
	s_setprio 1
	s_barrier
	v_mfma_f32_16x16x32_bf16 v[126:129], v[130:133], v[162:165], v[126:129]
	v_mfma_f32_16x16x32_bf16 v[122:125], v[138:141], v[162:165], v[122:125]
	v_mfma_f32_16x16x32_bf16 v[110:113], v[130:133], v[170:173], v[110:113]
	v_mfma_f32_16x16x32_bf16 v[106:109], v[138:141], v[170:173], v[106:109]
	v_mfma_f32_16x16x32_bf16 v[94:97], v[130:133], v[196:199], v[94:97]
	v_mfma_f32_16x16x32_bf16 v[90:93], v[138:141], v[196:199], v[90:93]
	v_mfma_f32_16x16x32_bf16 v[78:81], v[130:133], v[212:215], v[78:81]
	v_mfma_f32_16x16x32_bf16 v[74:77], v[138:141], v[212:215], v[74:77]
	v_mfma_f32_16x16x32_bf16 v[126:129], v[134:137], v[166:169], v[126:129]
	v_mfma_f32_16x16x32_bf16 v[122:125], v[142:145], v[166:169], v[122:125]
	v_mfma_f32_16x16x32_bf16 v[110:113], v[134:137], v[174:177], v[110:113]
	v_mfma_f32_16x16x32_bf16 v[106:109], v[142:145], v[174:177], v[106:109]
	v_mfma_f32_16x16x32_bf16 v[94:97], v[134:137], v[200:203], v[94:97]
	v_mfma_f32_16x16x32_bf16 v[90:93], v[142:145], v[200:203], v[90:93]
	v_mfma_f32_16x16x32_bf16 v[78:81], v[134:137], v[216:219], v[78:81]
	v_mfma_f32_16x16x32_bf16 v[74:77], v[142:145], v[216:219], v[74:77]
	s_setprio 0
	s_setprio 1
	v_mfma_f32_16x16x32_bf16 v[118:121], v[146:149], v[162:165], v[118:121]
	v_mfma_f32_16x16x32_bf16 v[114:117], v[154:157], v[162:165], v[114:117]
	v_mfma_f32_16x16x32_bf16 v[102:105], v[146:149], v[170:173], v[102:105]
	v_mfma_f32_16x16x32_bf16 v[98:101], v[154:157], v[170:173], v[98:101]
	v_mfma_f32_16x16x32_bf16 v[86:89], v[146:149], v[196:199], v[86:89]
	v_mfma_f32_16x16x32_bf16 v[82:85], v[154:157], v[196:199], v[82:85]
	v_mfma_f32_16x16x32_bf16 v[70:73], v[146:149], v[212:215], v[70:73]
	v_mfma_f32_16x16x32_bf16 v[66:69], v[154:157], v[212:215], v[66:69]
	v_mfma_f32_16x16x32_bf16 v[118:121], v[150:153], v[166:169], v[118:121]
	v_mfma_f32_16x16x32_bf16 v[114:117], v[158:161], v[166:169], v[114:117]
	v_mfma_f32_16x16x32_bf16 v[102:105], v[150:153], v[174:177], v[102:105]
	v_mfma_f32_16x16x32_bf16 v[98:101], v[158:161], v[174:177], v[98:101]
	v_mfma_f32_16x16x32_bf16 v[86:89], v[150:153], v[200:203], v[86:89]
	v_mfma_f32_16x16x32_bf16 v[82:85], v[158:161], v[200:203], v[82:85]
	v_mfma_f32_16x16x32_bf16 v[70:73], v[150:153], v[216:219], v[70:73]
	v_mfma_f32_16x16x32_bf16 v[66:69], v[158:161], v[216:219], v[66:69]
	s_barrier
	s_setprio 0
	s_add_i32 s85, s75, s29
	v_lshl_add_u64 v[204:205], s[56:57], 0, v[182:183]
	s_mov_b32 m0, s85
	ds_read_b128 v[162:165], v210 offset:16384
	ds_read_b128 v[166:169], v210 offset:17408
	ds_read_b128 v[170:173], v210 offset:18432
	ds_read_b128 v[174:177], v210 offset:19456
	ds_read_b128 v[196:199], v210 offset:20480
	ds_read_b128 v[200:203], v210 offset:21504
	ds_read_b128 v[212:215], v210 offset:22528
	ds_read_b128 v[216:219], v210 offset:23552
	global_load_lds_dwordx4 v[204:205], off
	s_add_i32 m0, s85, 0x2000
	s_add_u32 s88, s56, 0x160000
	v_lshl_add_u64 v[220:221], s[56:57], 0, v[186:187]
	s_addc_u32 s89, s57, 0
	s_add_i32 s85, s76, s29
	global_load_lds_dwordx4 v[220:221], off
	v_lshl_add_u64 v[222:223], s[88:89], 0, v[182:183]
	s_mov_b32 m0, s85
	v_lshl_add_u64 v[224:225], s[58:59], 0, v[184:185]
	global_load_lds_dwordx4 v[222:223], off
	v_lshl_add_u64 v[222:223], s[88:89], 0, v[186:187]
	s_add_i32 m0, s85, 0x2000
	s_nop 0
	global_load_lds_dwordx4 v[222:223], off
	v_lshl_add_u64 v[222:223], s[58:59], 0, v[180:181]
	s_mov_b32 m0, s31
	s_nop 0
	global_load_lds_dwordx4 v[222:223], off
	s_mov_b32 m0, s64
	s_nop 0
	global_load_lds_dwordx4 v[224:225], off
	s_waitcnt vmcnt(8)
	s_waitcnt lgkmcnt(0)
	s_setprio 1
	s_barrier
	v_mfma_f32_16x16x32_bf16 v[62:65], v[130:133], v[162:165], v[62:65]
	v_mfma_f32_16x16x32_bf16 v[58:61], v[138:141], v[162:165], v[58:61]
	v_mfma_f32_16x16x32_bf16 v[46:49], v[130:133], v[170:173], v[46:49]
	v_mfma_f32_16x16x32_bf16 v[42:45], v[138:141], v[170:173], v[42:45]
	v_mfma_f32_16x16x32_bf16 v[30:33], v[130:133], v[196:199], v[30:33]
	v_mfma_f32_16x16x32_bf16 v[26:29], v[138:141], v[196:199], v[26:29]
	v_mfma_f32_16x16x32_bf16 v[14:17], v[130:133], v[212:215], v[14:17]
	v_mfma_f32_16x16x32_bf16 v[10:13], v[138:141], v[212:215], v[10:13]
	v_mfma_f32_16x16x32_bf16 v[62:65], v[134:137], v[166:169], v[62:65]
	v_mfma_f32_16x16x32_bf16 v[58:61], v[142:145], v[166:169], v[58:61]
	v_mfma_f32_16x16x32_bf16 v[46:49], v[134:137], v[174:177], v[46:49]
	v_mfma_f32_16x16x32_bf16 v[42:45], v[142:145], v[174:177], v[42:45]
	v_mfma_f32_16x16x32_bf16 v[30:33], v[134:137], v[200:203], v[30:33]
	v_mfma_f32_16x16x32_bf16 v[26:29], v[142:145], v[200:203], v[26:29]
	v_mfma_f32_16x16x32_bf16 v[14:17], v[134:137], v[216:219], v[14:17]
	v_mfma_f32_16x16x32_bf16 v[10:13], v[142:145], v[216:219], v[10:13]
	s_setprio 0
	s_setprio 1
	v_mfma_f32_16x16x32_bf16 v[54:57], v[146:149], v[162:165], v[54:57]
	v_mfma_f32_16x16x32_bf16 v[50:53], v[154:157], v[162:165], v[50:53]
	v_mfma_f32_16x16x32_bf16 v[38:41], v[146:149], v[170:173], v[38:41]
	v_mfma_f32_16x16x32_bf16 v[34:37], v[154:157], v[170:173], v[34:37]
	v_mfma_f32_16x16x32_bf16 v[22:25], v[146:149], v[196:199], v[22:25]
	v_mfma_f32_16x16x32_bf16 v[18:21], v[154:157], v[196:199], v[18:21]
	v_mfma_f32_16x16x32_bf16 v[6:9], v[146:149], v[212:215], v[6:9]
	v_mfma_f32_16x16x32_bf16 v[2:5], v[154:157], v[212:215], v[2:5]
	v_mfma_f32_16x16x32_bf16 v[54:57], v[150:153], v[166:169], v[54:57]
	v_mfma_f32_16x16x32_bf16 v[50:53], v[158:161], v[166:169], v[50:53]
	v_mfma_f32_16x16x32_bf16 v[38:41], v[150:153], v[174:177], v[38:41]
	v_mfma_f32_16x16x32_bf16 v[34:37], v[158:161], v[174:177], v[34:37]
	v_mfma_f32_16x16x32_bf16 v[22:25], v[150:153], v[200:203], v[22:25]
	v_mfma_f32_16x16x32_bf16 v[18:21], v[158:161], v[200:203], v[18:21]
	v_mfma_f32_16x16x32_bf16 v[6:9], v[150:153], v[216:219], v[6:9]
	v_mfma_f32_16x16x32_bf16 v[2:5], v[158:161], v[216:219], v[2:5]
	s_barrier
	s_setprio 0
	s_add_i32 s85, 0, 0x18000
	v_add_u32_e32 v1, s85, v206
	s_add_i32 s87, 0, 0x1c000
	ds_read_b128 v[130:133], v1
	ds_read_b128 v[134:137], v1 offset:1024
	ds_read_b128 v[138:141], v1 offset:2048
	ds_read_b128 v[142:145], v1 offset:3072
	v_add_u32_e32 v1, s87, v206
	ds_read_b128 v[146:149], v1
	ds_read_b128 v[150:153], v1 offset:1024
	ds_read_b128 v[154:157], v1 offset:2048
	ds_read_b128 v[158:161], v1 offset:3072
	s_add_u32 s58, s58, 0x160000
	s_addc_u32 s59, s59, 0
	s_mov_b32 m0, s65
	v_lshl_add_u64 v[226:227], s[58:59], 0, v[180:181]
	ds_read_b128 v[162:165], v210 offset:32768
	ds_read_b128 v[166:169], v210 offset:33792
	ds_read_b128 v[170:173], v210 offset:34816
	ds_read_b128 v[174:177], v210 offset:35840
	ds_read_b128 v[196:199], v210 offset:36864
	ds_read_b128 v[200:203], v210 offset:37888
	ds_read_b128 v[212:215], v210 offset:38912
	ds_read_b128 v[216:219], v210 offset:39936
	global_load_lds_dwordx4 v[226:227], off
	v_lshl_add_u64 v[226:227], s[58:59], 0, v[184:185]
	s_mov_b32 m0, s66
	s_nop 0
	global_load_lds_dwordx4 v[226:227], off
	s_waitcnt vmcnt(8)
	s_waitcnt lgkmcnt(0)
	s_setprio 1
	s_barrier
	v_mfma_f32_16x16x32_bf16 v[126:129], v[130:133], v[162:165], v[126:129]
	v_mfma_f32_16x16x32_bf16 v[122:125], v[138:141], v[162:165], v[122:125]
	v_mfma_f32_16x16x32_bf16 v[110:113], v[130:133], v[170:173], v[110:113]
	v_mfma_f32_16x16x32_bf16 v[106:109], v[138:141], v[170:173], v[106:109]
	v_mfma_f32_16x16x32_bf16 v[94:97], v[130:133], v[196:199], v[94:97]
	v_mfma_f32_16x16x32_bf16 v[90:93], v[138:141], v[196:199], v[90:93]
	v_mfma_f32_16x16x32_bf16 v[78:81], v[130:133], v[212:215], v[78:81]
	v_mfma_f32_16x16x32_bf16 v[74:77], v[138:141], v[212:215], v[74:77]
	v_mfma_f32_16x16x32_bf16 v[126:129], v[134:137], v[166:169], v[126:129]
	v_mfma_f32_16x16x32_bf16 v[122:125], v[142:145], v[166:169], v[122:125]
	v_mfma_f32_16x16x32_bf16 v[110:113], v[134:137], v[174:177], v[110:113]
	v_mfma_f32_16x16x32_bf16 v[106:109], v[142:145], v[174:177], v[106:109]
	v_mfma_f32_16x16x32_bf16 v[94:97], v[134:137], v[200:203], v[94:97]
	v_mfma_f32_16x16x32_bf16 v[90:93], v[142:145], v[200:203], v[90:93]
	v_mfma_f32_16x16x32_bf16 v[78:81], v[134:137], v[216:219], v[78:81]
	v_mfma_f32_16x16x32_bf16 v[74:77], v[142:145], v[216:219], v[74:77]
	s_setprio 0
	s_setprio 1
	v_mfma_f32_16x16x32_bf16 v[118:121], v[146:149], v[162:165], v[118:121]
	v_mfma_f32_16x16x32_bf16 v[114:117], v[154:157], v[162:165], v[114:117]
	v_mfma_f32_16x16x32_bf16 v[102:105], v[146:149], v[170:173], v[102:105]
	v_mfma_f32_16x16x32_bf16 v[98:101], v[154:157], v[170:173], v[98:101]
	v_mfma_f32_16x16x32_bf16 v[86:89], v[146:149], v[196:199], v[86:89]
	v_mfma_f32_16x16x32_bf16 v[82:85], v[154:157], v[196:199], v[82:85]
	v_mfma_f32_16x16x32_bf16 v[70:73], v[146:149], v[212:215], v[70:73]
	v_mfma_f32_16x16x32_bf16 v[66:69], v[154:157], v[212:215], v[66:69]
	v_mfma_f32_16x16x32_bf16 v[118:121], v[150:153], v[166:169], v[118:121]
	v_mfma_f32_16x16x32_bf16 v[114:117], v[158:161], v[166:169], v[114:117]
	v_mfma_f32_16x16x32_bf16 v[102:105], v[150:153], v[174:177], v[102:105]
	v_mfma_f32_16x16x32_bf16 v[98:101], v[158:161], v[174:177], v[98:101]
	v_mfma_f32_16x16x32_bf16 v[86:89], v[150:153], v[200:203], v[86:89]
	v_mfma_f32_16x16x32_bf16 v[82:85], v[158:161], v[200:203], v[82:85]
	v_mfma_f32_16x16x32_bf16 v[70:73], v[150:153], v[216:219], v[70:73]
	v_mfma_f32_16x16x32_bf16 v[66:69], v[158:161], v[216:219], v[66:69]
	s_barrier
	s_setprio 0
	s_add_i32 s58, s85, s29
	v_lshl_add_u64 v[204:205], v[204:205], 0, s[16:17]
	s_mov_b32 m0, s58
	ds_read_b128 v[162:165], v210 offset:49152
	ds_read_b128 v[166:169], v210 offset:50176
	ds_read_b128 v[170:173], v210 offset:51200
	ds_read_b128 v[174:177], v210 offset:52224
	ds_read_b128 v[196:199], v210 offset:53248
	ds_read_b128 v[200:203], v210 offset:54272
	ds_read_b128 v[212:215], v210 offset:55296
	ds_read_b128 v[216:219], v210 offset:56320
	global_load_lds_dwordx4 v[204:205], off
	s_add_i32 m0, s58, 0x2000
	s_add_u32 s56, s56, 0x160080
	v_lshl_add_u64 v[204:205], v[220:221], 0, s[16:17]
	s_addc_u32 s57, s57, 0
	s_add_i32 s58, s87, s29
	global_load_lds_dwordx4 v[204:205], off
	v_lshl_add_u64 v[204:205], s[56:57], 0, v[182:183]
	s_mov_b32 m0, s58
	s_nop 0
	global_load_lds_dwordx4 v[204:205], off
	v_lshl_add_u64 v[204:205], s[56:57], 0, v[186:187]
	s_add_i32 m0, s58, 0x2000
	s_nop 0
	global_load_lds_dwordx4 v[204:205], off
	v_lshl_add_u64 v[204:205], v[222:223], 0, s[16:17]
	s_mov_b32 m0, s71
	s_nop 0
	global_load_lds_dwordx4 v[204:205], off
	v_lshl_add_u64 v[204:205], v[224:225], 0, s[16:17]
	s_mov_b32 m0, s72
	s_nop 0
	global_load_lds_dwordx4 v[204:205], off
	s_waitcnt vmcnt(8)
	s_waitcnt lgkmcnt(0)
	s_setprio 1
	s_barrier
	v_mfma_f32_16x16x32_bf16 v[62:65], v[130:133], v[162:165], v[62:65]
	v_mfma_f32_16x16x32_bf16 v[58:61], v[138:141], v[162:165], v[58:61]
	v_mfma_f32_16x16x32_bf16 v[46:49], v[130:133], v[170:173], v[46:49]
	v_mfma_f32_16x16x32_bf16 v[42:45], v[138:141], v[170:173], v[42:45]
	v_mfma_f32_16x16x32_bf16 v[30:33], v[130:133], v[196:199], v[30:33]
	v_mfma_f32_16x16x32_bf16 v[26:29], v[138:141], v[196:199], v[26:29]
	v_mfma_f32_16x16x32_bf16 v[14:17], v[130:133], v[212:215], v[14:17]
	v_mfma_f32_16x16x32_bf16 v[10:13], v[138:141], v[212:215], v[10:13]
	v_mfma_f32_16x16x32_bf16 v[62:65], v[134:137], v[166:169], v[62:65]
	v_mfma_f32_16x16x32_bf16 v[58:61], v[142:145], v[166:169], v[58:61]
	v_mfma_f32_16x16x32_bf16 v[46:49], v[134:137], v[174:177], v[46:49]
	v_mfma_f32_16x16x32_bf16 v[42:45], v[142:145], v[174:177], v[42:45]
	v_mfma_f32_16x16x32_bf16 v[30:33], v[134:137], v[200:203], v[30:33]
	v_mfma_f32_16x16x32_bf16 v[26:29], v[142:145], v[200:203], v[26:29]
	v_mfma_f32_16x16x32_bf16 v[14:17], v[134:137], v[216:219], v[14:17]
	v_mfma_f32_16x16x32_bf16 v[10:13], v[142:145], v[216:219], v[10:13]
	s_setprio 0
	s_setprio 1
	v_mfma_f32_16x16x32_bf16 v[54:57], v[146:149], v[162:165], v[54:57]
	v_mfma_f32_16x16x32_bf16 v[50:53], v[154:157], v[162:165], v[50:53]
	v_mfma_f32_16x16x32_bf16 v[38:41], v[146:149], v[170:173], v[38:41]
	v_mfma_f32_16x16x32_bf16 v[34:37], v[154:157], v[170:173], v[34:37]
	v_mfma_f32_16x16x32_bf16 v[22:25], v[146:149], v[196:199], v[22:25]
	v_mfma_f32_16x16x32_bf16 v[18:21], v[154:157], v[196:199], v[18:21]
	v_mfma_f32_16x16x32_bf16 v[6:9], v[146:149], v[212:215], v[6:9]
	v_mfma_f32_16x16x32_bf16 v[2:5], v[154:157], v[212:215], v[2:5]
	v_mfma_f32_16x16x32_bf16 v[54:57], v[150:153], v[166:169], v[54:57]
	v_mfma_f32_16x16x32_bf16 v[50:53], v[158:161], v[166:169], v[50:53]
	v_mfma_f32_16x16x32_bf16 v[38:41], v[150:153], v[174:177], v[38:41]
	v_mfma_f32_16x16x32_bf16 v[34:37], v[158:161], v[174:177], v[34:37]
	v_mfma_f32_16x16x32_bf16 v[22:25], v[150:153], v[200:203], v[22:25]
	v_mfma_f32_16x16x32_bf16 v[18:21], v[158:161], v[200:203], v[18:21]
	v_mfma_f32_16x16x32_bf16 v[6:9], v[150:153], v[216:219], v[6:9]
	v_mfma_f32_16x16x32_bf16 v[2:5], v[158:161], v[216:219], v[2:5]
	s_barrier
	s_setprio 0
	s_add_i32 s83, s83, 2
	s_add_u32 s12, s12, 0x100
	s_addc_u32 s13, s13, 0
	s_add_u32 s81, s81, 0x100
	s_addc_u32 s82, s82, 0
	s_cmpk_gt_u32 s83, 0x55
	s_cbranch_scc0 .LBB0_379
	s_and_b64 vcc, exec, s[34:35]
	s_cbranch_vccz .LBB0_382
	s_barrier

.LBB0_468:
	s_ashr_i32 s11, s10, 31
	s_lshl_b64 s[70:71], s[10:11], 20
	s_add_u32 s70, s89, s70
	s_addc_u32 s71, s90, s71
	s_and_b64 s[72:73], s[4:5], exec
	s_cselect_b32 s11, s71, s1
	s_cselect_b32 s76, s70, s0
	s_ashr_i32 s69, s68, 31
	s_lshl_b64 s[72:73], s[68:69], 20
	s_add_u32 s72, s91, s72
	s_addc_u32 s73, s92, s73
	s_and_b64 s[74:75], s[4:5], exec
	s_cselect_b32 s69, s73, s9
	s_cselect_b32 s77, s72, s8
	s_add_u32 s0, s0, 0x80080
	s_addc_u32 s1, s1, 0
	s_add_u32 s78, s8, 0x100
	v_mov_b32_e32 v70, 0
	v_mov_b32_e32 v71, 0
	s_addc_u32 s79, s9, 0
	s_mov_b32 s80, -2
	v_mov_b64_e32 v[2:3], v[70:71]
	v_mov_b64_e32 v[4:5], v[70:71]
	v_mov_b64_e32 v[6:7], v[70:71]
	v_mov_b64_e32 v[8:9], v[70:71]
	v_mov_b64_e32 v[10:11], v[70:71]
	v_mov_b64_e32 v[12:13], v[70:71]
	v_mov_b64_e32 v[14:15], v[70:71]
	v_mov_b64_e32 v[16:17], v[70:71]
	v_mov_b64_e32 v[18:19], v[70:71]
	v_mov_b64_e32 v[20:21], v[70:71]
	v_mov_b64_e32 v[22:23], v[70:71]
	v_mov_b64_e32 v[24:25], v[70:71]
	v_mov_b64_e32 v[26:27], v[70:71]
	v_mov_b64_e32 v[28:29], v[70:71]
	v_mov_b64_e32 v[30:31], v[70:71]
	v_mov_b64_e32 v[32:33], v[70:71]
	v_mov_b64_e32 v[34:35], v[70:71]
	v_mov_b64_e32 v[36:37], v[70:71]
	v_mov_b64_e32 v[38:39], v[70:71]
	v_mov_b64_e32 v[40:41], v[70:71]
	v_mov_b64_e32 v[42:43], v[70:71]
	v_mov_b64_e32 v[44:45], v[70:71]
	v_mov_b64_e32 v[46:47], v[70:71]
	v_mov_b64_e32 v[48:49], v[70:71]
	v_mov_b64_e32 v[54:55], v[70:71]
	v_mov_b64_e32 v[56:57], v[70:71]
	v_mov_b64_e32 v[58:59], v[70:71]
	v_mov_b64_e32 v[60:61], v[70:71]
	v_mov_b64_e32 v[62:63], v[70:71]
	v_mov_b64_e32 v[64:65], v[70:71]
	v_mov_b64_e32 v[66:67], v[70:71]
	v_mov_b64_e32 v[68:69], v[70:71]
	v_mov_b64_e32 v[72:73], v[70:71]
	v_mov_b64_e32 v[74:75], v[70:71]
	v_mov_b64_e32 v[76:77], v[70:71]
	v_mov_b64_e32 v[82:83], v[70:71]
	v_mov_b64_e32 v[84:85], v[70:71]
	v_mov_b64_e32 v[86:87], v[70:71]
	v_mov_b64_e32 v[88:89], v[70:71]
	v_mov_b64_e32 v[90:91], v[70:71]
	v_mov_b64_e32 v[92:93], v[70:71]
	v_mov_b64_e32 v[94:95], v[70:71]
	v_mov_b64_e32 v[96:97], v[70:71]
	v_mov_b64_e32 v[98:99], v[70:71]
	v_mov_b64_e32 v[100:101], v[70:71]
	v_mov_b64_e32 v[102:103], v[70:71]
	v_mov_b64_e32 v[104:105], v[70:71]
	v_mov_b64_e32 v[106:107], v[70:71]
	v_mov_b64_e32 v[108:109], v[70:71]
	v_mov_b64_e32 v[110:111], v[70:71]
	v_mov_b64_e32 v[112:113], v[70:71]
	v_mov_b64_e32 v[114:115], v[70:71]
	v_mov_b64_e32 v[116:117], v[70:71]
	v_mov_b64_e32 v[118:119], v[70:71]
	v_mov_b64_e32 v[120:121], v[70:71]
	v_mov_b64_e32 v[122:123], v[70:71]
	v_mov_b64_e32 v[124:125], v[70:71]
	v_mov_b64_e32 v[126:127], v[70:71]
	v_mov_b64_e32 v[128:129], v[70:71]
	v_mov_b64_e32 v[130:131], v[70:71]
	v_mov_b64_e32 v[132:133], v[70:71]
	v_mov_b64_e32 v[134:135], v[70:71]
	v_mov_b64_e32 v[136:137], v[70:71]
.LBB0_469:
	ds_read_b128 v[78:81], v204
	ds_read_b128 v[138:141], v204 offset:1024
	ds_read_b128 v[142:145], v204 offset:2048
	ds_read_b128 v[146:149], v204 offset:3072
	ds_read_b128 v[170:173], v205
	ds_read_b128 v[174:177], v205 offset:1024
	ds_read_b128 v[180:183], v205 offset:2048
	ds_read_b128 v[210:213], v205 offset:3072
	s_add_u32 s8, s0, 0xfff80080
	s_addc_u32 s9, s1, -1
	s_cmp_eq_u32 s80, 28
	s_cselect_b32 s75, s11, s9
	s_cselect_b32 s74, s76, s8
	s_cselect_b32 s9, s69, s79
	s_cselect_b32 s8, s77, s78
	v_lshl_add_u64 v[246:247], s[0:1], 0, v[162:163]
	s_add_i32 m0, s94, 0xc000
	ds_read_b128 v[214:217], v206
	ds_read_b128 v[218:221], v206 offset:1024
	ds_read_b128 v[222:225], v206 offset:2048
	ds_read_b128 v[226:229], v206 offset:3072
	ds_read_b128 v[230:233], v206 offset:4096
	ds_read_b128 v[234:237], v206 offset:5120
	ds_read_b128 v[238:241], v206 offset:6144
	ds_read_b128 v[242:245], v206 offset:7168
	global_load_lds_dwordx4 v[246:247], off
	v_lshl_add_u64 v[246:247], s[0:1], 0, v[164:165]
	s_add_i32 m0, s94, 0xe000
	s_nop 0
	global_load_lds_dwordx4 v[246:247], off
	s_waitcnt vmcnt(8)
	s_waitcnt lgkmcnt(0)
	s_setprio 1
	s_barrier
	v_mfma_f32_16x16x32_bf16 v[66:69], v[78:81], v[214:217], v[66:69]
	v_mfma_f32_16x16x32_bf16 v[62:65], v[142:145], v[214:217], v[62:65]
	v_mfma_f32_16x16x32_bf16 v[58:61], v[78:81], v[222:225], v[58:61]
	v_mfma_f32_16x16x32_bf16 v[54:57], v[142:145], v[222:225], v[54:57]
	v_mfma_f32_16x16x32_bf16 v[46:49], v[78:81], v[230:233], v[46:49]
	v_mfma_f32_16x16x32_bf16 v[42:45], v[142:145], v[230:233], v[42:45]
	v_mfma_f32_16x16x32_bf16 v[38:41], v[78:81], v[238:241], v[38:41]
	v_mfma_f32_16x16x32_bf16 v[34:37], v[142:145], v[238:241], v[34:37]
	v_mfma_f32_16x16x32_bf16 v[66:69], v[138:141], v[218:221], v[66:69]
	v_mfma_f32_16x16x32_bf16 v[62:65], v[146:149], v[218:221], v[62:65]
	v_mfma_f32_16x16x32_bf16 v[58:61], v[138:141], v[226:229], v[58:61]
	v_mfma_f32_16x16x32_bf16 v[54:57], v[146:149], v[226:229], v[54:57]
	v_mfma_f32_16x16x32_bf16 v[46:49], v[138:141], v[234:237], v[46:49]
	v_mfma_f32_16x16x32_bf16 v[42:45], v[146:149], v[234:237], v[42:45]
	v_mfma_f32_16x16x32_bf16 v[38:41], v[138:141], v[242:245], v[38:41]
	v_mfma_f32_16x16x32_bf16 v[34:37], v[146:149], v[242:245], v[34:37]
	s_setprio 0
	s_setprio 1
	v_mfma_f32_16x16x32_bf16 v[134:137], v[170:173], v[214:217], v[134:137]
	v_mfma_f32_16x16x32_bf16 v[130:133], v[180:183], v[214:217], v[130:133]
	v_mfma_f32_16x16x32_bf16 v[126:129], v[170:173], v[222:225], v[126:129]
	v_mfma_f32_16x16x32_bf16 v[122:125], v[180:183], v[222:225], v[122:125]
	v_mfma_f32_16x16x32_bf16 v[118:121], v[170:173], v[230:233], v[118:121]
	v_mfma_f32_16x16x32_bf16 v[114:117], v[180:183], v[230:233], v[114:117]
	v_mfma_f32_16x16x32_bf16 v[110:113], v[170:173], v[238:241], v[110:113]
	v_mfma_f32_16x16x32_bf16 v[106:109], v[180:183], v[238:241], v[106:109]
	v_mfma_f32_16x16x32_bf16 v[134:137], v[174:177], v[218:221], v[134:137]
	v_mfma_f32_16x16x32_bf16 v[130:133], v[210:213], v[218:221], v[130:133]
	v_mfma_f32_16x16x32_bf16 v[126:129], v[174:177], v[226:229], v[126:129]
	v_mfma_f32_16x16x32_bf16 v[122:125], v[210:213], v[226:229], v[122:125]
	v_mfma_f32_16x16x32_bf16 v[118:121], v[174:177], v[234:237], v[118:121]
	v_mfma_f32_16x16x32_bf16 v[114:117], v[210:213], v[234:237], v[114:117]
	v_mfma_f32_16x16x32_bf16 v[110:113], v[174:177], v[242:245], v[110:113]
	v_mfma_f32_16x16x32_bf16 v[106:109], v[210:213], v[242:245], v[106:109]
	s_barrier
	s_setprio 0
	s_add_i32 s81, s53, s93
	v_lshl_add_u64 v[246:247], s[8:9], 0, v[152:153]
	s_mov_b32 m0, s81
	ds_read_b128 v[214:217], v206 offset:16384
	ds_read_b128 v[218:221], v206 offset:17408
	ds_read_b128 v[222:225], v206 offset:18432
	ds_read_b128 v[226:229], v206 offset:19456
	ds_read_b128 v[230:233], v206 offset:20480
	ds_read_b128 v[234:237], v206 offset:21504
	ds_read_b128 v[238:241], v206 offset:22528
	ds_read_b128 v[242:245], v206 offset:23552
	global_load_lds_dwordx4 v[246:247], off
	s_add_i32 m0, s81, 0x2000
	s_add_u32 s82, s8, 0x80000
	v_lshl_add_u64 v[248:249], s[8:9], 0, v[156:157]
	s_addc_u32 s83, s9, 0
	s_add_i32 s81, s54, s93
	global_load_lds_dwordx4 v[248:249], off
	v_lshl_add_u64 v[250:251], s[82:83], 0, v[152:153]
	s_mov_b32 m0, s81
	v_lshl_add_u64 v[252:253], s[74:75], 0, v[154:155]
	global_load_lds_dwordx4 v[250:251], off
	v_lshl_add_u64 v[250:251], s[82:83], 0, v[156:157]
	s_add_i32 m0, s81, 0x2000
	s_nop 0
	global_load_lds_dwordx4 v[250:251], off
	v_lshl_add_u64 v[250:251], s[74:75], 0, v[150:151]
	s_mov_b32 m0, s94
	s_nop 0
	global_load_lds_dwordx4 v[250:251], off
	s_mov_b32 m0, s95
	s_nop 0
	global_load_lds_dwordx4 v[252:253], off
	s_waitcnt vmcnt(8)
	s_waitcnt lgkmcnt(0)
	s_setprio 1
	s_barrier
	v_mfma_f32_16x16x32_bf16 v[30:33], v[78:81], v[214:217], v[30:33]
	v_mfma_f32_16x16x32_bf16 v[26:29], v[142:145], v[214:217], v[26:29]
	v_mfma_f32_16x16x32_bf16 v[22:25], v[78:81], v[222:225], v[22:25]
	v_mfma_f32_16x16x32_bf16 v[18:21], v[142:145], v[222:225], v[18:21]
	v_mfma_f32_16x16x32_bf16 v[14:17], v[78:81], v[230:233], v[14:17]
	v_mfma_f32_16x16x32_bf16 v[10:13], v[142:145], v[230:233], v[10:13]
	v_mfma_f32_16x16x32_bf16 v[6:9], v[78:81], v[238:241], v[6:9]
	v_mfma_f32_16x16x32_bf16 v[2:5], v[142:145], v[238:241], v[2:5]
	v_mfma_f32_16x16x32_bf16 v[30:33], v[138:141], v[218:221], v[30:33]
	v_mfma_f32_16x16x32_bf16 v[26:29], v[146:149], v[218:221], v[26:29]
	v_mfma_f32_16x16x32_bf16 v[22:25], v[138:141], v[226:229], v[22:25]
	v_mfma_f32_16x16x32_bf16 v[18:21], v[146:149], v[226:229], v[18:21]
	v_mfma_f32_16x16x32_bf16 v[14:17], v[138:141], v[234:237], v[14:17]
	v_mfma_f32_16x16x32_bf16 v[10:13], v[146:149], v[234:237], v[10:13]
	v_mfma_f32_16x16x32_bf16 v[6:9], v[138:141], v[242:245], v[6:9]
	v_mfma_f32_16x16x32_bf16 v[2:5], v[146:149], v[242:245], v[2:5]
	s_setprio 0
	s_setprio 1
	v_mfma_f32_16x16x32_bf16 v[98:101], v[180:183], v[214:217], v[98:101]
	v_mfma_f32_16x16x32_bf16 v[94:97], v[170:173], v[222:225], v[94:97]
	v_mfma_f32_16x16x32_bf16 v[90:93], v[180:183], v[222:225], v[90:93]
	v_mfma_f32_16x16x32_bf16 v[86:89], v[170:173], v[230:233], v[86:89]
	v_mfma_f32_16x16x32_bf16 v[82:85], v[180:183], v[230:233], v[82:85]
	v_mfma_f32_16x16x32_bf16 v[74:77], v[170:173], v[238:241], v[74:77]
	v_mfma_f32_16x16x32_bf16 v[70:73], v[180:183], v[238:241], v[70:73]
	v_mfma_f32_16x16x32_bf16 v[78:81], v[170:173], v[214:217], v[102:105]
	v_mfma_f32_16x16x32_bf16 v[98:101], v[210:213], v[218:221], v[98:101]
	v_mfma_f32_16x16x32_bf16 v[94:97], v[174:177], v[226:229], v[94:97]
	v_mfma_f32_16x16x32_bf16 v[90:93], v[210:213], v[226:229], v[90:93]
	v_mfma_f32_16x16x32_bf16 v[86:89], v[174:177], v[234:237], v[86:89]
	v_mfma_f32_16x16x32_bf16 v[82:85], v[210:213], v[234:237], v[82:85]
	v_mfma_f32_16x16x32_bf16 v[74:77], v[174:177], v[242:245], v[74:77]
	v_mfma_f32_16x16x32_bf16 v[70:73], v[210:213], v[242:245], v[70:73]
	v_mfma_f32_16x16x32_bf16 v[78:81], v[174:177], v[218:221], v[78:81]
	s_barrier
	s_setprio 0
	s_add_i32 s81, 0, 0x18000
	v_add_u32_e32 v1, s81, v194
	s_add_i32 s82, 0, 0x1c000
	ds_read_b128 v[102:105], v1
	ds_read_b128 v[138:141], v1 offset:1024
	ds_read_b128 v[142:145], v1 offset:2048
	ds_read_b128 v[146:149], v1 offset:3072
	v_add_u32_e32 v1, s82, v194
	ds_read_b128 v[170:173], v1
	ds_read_b128 v[174:177], v1 offset:1024
	ds_read_b128 v[180:183], v1 offset:2048
	ds_read_b128 v[210:213], v1 offset:3072
	s_add_u32 s74, s74, 0x80000
	s_addc_u32 s75, s75, 0
	s_mov_b32 m0, s96
	v_lshl_add_u64 v[190:191], s[74:75], 0, v[150:151]
	ds_read_b128 v[214:217], v206 offset:32768
	ds_read_b128 v[218:221], v206 offset:33792
	ds_read_b128 v[222:225], v206 offset:34816
	ds_read_b128 v[226:229], v206 offset:35840
	ds_read_b128 v[230:233], v206 offset:36864
	ds_read_b128 v[234:237], v206 offset:37888
	ds_read_b128 v[238:241], v206 offset:38912
	ds_read_b128 v[242:245], v206 offset:39936
	global_load_lds_dwordx4 v[190:191], off
	v_lshl_add_u64 v[190:191], s[74:75], 0, v[154:155]
	s_mov_b32 m0, s97
	s_nop 0
	global_load_lds_dwordx4 v[190:191], off
	s_waitcnt vmcnt(8)
	s_waitcnt lgkmcnt(0)
	s_setprio 1
	s_barrier
	v_mfma_f32_16x16x32_bf16 v[66:69], v[102:105], v[214:217], v[66:69]
	v_mfma_f32_16x16x32_bf16 v[62:65], v[142:145], v[214:217], v[62:65]
	v_mfma_f32_16x16x32_bf16 v[58:61], v[102:105], v[222:225], v[58:61]
	v_mfma_f32_16x16x32_bf16 v[54:57], v[142:145], v[222:225], v[54:57]
	v_mfma_f32_16x16x32_bf16 v[46:49], v[102:105], v[230:233], v[46:49]
	v_mfma_f32_16x16x32_bf16 v[42:45], v[142:145], v[230:233], v[42:45]
	v_mfma_f32_16x16x32_bf16 v[38:41], v[102:105], v[238:241], v[38:41]
	v_mfma_f32_16x16x32_bf16 v[34:37], v[142:145], v[238:241], v[34:37]
	v_mfma_f32_16x16x32_bf16 v[66:69], v[138:141], v[218:221], v[66:69]
	v_mfma_f32_16x16x32_bf16 v[62:65], v[146:149], v[218:221], v[62:65]
	v_mfma_f32_16x16x32_bf16 v[58:61], v[138:141], v[226:229], v[58:61]
	v_mfma_f32_16x16x32_bf16 v[54:57], v[146:149], v[226:229], v[54:57]
	v_mfma_f32_16x16x32_bf16 v[46:49], v[138:141], v[234:237], v[46:49]
	v_mfma_f32_16x16x32_bf16 v[42:45], v[146:149], v[234:237], v[42:45]
	v_mfma_f32_16x16x32_bf16 v[38:41], v[138:141], v[242:245], v[38:41]
	v_mfma_f32_16x16x32_bf16 v[34:37], v[146:149], v[242:245], v[34:37]
	s_setprio 0
	s_setprio 1
	v_mfma_f32_16x16x32_bf16 v[134:137], v[170:173], v[214:217], v[134:137]
	v_mfma_f32_16x16x32_bf16 v[130:133], v[180:183], v[214:217], v[130:133]
	v_mfma_f32_16x16x32_bf16 v[126:129], v[170:173], v[222:225], v[126:129]
	v_mfma_f32_16x16x32_bf16 v[122:125], v[180:183], v[222:225], v[122:125]
	v_mfma_f32_16x16x32_bf16 v[118:121], v[170:173], v[230:233], v[118:121]
	v_mfma_f32_16x16x32_bf16 v[114:117], v[180:183], v[230:233], v[114:117]
	v_mfma_f32_16x16x32_bf16 v[110:113], v[170:173], v[238:241], v[110:113]
	v_mfma_f32_16x16x32_bf16 v[106:109], v[180:183], v[238:241], v[106:109]
	v_mfma_f32_16x16x32_bf16 v[134:137], v[174:177], v[218:221], v[134:137]
	v_mfma_f32_16x16x32_bf16 v[130:133], v[210:213], v[218:221], v[130:133]
	v_mfma_f32_16x16x32_bf16 v[126:129], v[174:177], v[226:229], v[126:129]
	v_mfma_f32_16x16x32_bf16 v[122:125], v[210:213], v[226:229], v[122:125]
	v_mfma_f32_16x16x32_bf16 v[118:121], v[174:177], v[234:237], v[118:121]
	v_mfma_f32_16x16x32_bf16 v[114:117], v[210:213], v[234:237], v[114:117]
	v_mfma_f32_16x16x32_bf16 v[110:113], v[174:177], v[242:245], v[110:113]
	v_mfma_f32_16x16x32_bf16 v[106:109], v[210:213], v[242:245], v[106:109]
	s_barrier
	s_setprio 0
	s_add_i32 s74, s81, s93
	v_lshl_add_u64 v[190:191], v[246:247], 0, s[56:57]
	s_mov_b32 m0, s74
	ds_read_b128 v[214:217], v206 offset:49152
	ds_read_b128 v[218:221], v206 offset:50176
	ds_read_b128 v[222:225], v206 offset:51200
	ds_read_b128 v[226:229], v206 offset:52224
	ds_read_b128 v[230:233], v206 offset:53248
	ds_read_b128 v[234:237], v206 offset:54272
	ds_read_b128 v[238:241], v206 offset:55296
	ds_read_b128 v[242:245], v206 offset:56320
	global_load_lds_dwordx4 v[190:191], off
	s_add_i32 m0, s74, 0x2000
	s_add_u32 s8, s8, 0x80080
	v_lshl_add_u64 v[190:191], v[248:249], 0, s[56:57]
	s_addc_u32 s9, s9, 0
	s_add_i32 s74, s82, s93
	global_load_lds_dwordx4 v[190:191], off
	v_lshl_add_u64 v[190:191], s[8:9], 0, v[152:153]
	s_mov_b32 m0, s74
	s_nop 0
	global_load_lds_dwordx4 v[190:191], off
	v_lshl_add_u64 v[190:191], s[8:9], 0, v[156:157]
	s_add_i32 m0, s74, 0x2000
	s_nop 0
	global_load_lds_dwordx4 v[190:191], off
	v_lshl_add_u64 v[190:191], v[250:251], 0, s[56:57]
	s_mov_b32 m0, s85
	s_nop 0
	global_load_lds_dwordx4 v[190:191], off
	v_lshl_add_u64 v[190:191], v[252:253], 0, s[56:57]
	s_mov_b32 m0, s18
	s_nop 0
	global_load_lds_dwordx4 v[190:191], off
	s_waitcnt vmcnt(8)
	s_waitcnt lgkmcnt(0)
	s_setprio 1
	s_barrier
	v_mfma_f32_16x16x32_bf16 v[30:33], v[102:105], v[214:217], v[30:33]
	v_mfma_f32_16x16x32_bf16 v[26:29], v[142:145], v[214:217], v[26:29]
	v_mfma_f32_16x16x32_bf16 v[22:25], v[102:105], v[222:225], v[22:25]
	v_mfma_f32_16x16x32_bf16 v[18:21], v[142:145], v[222:225], v[18:21]
	v_mfma_f32_16x16x32_bf16 v[14:17], v[102:105], v[230:233], v[14:17]
	v_mfma_f32_16x16x32_bf16 v[10:13], v[142:145], v[230:233], v[10:13]
	v_mfma_f32_16x16x32_bf16 v[6:9], v[102:105], v[238:241], v[6:9]
	v_mfma_f32_16x16x32_bf16 v[2:5], v[142:145], v[238:241], v[2:5]
	v_mfma_f32_16x16x32_bf16 v[30:33], v[138:141], v[218:221], v[30:33]
	v_mfma_f32_16x16x32_bf16 v[26:29], v[146:149], v[218:221], v[26:29]
	v_mfma_f32_16x16x32_bf16 v[22:25], v[138:141], v[226:229], v[22:25]
	v_mfma_f32_16x16x32_bf16 v[18:21], v[146:149], v[226:229], v[18:21]
	v_mfma_f32_16x16x32_bf16 v[14:17], v[138:141], v[234:237], v[14:17]
	v_mfma_f32_16x16x32_bf16 v[10:13], v[146:149], v[234:237], v[10:13]
	v_mfma_f32_16x16x32_bf16 v[6:9], v[138:141], v[242:245], v[6:9]
	v_mfma_f32_16x16x32_bf16 v[2:5], v[146:149], v[242:245], v[2:5]
	s_setprio 0
	s_setprio 1
	v_mfma_f32_16x16x32_bf16 v[78:81], v[170:173], v[214:217], v[78:81]
	v_mfma_f32_16x16x32_bf16 v[102:105], v[174:177], v[218:221], v[78:81]
	v_mfma_f32_16x16x32_bf16 v[78:81], v[180:183], v[214:217], v[98:101]
	v_mfma_f32_16x16x32_bf16 v[98:101], v[210:213], v[218:221], v[78:81]
	v_mfma_f32_16x16x32_bf16 v[78:81], v[170:173], v[222:225], v[94:97]
	v_mfma_f32_16x16x32_bf16 v[94:97], v[174:177], v[226:229], v[78:81]
	v_mfma_f32_16x16x32_bf16 v[78:81], v[180:183], v[222:225], v[90:93]
	v_mfma_f32_16x16x32_bf16 v[90:93], v[210:213], v[226:229], v[78:81]
	v_mfma_f32_16x16x32_bf16 v[78:81], v[170:173], v[230:233], v[86:89]
	v_mfma_f32_16x16x32_bf16 v[86:89], v[174:177], v[234:237], v[78:81]
	v_mfma_f32_16x16x32_bf16 v[78:81], v[180:183], v[230:233], v[82:85]
	v_mfma_f32_16x16x32_bf16 v[74:77], v[170:173], v[238:241], v[74:77]
	v_mfma_f32_16x16x32_bf16 v[70:73], v[180:183], v[238:241], v[70:73]
	v_mfma_f32_16x16x32_bf16 v[82:85], v[210:213], v[234:237], v[78:81]
	v_mfma_f32_16x16x32_bf16 v[74:77], v[174:177], v[242:245], v[74:77]
	v_mfma_f32_16x16x32_bf16 v[70:73], v[210:213], v[242:245], v[70:73]
	s_barrier
	s_setprio 0
	s_add_i32 s80, s80, 2
	s_add_u32 s0, s0, 0x100
	s_addc_u32 s1, s1, 0
	s_add_u32 s78, s78, 0x100
	s_addc_u32 s79, s79, 0
	s_cmp_gt_u32 s80, 29
	s_cbranch_scc0 .LBB0_469
	s_and_b64 vcc, exec, s[58:59]
	s_cbranch_vccz .LBB0_472
	s_barrier

.LBB0_700:
	s_ashr_i32 s37, s36, 31
	s_lshl_b64 s[40:41], s[36:37], 20
	s_add_u32 s40, s18, s40
	s_addc_u32 s41, s19, s41
	s_and_b64 s[42:43], s[16:17], exec
	s_cselect_b32 s37, s41, s55
	s_cselect_b32 s75, s40, s54
	s_ashr_i32 s35, s34, 31
	s_lshl_b64 s[42:43], s[34:35], 20
	s_add_u32 s42, s28, s42
	s_addc_u32 s43, s29, s43
	s_and_b64 s[58:59], s[16:17], exec
	s_cselect_b32 s35, s43, s57
	s_cselect_b32 s76, s42, s56
	s_add_u32 s54, s54, 0x80080
	s_addc_u32 s55, s55, 0
	s_add_u32 s77, s56, 0x100
	v_mov_b32_e32 v2, 0
	v_mov_b32_e32 v3, 0
	s_addc_u32 s78, s57, 0
	s_mov_b32 s79, -2
	v_mov_b64_e32 v[4:5], v[2:3]
	v_mov_b64_e32 v[6:7], v[2:3]
	v_mov_b64_e32 v[8:9], v[2:3]
	v_mov_b64_e32 v[10:11], v[2:3]
	v_mov_b64_e32 v[12:13], v[2:3]
	v_mov_b64_e32 v[14:15], v[2:3]
	v_mov_b64_e32 v[16:17], v[2:3]
	v_mov_b64_e32 v[18:19], v[2:3]
	v_mov_b64_e32 v[20:21], v[2:3]
	v_mov_b64_e32 v[22:23], v[2:3]
	v_mov_b64_e32 v[24:25], v[2:3]
	v_mov_b64_e32 v[26:27], v[2:3]
	v_mov_b64_e32 v[28:29], v[2:3]
	v_mov_b64_e32 v[30:31], v[2:3]
	v_mov_b64_e32 v[32:33], v[2:3]
	v_mov_b64_e32 v[34:35], v[2:3]
	v_mov_b64_e32 v[36:37], v[2:3]
	v_mov_b64_e32 v[38:39], v[2:3]
	v_mov_b64_e32 v[40:41], v[2:3]
	v_mov_b64_e32 v[42:43], v[2:3]
	v_mov_b64_e32 v[44:45], v[2:3]
	v_mov_b64_e32 v[46:47], v[2:3]
	v_mov_b64_e32 v[48:49], v[2:3]
	v_mov_b64_e32 v[50:51], v[2:3]
	v_mov_b64_e32 v[52:53], v[2:3]
	v_mov_b64_e32 v[54:55], v[2:3]
	v_mov_b64_e32 v[56:57], v[2:3]
	v_mov_b64_e32 v[58:59], v[2:3]
	v_mov_b64_e32 v[60:61], v[2:3]
	v_mov_b64_e32 v[62:63], v[2:3]
	v_mov_b64_e32 v[64:65], v[2:3]
	v_mov_b64_e32 v[66:67], v[2:3]
	v_mov_b64_e32 v[68:69], v[2:3]
	v_mov_b64_e32 v[70:71], v[2:3]
	v_mov_b64_e32 v[72:73], v[2:3]
	v_mov_b64_e32 v[74:75], v[2:3]
	v_mov_b64_e32 v[76:77], v[2:3]
	v_mov_b64_e32 v[78:79], v[2:3]
	v_mov_b64_e32 v[80:81], v[2:3]
	v_mov_b64_e32 v[82:83], v[2:3]
	v_mov_b64_e32 v[84:85], v[2:3]
	v_mov_b64_e32 v[86:87], v[2:3]
	v_mov_b64_e32 v[88:89], v[2:3]
	v_mov_b64_e32 v[90:91], v[2:3]
	v_mov_b64_e32 v[92:93], v[2:3]
	v_mov_b64_e32 v[94:95], v[2:3]
	v_mov_b64_e32 v[96:97], v[2:3]
	v_mov_b64_e32 v[98:99], v[2:3]
	v_mov_b64_e32 v[100:101], v[2:3]
	v_mov_b64_e32 v[102:103], v[2:3]
	v_mov_b64_e32 v[104:105], v[2:3]
	v_mov_b64_e32 v[106:107], v[2:3]
	v_mov_b64_e32 v[108:109], v[2:3]
	v_mov_b64_e32 v[110:111], v[2:3]
	v_mov_b64_e32 v[112:113], v[2:3]
	v_mov_b64_e32 v[114:115], v[2:3]
	v_mov_b64_e32 v[116:117], v[2:3]
	v_mov_b64_e32 v[118:119], v[2:3]
	v_mov_b64_e32 v[120:121], v[2:3]
	v_mov_b64_e32 v[122:123], v[2:3]
	v_mov_b64_e32 v[124:125], v[2:3]
	v_mov_b64_e32 v[126:127], v[2:3]
	v_mov_b64_e32 v[128:129], v[2:3]
.LBB0_701:
	ds_read_b128 v[144:147], v141
	ds_read_b128 v[158:161], v141 offset:1024
	ds_read_b128 v[162:165], v141 offset:2048
	ds_read_b128 v[166:169], v141 offset:3072
	ds_read_b128 v[170:173], v142
	ds_read_b128 v[174:177], v142 offset:1024
	ds_read_b128 v[180:183], v142 offset:2048
	ds_read_b128 v[190:193], v142 offset:3072
	s_add_u32 s56, s54, 0xfff80080
	s_addc_u32 s57, s55, -1
	s_cmp_eq_u32 s79, 28
	s_cselect_b32 s59, s37, s57
	s_cselect_b32 s58, s75, s56
	s_cselect_b32 s57, s35, s78
	s_cselect_b32 s56, s76, s77
	v_lshl_add_u64 v[134:135], s[54:55], 0, v[130:131]
	s_add_i32 m0, s53, 0xc000
	ds_read_b128 v[194:197], v143
	ds_read_b128 v[198:201], v143 offset:1024
	ds_read_b128 v[202:205], v143 offset:2048
	ds_read_b128 v[206:209], v143 offset:3072
	ds_read_b128 v[210:213], v143 offset:4096
	ds_read_b128 v[214:217], v143 offset:5120
	ds_read_b128 v[218:221], v143 offset:6144
	ds_read_b128 v[222:225], v143 offset:7168
	global_load_lds_dwordx4 v[134:135], off
	v_lshl_add_u64 v[134:135], s[54:55], 0, v[132:133]
	s_add_i32 m0, s53, 0xe000
	s_nop 0
	global_load_lds_dwordx4 v[134:135], off
	s_waitcnt vmcnt(8)
	s_waitcnt lgkmcnt(0)
	s_setprio 1
	s_barrier
	v_mfma_f32_16x16x32_bf16 v[126:129], v[144:147], v[194:197], v[126:129]
	v_mfma_f32_16x16x32_bf16 v[122:125], v[162:165], v[194:197], v[122:125]
	v_mfma_f32_16x16x32_bf16 v[114:117], v[144:147], v[202:205], v[114:117]
	v_mfma_f32_16x16x32_bf16 v[106:109], v[162:165], v[202:205], v[106:109]
	v_mfma_f32_16x16x32_bf16 v[98:101], v[144:147], v[210:213], v[98:101]
	v_mfma_f32_16x16x32_bf16 v[90:93], v[162:165], v[210:213], v[90:93]
	v_mfma_f32_16x16x32_bf16 v[82:85], v[144:147], v[218:221], v[82:85]
	v_mfma_f32_16x16x32_bf16 v[74:77], v[162:165], v[218:221], v[74:77]
	v_mfma_f32_16x16x32_bf16 v[126:129], v[158:161], v[198:201], v[126:129]
	v_mfma_f32_16x16x32_bf16 v[122:125], v[166:169], v[198:201], v[122:125]
	v_mfma_f32_16x16x32_bf16 v[114:117], v[158:161], v[206:209], v[114:117]
	v_mfma_f32_16x16x32_bf16 v[106:109], v[166:169], v[206:209], v[106:109]
	v_mfma_f32_16x16x32_bf16 v[98:101], v[158:161], v[214:217], v[98:101]
	v_mfma_f32_16x16x32_bf16 v[90:93], v[166:169], v[214:217], v[90:93]
	v_mfma_f32_16x16x32_bf16 v[82:85], v[158:161], v[222:225], v[82:85]
	v_mfma_f32_16x16x32_bf16 v[74:77], v[166:169], v[222:225], v[74:77]
	s_setprio 0
	s_setprio 1
	v_mfma_f32_16x16x32_bf16 v[118:121], v[170:173], v[194:197], v[118:121]
	v_mfma_f32_16x16x32_bf16 v[110:113], v[180:183], v[194:197], v[110:113]
	v_mfma_f32_16x16x32_bf16 v[102:105], v[170:173], v[202:205], v[102:105]
	v_mfma_f32_16x16x32_bf16 v[94:97], v[180:183], v[202:205], v[94:97]
	v_mfma_f32_16x16x32_bf16 v[86:89], v[170:173], v[210:213], v[86:89]
	v_mfma_f32_16x16x32_bf16 v[78:81], v[180:183], v[210:213], v[78:81]
	v_mfma_f32_16x16x32_bf16 v[70:73], v[170:173], v[218:221], v[70:73]
	v_mfma_f32_16x16x32_bf16 v[66:69], v[180:183], v[218:221], v[66:69]
	v_mfma_f32_16x16x32_bf16 v[118:121], v[174:177], v[198:201], v[118:121]
	v_mfma_f32_16x16x32_bf16 v[110:113], v[190:193], v[198:201], v[110:113]
	v_mfma_f32_16x16x32_bf16 v[102:105], v[174:177], v[206:209], v[102:105]
	v_mfma_f32_16x16x32_bf16 v[94:97], v[190:193], v[206:209], v[94:97]
	v_mfma_f32_16x16x32_bf16 v[86:89], v[174:177], v[214:217], v[86:89]
	v_mfma_f32_16x16x32_bf16 v[78:81], v[190:193], v[214:217], v[78:81]
	v_mfma_f32_16x16x32_bf16 v[70:73], v[174:177], v[222:225], v[70:73]
	v_mfma_f32_16x16x32_bf16 v[66:69], v[190:193], v[222:225], v[66:69]
	s_barrier
	s_setprio 0
	s_add_i32 s80, s68, s60
	v_lshl_add_u64 v[134:135], s[56:57], 0, v[152:153]
	s_mov_b32 m0, s80
	ds_read_b128 v[194:197], v143 offset:16384
	ds_read_b128 v[198:201], v143 offset:17408
	ds_read_b128 v[202:205], v143 offset:18432
	ds_read_b128 v[206:209], v143 offset:19456
	ds_read_b128 v[210:213], v143 offset:20480
	ds_read_b128 v[214:217], v143 offset:21504
	ds_read_b128 v[218:221], v143 offset:22528
	ds_read_b128 v[222:225], v143 offset:23552
	global_load_lds_dwordx4 v[134:135], off
	s_add_i32 m0, s80, 0x2000
	s_add_u32 s80, s56, 0x80000
	v_lshl_add_u64 v[148:149], s[56:57], 0, v[156:157]
	s_addc_u32 s81, s57, 0
	s_add_i32 s82, s69, s60
	global_load_lds_dwordx4 v[148:149], off
	v_lshl_add_u64 v[226:227], s[80:81], 0, v[152:153]
	s_mov_b32 m0, s82
	v_lshl_add_u64 v[228:229], s[58:59], 0, v[154:155]
	global_load_lds_dwordx4 v[226:227], off
	v_lshl_add_u64 v[226:227], s[80:81], 0, v[156:157]
	s_add_i32 m0, s82, 0x2000
	s_nop 0
	global_load_lds_dwordx4 v[226:227], off
	v_lshl_add_u64 v[226:227], s[58:59], 0, v[150:151]
	s_mov_b32 m0, s53
	s_nop 0
	global_load_lds_dwordx4 v[226:227], off
	s_mov_b32 m0, s61
	s_nop 0
	global_load_lds_dwordx4 v[228:229], off
	s_waitcnt vmcnt(8)
	s_waitcnt lgkmcnt(0)
	s_setprio 1
	s_barrier
	v_mfma_f32_16x16x32_bf16 v[62:65], v[144:147], v[194:197], v[62:65]
	v_mfma_f32_16x16x32_bf16 v[58:61], v[162:165], v[194:197], v[58:61]
	v_mfma_f32_16x16x32_bf16 v[50:53], v[144:147], v[202:205], v[50:53]
	v_mfma_f32_16x16x32_bf16 v[42:45], v[162:165], v[202:205], v[42:45]
	v_mfma_f32_16x16x32_bf16 v[34:37], v[144:147], v[210:213], v[34:37]
	v_mfma_f32_16x16x32_bf16 v[26:29], v[162:165], v[210:213], v[26:29]
	v_mfma_f32_16x16x32_bf16 v[18:21], v[144:147], v[218:221], v[18:21]
	v_mfma_f32_16x16x32_bf16 v[10:13], v[162:165], v[218:221], v[10:13]
	v_mfma_f32_16x16x32_bf16 v[62:65], v[158:161], v[198:201], v[62:65]
	v_mfma_f32_16x16x32_bf16 v[58:61], v[166:169], v[198:201], v[58:61]
	v_mfma_f32_16x16x32_bf16 v[50:53], v[158:161], v[206:209], v[50:53]
	v_mfma_f32_16x16x32_bf16 v[42:45], v[166:169], v[206:209], v[42:45]
	v_mfma_f32_16x16x32_bf16 v[34:37], v[158:161], v[214:217], v[34:37]
	v_mfma_f32_16x16x32_bf16 v[26:29], v[166:169], v[214:217], v[26:29]
	v_mfma_f32_16x16x32_bf16 v[18:21], v[158:161], v[222:225], v[18:21]
	v_mfma_f32_16x16x32_bf16 v[10:13], v[166:169], v[222:225], v[10:13]
	s_setprio 0
	s_setprio 1
	v_mfma_f32_16x16x32_bf16 v[54:57], v[170:173], v[194:197], v[54:57]
	v_mfma_f32_16x16x32_bf16 v[46:49], v[180:183], v[194:197], v[46:49]
	v_mfma_f32_16x16x32_bf16 v[38:41], v[170:173], v[202:205], v[38:41]
	v_mfma_f32_16x16x32_bf16 v[30:33], v[180:183], v[202:205], v[30:33]
	v_mfma_f32_16x16x32_bf16 v[22:25], v[170:173], v[210:213], v[22:25]
	v_mfma_f32_16x16x32_bf16 v[14:17], v[180:183], v[210:213], v[14:17]
	v_mfma_f32_16x16x32_bf16 v[6:9], v[170:173], v[218:221], v[6:9]
	v_mfma_f32_16x16x32_bf16 v[2:5], v[180:183], v[218:221], v[2:5]
	v_mfma_f32_16x16x32_bf16 v[54:57], v[174:177], v[198:201], v[54:57]
	v_mfma_f32_16x16x32_bf16 v[46:49], v[190:193], v[198:201], v[46:49]
	v_mfma_f32_16x16x32_bf16 v[38:41], v[174:177], v[206:209], v[38:41]
	v_mfma_f32_16x16x32_bf16 v[30:33], v[190:193], v[206:209], v[30:33]
	v_mfma_f32_16x16x32_bf16 v[22:25], v[174:177], v[214:217], v[22:25]
	v_mfma_f32_16x16x32_bf16 v[14:17], v[190:193], v[214:217], v[14:17]
	v_mfma_f32_16x16x32_bf16 v[6:9], v[174:177], v[222:225], v[6:9]
	v_mfma_f32_16x16x32_bf16 v[2:5], v[190:193], v[222:225], v[2:5]
	s_barrier
	s_setprio 0
	s_add_i32 s80, 0, 0x18000
	v_add_u32_e32 v1, s80, v139
	s_add_i32 s81, 0, 0x1c000
	ds_read_b128 v[144:147], v1
	ds_read_b128 v[158:161], v1 offset:1024
	ds_read_b128 v[162:165], v1 offset:2048
	ds_read_b128 v[166:169], v1 offset:3072
	v_add_u32_e32 v1, s81, v139
	ds_read_b128 v[170:173], v1
	ds_read_b128 v[174:177], v1 offset:1024
	ds_read_b128 v[180:183], v1 offset:2048
	ds_read_b128 v[190:193], v1 offset:3072
	s_add_u32 s58, s58, 0x80000
	s_addc_u32 s59, s59, 0
	s_mov_b32 m0, s62
	v_lshl_add_u64 v[230:231], s[58:59], 0, v[150:151]
	ds_read_b128 v[194:197], v143 offset:32768
	ds_read_b128 v[198:201], v143 offset:33792
	ds_read_b128 v[202:205], v143 offset:34816
	ds_read_b128 v[206:209], v143 offset:35840
	ds_read_b128 v[210:213], v143 offset:36864
	ds_read_b128 v[214:217], v143 offset:37888
	ds_read_b128 v[218:221], v143 offset:38912
	ds_read_b128 v[222:225], v143 offset:39936
	global_load_lds_dwordx4 v[230:231], off
	v_lshl_add_u64 v[230:231], s[58:59], 0, v[154:155]
	s_mov_b32 m0, s63
	s_nop 0
	global_load_lds_dwordx4 v[230:231], off
	s_waitcnt vmcnt(8)
	s_waitcnt lgkmcnt(0)
	s_setprio 1
	s_barrier
	v_mfma_f32_16x16x32_bf16 v[126:129], v[144:147], v[194:197], v[126:129]
	v_mfma_f32_16x16x32_bf16 v[122:125], v[162:165], v[194:197], v[122:125]
	v_mfma_f32_16x16x32_bf16 v[114:117], v[144:147], v[202:205], v[114:117]
	v_mfma_f32_16x16x32_bf16 v[106:109], v[162:165], v[202:205], v[106:109]
	v_mfma_f32_16x16x32_bf16 v[98:101], v[144:147], v[210:213], v[98:101]
	v_mfma_f32_16x16x32_bf16 v[90:93], v[162:165], v[210:213], v[90:93]
	v_mfma_f32_16x16x32_bf16 v[82:85], v[144:147], v[218:221], v[82:85]
	v_mfma_f32_16x16x32_bf16 v[74:77], v[162:165], v[218:221], v[74:77]
	v_mfma_f32_16x16x32_bf16 v[126:129], v[158:161], v[198:201], v[126:129]
	v_mfma_f32_16x16x32_bf16 v[122:125], v[166:169], v[198:201], v[122:125]
	v_mfma_f32_16x16x32_bf16 v[114:117], v[158:161], v[206:209], v[114:117]
	v_mfma_f32_16x16x32_bf16 v[106:109], v[166:169], v[206:209], v[106:109]
	v_mfma_f32_16x16x32_bf16 v[98:101], v[158:161], v[214:217], v[98:101]
	v_mfma_f32_16x16x32_bf16 v[90:93], v[166:169], v[214:217], v[90:93]
	v_mfma_f32_16x16x32_bf16 v[82:85], v[158:161], v[222:225], v[82:85]
	v_mfma_f32_16x16x32_bf16 v[74:77], v[166:169], v[222:225], v[74:77]
	s_setprio 0
	s_setprio 1
	v_mfma_f32_16x16x32_bf16 v[118:121], v[170:173], v[194:197], v[118:121]
	v_mfma_f32_16x16x32_bf16 v[110:113], v[180:183], v[194:197], v[110:113]
	v_mfma_f32_16x16x32_bf16 v[102:105], v[170:173], v[202:205], v[102:105]
	v_mfma_f32_16x16x32_bf16 v[94:97], v[180:183], v[202:205], v[94:97]
	v_mfma_f32_16x16x32_bf16 v[86:89], v[170:173], v[210:213], v[86:89]
	v_mfma_f32_16x16x32_bf16 v[78:81], v[180:183], v[210:213], v[78:81]
	v_mfma_f32_16x16x32_bf16 v[70:73], v[170:173], v[218:221], v[70:73]
	v_mfma_f32_16x16x32_bf16 v[66:69], v[180:183], v[218:221], v[66:69]
	v_mfma_f32_16x16x32_bf16 v[118:121], v[174:177], v[198:201], v[118:121]
	v_mfma_f32_16x16x32_bf16 v[110:113], v[190:193], v[198:201], v[110:113]
	v_mfma_f32_16x16x32_bf16 v[102:105], v[174:177], v[206:209], v[102:105]
	v_mfma_f32_16x16x32_bf16 v[94:97], v[190:193], v[206:209], v[94:97]
	v_mfma_f32_16x16x32_bf16 v[86:89], v[174:177], v[214:217], v[86:89]
	v_mfma_f32_16x16x32_bf16 v[78:81], v[190:193], v[214:217], v[78:81]
	v_mfma_f32_16x16x32_bf16 v[70:73], v[174:177], v[222:225], v[70:73]
	v_mfma_f32_16x16x32_bf16 v[66:69], v[190:193], v[222:225], v[66:69]
	s_barrier
	s_setprio 0
	s_add_i32 s58, s80, s60
	v_lshl_add_u64 v[134:135], v[134:135], 0, s[4:5]
	s_mov_b32 m0, s58
	ds_read_b128 v[194:197], v143 offset:49152
	ds_read_b128 v[198:201], v143 offset:50176
	ds_read_b128 v[202:205], v143 offset:51200
	ds_read_b128 v[206:209], v143 offset:52224
	ds_read_b128 v[210:213], v143 offset:53248
	ds_read_b128 v[214:217], v143 offset:54272
	ds_read_b128 v[218:221], v143 offset:55296
	ds_read_b128 v[222:225], v143 offset:56320
	global_load_lds_dwordx4 v[134:135], off
	s_add_i32 m0, s58, 0x2000
	s_add_u32 s56, s56, 0x80080
	v_lshl_add_u64 v[134:135], v[148:149], 0, s[4:5]
	s_addc_u32 s57, s57, 0
	s_add_i32 s58, s81, s60
	global_load_lds_dwordx4 v[134:135], off
	v_lshl_add_u64 v[134:135], s[56:57], 0, v[152:153]
	s_mov_b32 m0, s58
	s_nop 0
	global_load_lds_dwordx4 v[134:135], off
	v_lshl_add_u64 v[134:135], s[56:57], 0, v[156:157]
	s_add_i32 m0, s58, 0x2000
	s_nop 0
	global_load_lds_dwordx4 v[134:135], off
	v_lshl_add_u64 v[134:135], v[226:227], 0, s[4:5]
	s_mov_b32 m0, s65
	s_nop 0
	global_load_lds_dwordx4 v[134:135], off
	v_lshl_add_u64 v[134:135], v[228:229], 0, s[4:5]
	s_mov_b32 m0, s66
	s_nop 0
	global_load_lds_dwordx4 v[134:135], off
	s_waitcnt vmcnt(8)
	s_waitcnt lgkmcnt(0)
	s_setprio 1
	s_barrier
	v_mfma_f32_16x16x32_bf16 v[62:65], v[144:147], v[194:197], v[62:65]
	v_mfma_f32_16x16x32_bf16 v[58:61], v[162:165], v[194:197], v[58:61]
	v_mfma_f32_16x16x32_bf16 v[50:53], v[144:147], v[202:205], v[50:53]
	v_mfma_f32_16x16x32_bf16 v[42:45], v[162:165], v[202:205], v[42:45]
	v_mfma_f32_16x16x32_bf16 v[34:37], v[144:147], v[210:213], v[34:37]
	v_mfma_f32_16x16x32_bf16 v[26:29], v[162:165], v[210:213], v[26:29]
	v_mfma_f32_16x16x32_bf16 v[18:21], v[144:147], v[218:221], v[18:21]
	v_mfma_f32_16x16x32_bf16 v[10:13], v[162:165], v[218:221], v[10:13]
	v_mfma_f32_16x16x32_bf16 v[62:65], v[158:161], v[198:201], v[62:65]
	v_mfma_f32_16x16x32_bf16 v[58:61], v[166:169], v[198:201], v[58:61]
	v_mfma_f32_16x16x32_bf16 v[50:53], v[158:161], v[206:209], v[50:53]
	v_mfma_f32_16x16x32_bf16 v[42:45], v[166:169], v[206:209], v[42:45]
	v_mfma_f32_16x16x32_bf16 v[34:37], v[158:161], v[214:217], v[34:37]
	v_mfma_f32_16x16x32_bf16 v[26:29], v[166:169], v[214:217], v[26:29]
	v_mfma_f32_16x16x32_bf16 v[18:21], v[158:161], v[222:225], v[18:21]
	v_mfma_f32_16x16x32_bf16 v[10:13], v[166:169], v[222:225], v[10:13]
	s_setprio 0
	s_setprio 1
	v_mfma_f32_16x16x32_bf16 v[54:57], v[170:173], v[194:197], v[54:57]
	v_mfma_f32_16x16x32_bf16 v[46:49], v[180:183], v[194:197], v[46:49]
	v_mfma_f32_16x16x32_bf16 v[38:41], v[170:173], v[202:205], v[38:41]
	v_mfma_f32_16x16x32_bf16 v[30:33], v[180:183], v[202:205], v[30:33]
	v_mfma_f32_16x16x32_bf16 v[22:25], v[170:173], v[210:213], v[22:25]
	v_mfma_f32_16x16x32_bf16 v[14:17], v[180:183], v[210:213], v[14:17]
	v_mfma_f32_16x16x32_bf16 v[6:9], v[170:173], v[218:221], v[6:9]
	v_mfma_f32_16x16x32_bf16 v[2:5], v[180:183], v[218:221], v[2:5]
	v_mfma_f32_16x16x32_bf16 v[54:57], v[174:177], v[198:201], v[54:57]
	v_mfma_f32_16x16x32_bf16 v[46:49], v[190:193], v[198:201], v[46:49]
	v_mfma_f32_16x16x32_bf16 v[38:41], v[174:177], v[206:209], v[38:41]
	v_mfma_f32_16x16x32_bf16 v[30:33], v[190:193], v[206:209], v[30:33]
	v_mfma_f32_16x16x32_bf16 v[22:25], v[174:177], v[214:217], v[22:25]
	v_mfma_f32_16x16x32_bf16 v[14:17], v[190:193], v[214:217], v[14:17]
	v_mfma_f32_16x16x32_bf16 v[6:9], v[174:177], v[222:225], v[6:9]
	v_mfma_f32_16x16x32_bf16 v[2:5], v[190:193], v[222:225], v[2:5]
	s_barrier
	s_setprio 0
	s_add_i32 s79, s79, 2
	s_add_u32 s54, s54, 0x100
	s_addc_u32 s55, s55, 0
	s_add_u32 s77, s77, 0x100
	s_addc_u32 s78, s78, 0
	s_cmp_gt_u32 s79, 29
	s_cbranch_scc0 .LBB0_701
	s_and_b64 vcc, exec, s[6:7]
	s_cbranch_vccz .LBB0_704
	s_barrier

.LBB0_724:
	s_ashr_i32 s37, s36, 31
	s_lshl_b64 s[40:41], s[36:37], 20
	s_add_u32 s40, s31, s40
	s_addc_u32 s41, s60, s41
	s_and_b64 s[42:43], s[16:17], exec
	s_cselect_b32 s37, s41, s55
	s_cselect_b32 s76, s40, s54
	s_ashr_i32 s35, s34, 31
	s_lshl_b64 s[42:43], s[34:35], 20
	s_add_u32 s42, s18, s42
	s_addc_u32 s43, s19, s43
	s_and_b64 s[58:59], s[16:17], exec
	s_cselect_b32 s35, s43, s57
	s_cselect_b32 s77, s42, s56
	s_add_u32 s54, s54, 0x80080
	s_addc_u32 s55, s55, 0
	s_add_u32 s78, s56, 0x100
	v_mov_b32_e32 v2, 0
	v_mov_b32_e32 v3, 0
	s_addc_u32 s79, s57, 0
	s_mov_b32 s80, -2
	v_mov_b64_e32 v[4:5], v[2:3]
	v_mov_b64_e32 v[6:7], v[2:3]
	v_mov_b64_e32 v[8:9], v[2:3]
	v_mov_b64_e32 v[10:11], v[2:3]
	v_mov_b64_e32 v[12:13], v[2:3]
	v_mov_b64_e32 v[14:15], v[2:3]
	v_mov_b64_e32 v[16:17], v[2:3]
	v_mov_b64_e32 v[18:19], v[2:3]
	v_mov_b64_e32 v[20:21], v[2:3]
	v_mov_b64_e32 v[22:23], v[2:3]
	v_mov_b64_e32 v[24:25], v[2:3]
	v_mov_b64_e32 v[26:27], v[2:3]
	v_mov_b64_e32 v[28:29], v[2:3]
	v_mov_b64_e32 v[30:31], v[2:3]
	v_mov_b64_e32 v[32:33], v[2:3]
	v_mov_b64_e32 v[34:35], v[2:3]
	v_mov_b64_e32 v[36:37], v[2:3]
	v_mov_b64_e32 v[38:39], v[2:3]
	v_mov_b64_e32 v[40:41], v[2:3]
	v_mov_b64_e32 v[42:43], v[2:3]
	v_mov_b64_e32 v[44:45], v[2:3]
	v_mov_b64_e32 v[46:47], v[2:3]
	v_mov_b64_e32 v[48:49], v[2:3]
	v_mov_b64_e32 v[50:51], v[2:3]
	v_mov_b64_e32 v[52:53], v[2:3]
	v_mov_b64_e32 v[54:55], v[2:3]
	v_mov_b64_e32 v[56:57], v[2:3]
	v_mov_b64_e32 v[58:59], v[2:3]
	v_mov_b64_e32 v[60:61], v[2:3]
	v_mov_b64_e32 v[62:63], v[2:3]
	v_mov_b64_e32 v[64:65], v[2:3]
	v_mov_b64_e32 v[66:67], v[2:3]
	v_mov_b64_e32 v[68:69], v[2:3]
	v_mov_b64_e32 v[70:71], v[2:3]
	v_mov_b64_e32 v[72:73], v[2:3]
	v_mov_b64_e32 v[74:75], v[2:3]
	v_mov_b64_e32 v[76:77], v[2:3]
	v_mov_b64_e32 v[78:79], v[2:3]
	v_mov_b64_e32 v[80:81], v[2:3]
	v_mov_b64_e32 v[82:83], v[2:3]
	v_mov_b64_e32 v[84:85], v[2:3]
	v_mov_b64_e32 v[86:87], v[2:3]
	v_mov_b64_e32 v[88:89], v[2:3]
	v_mov_b64_e32 v[90:91], v[2:3]
	v_mov_b64_e32 v[92:93], v[2:3]
	v_mov_b64_e32 v[94:95], v[2:3]
	v_mov_b64_e32 v[96:97], v[2:3]
	v_mov_b64_e32 v[98:99], v[2:3]
	v_mov_b64_e32 v[100:101], v[2:3]
	v_mov_b64_e32 v[102:103], v[2:3]
	v_mov_b64_e32 v[104:105], v[2:3]
	v_mov_b64_e32 v[106:107], v[2:3]
	v_mov_b64_e32 v[108:109], v[2:3]
	v_mov_b64_e32 v[110:111], v[2:3]
	v_mov_b64_e32 v[112:113], v[2:3]
	v_mov_b64_e32 v[114:115], v[2:3]
	v_mov_b64_e32 v[116:117], v[2:3]
	v_mov_b64_e32 v[118:119], v[2:3]
	v_mov_b64_e32 v[120:121], v[2:3]
	v_mov_b64_e32 v[122:123], v[2:3]
	v_mov_b64_e32 v[124:125], v[2:3]
	v_mov_b64_e32 v[126:127], v[2:3]
	v_mov_b64_e32 v[128:129], v[2:3]
.LBB0_725:
	ds_read_b128 v[142:145], v139
	ds_read_b128 v[146:149], v139 offset:1024
	ds_read_b128 v[158:161], v139 offset:2048
	ds_read_b128 v[162:165], v139 offset:3072
	ds_read_b128 v[166:169], v140
	ds_read_b128 v[170:173], v140 offset:1024
	ds_read_b128 v[174:177], v140 offset:2048
	ds_read_b128 v[180:183], v140 offset:3072
	s_add_u32 s56, s54, 0xfff80080
	s_addc_u32 s57, s55, -1
	s_cmp_eq_u32 s80, 28
	s_cselect_b32 s59, s37, s57
	s_cselect_b32 s58, s76, s56
	s_cselect_b32 s57, s35, s79
	s_cselect_b32 s56, s77, s78
	v_lshl_add_u64 v[134:135], s[54:55], 0, v[130:131]
	s_add_i32 m0, s53, 0xc000
	ds_read_b128 v[184:187], v141
	ds_read_b128 v[188:191], v141 offset:1024
	ds_read_b128 v[192:195], v141 offset:2048
	ds_read_b128 v[196:199], v141 offset:3072
	ds_read_b128 v[200:203], v141 offset:4096
	ds_read_b128 v[204:207], v141 offset:5120
	ds_read_b128 v[208:211], v141 offset:6144
	ds_read_b128 v[212:215], v141 offset:7168
	global_load_lds_dwordx4 v[134:135], off
	v_lshl_add_u64 v[134:135], s[54:55], 0, v[132:133]
	s_add_i32 m0, s53, 0xe000
	s_nop 0
	global_load_lds_dwordx4 v[134:135], off
	s_waitcnt vmcnt(8)
	s_waitcnt lgkmcnt(0)
	s_setprio 1
	s_barrier
	v_mfma_f32_16x16x32_bf16 v[126:129], v[142:145], v[184:187], v[126:129]
	v_mfma_f32_16x16x32_bf16 v[122:125], v[158:161], v[184:187], v[122:125]
	v_mfma_f32_16x16x32_bf16 v[114:117], v[142:145], v[192:195], v[114:117]
	v_mfma_f32_16x16x32_bf16 v[106:109], v[158:161], v[192:195], v[106:109]
	v_mfma_f32_16x16x32_bf16 v[98:101], v[142:145], v[200:203], v[98:101]
	v_mfma_f32_16x16x32_bf16 v[90:93], v[158:161], v[200:203], v[90:93]
	v_mfma_f32_16x16x32_bf16 v[82:85], v[142:145], v[208:211], v[82:85]
	v_mfma_f32_16x16x32_bf16 v[74:77], v[158:161], v[208:211], v[74:77]
	v_mfma_f32_16x16x32_bf16 v[126:129], v[146:149], v[188:191], v[126:129]
	v_mfma_f32_16x16x32_bf16 v[122:125], v[162:165], v[188:191], v[122:125]
	v_mfma_f32_16x16x32_bf16 v[114:117], v[146:149], v[196:199], v[114:117]
	v_mfma_f32_16x16x32_bf16 v[106:109], v[162:165], v[196:199], v[106:109]
	v_mfma_f32_16x16x32_bf16 v[98:101], v[146:149], v[204:207], v[98:101]
	v_mfma_f32_16x16x32_bf16 v[90:93], v[162:165], v[204:207], v[90:93]
	v_mfma_f32_16x16x32_bf16 v[82:85], v[146:149], v[212:215], v[82:85]
	v_mfma_f32_16x16x32_bf16 v[74:77], v[162:165], v[212:215], v[74:77]
	s_setprio 0
	s_setprio 1
	v_mfma_f32_16x16x32_bf16 v[118:121], v[166:169], v[184:187], v[118:121]
	v_mfma_f32_16x16x32_bf16 v[110:113], v[174:177], v[184:187], v[110:113]
	v_mfma_f32_16x16x32_bf16 v[102:105], v[166:169], v[192:195], v[102:105]
	v_mfma_f32_16x16x32_bf16 v[94:97], v[174:177], v[192:195], v[94:97]
	v_mfma_f32_16x16x32_bf16 v[86:89], v[166:169], v[200:203], v[86:89]
	v_mfma_f32_16x16x32_bf16 v[78:81], v[174:177], v[200:203], v[78:81]
	v_mfma_f32_16x16x32_bf16 v[70:73], v[166:169], v[208:211], v[70:73]
	v_mfma_f32_16x16x32_bf16 v[66:69], v[174:177], v[208:211], v[66:69]
	v_mfma_f32_16x16x32_bf16 v[118:121], v[170:173], v[188:191], v[118:121]
	v_mfma_f32_16x16x32_bf16 v[110:113], v[180:183], v[188:191], v[110:113]
	v_mfma_f32_16x16x32_bf16 v[102:105], v[170:173], v[196:199], v[102:105]
	v_mfma_f32_16x16x32_bf16 v[94:97], v[180:183], v[196:199], v[94:97]
	v_mfma_f32_16x16x32_bf16 v[86:89], v[170:173], v[204:207], v[86:89]
	v_mfma_f32_16x16x32_bf16 v[78:81], v[180:183], v[204:207], v[78:81]
	v_mfma_f32_16x16x32_bf16 v[70:73], v[170:173], v[212:215], v[70:73]
	v_mfma_f32_16x16x32_bf16 v[66:69], v[180:183], v[212:215], v[66:69]
	s_barrier
	s_setprio 0
	s_add_i32 s81, s69, s61
	v_lshl_add_u64 v[134:135], s[56:57], 0, v[152:153]
	s_mov_b32 m0, s81
	ds_read_b128 v[184:187], v141 offset:16384
	ds_read_b128 v[188:191], v141 offset:17408
	ds_read_b128 v[192:195], v141 offset:18432
	ds_read_b128 v[196:199], v141 offset:19456
	ds_read_b128 v[200:203], v141 offset:20480
	ds_read_b128 v[204:207], v141 offset:21504
	ds_read_b128 v[208:211], v141 offset:22528
	ds_read_b128 v[212:215], v141 offset:23552
	global_load_lds_dwordx4 v[134:135], off
	s_add_i32 m0, s81, 0x2000
	s_add_u32 s82, s56, 0x80000
	v_lshl_add_u64 v[216:217], s[56:57], 0, v[156:157]
	s_addc_u32 s83, s57, 0
	s_add_i32 s81, s70, s61
	global_load_lds_dwordx4 v[216:217], off
	v_lshl_add_u64 v[218:219], s[82:83], 0, v[152:153]
	s_mov_b32 m0, s81
	v_lshl_add_u64 v[220:221], s[58:59], 0, v[154:155]
	global_load_lds_dwordx4 v[218:219], off
	v_lshl_add_u64 v[218:219], s[82:83], 0, v[156:157]
	s_add_i32 m0, s81, 0x2000
	s_nop 0
	global_load_lds_dwordx4 v[218:219], off
	v_lshl_add_u64 v[218:219], s[58:59], 0, v[150:151]
	s_mov_b32 m0, s53
	s_nop 0
	global_load_lds_dwordx4 v[218:219], off
	s_mov_b32 m0, s62
	s_nop 0
	global_load_lds_dwordx4 v[220:221], off
	s_waitcnt vmcnt(8)
	s_waitcnt lgkmcnt(0)
	s_setprio 1
	s_barrier
	v_mfma_f32_16x16x32_bf16 v[62:65], v[142:145], v[184:187], v[62:65]
	v_mfma_f32_16x16x32_bf16 v[58:61], v[158:161], v[184:187], v[58:61]
	v_mfma_f32_16x16x32_bf16 v[50:53], v[142:145], v[192:195], v[50:53]
	v_mfma_f32_16x16x32_bf16 v[42:45], v[158:161], v[192:195], v[42:45]
	v_mfma_f32_16x16x32_bf16 v[34:37], v[142:145], v[200:203], v[34:37]
	v_mfma_f32_16x16x32_bf16 v[26:29], v[158:161], v[200:203], v[26:29]
	v_mfma_f32_16x16x32_bf16 v[18:21], v[142:145], v[208:211], v[18:21]
	v_mfma_f32_16x16x32_bf16 v[10:13], v[158:161], v[208:211], v[10:13]
	v_mfma_f32_16x16x32_bf16 v[62:65], v[146:149], v[188:191], v[62:65]
	v_mfma_f32_16x16x32_bf16 v[58:61], v[162:165], v[188:191], v[58:61]
	v_mfma_f32_16x16x32_bf16 v[50:53], v[146:149], v[196:199], v[50:53]
	v_mfma_f32_16x16x32_bf16 v[42:45], v[162:165], v[196:199], v[42:45]
	v_mfma_f32_16x16x32_bf16 v[34:37], v[146:149], v[204:207], v[34:37]
	v_mfma_f32_16x16x32_bf16 v[26:29], v[162:165], v[204:207], v[26:29]
	v_mfma_f32_16x16x32_bf16 v[18:21], v[146:149], v[212:215], v[18:21]
	v_mfma_f32_16x16x32_bf16 v[10:13], v[162:165], v[212:215], v[10:13]
	s_setprio 0
	s_setprio 1
	v_mfma_f32_16x16x32_bf16 v[54:57], v[166:169], v[184:187], v[54:57]
	v_mfma_f32_16x16x32_bf16 v[46:49], v[174:177], v[184:187], v[46:49]
	v_mfma_f32_16x16x32_bf16 v[38:41], v[166:169], v[192:195], v[38:41]
	v_mfma_f32_16x16x32_bf16 v[30:33], v[174:177], v[192:195], v[30:33]
	v_mfma_f32_16x16x32_bf16 v[22:25], v[166:169], v[200:203], v[22:25]
	v_mfma_f32_16x16x32_bf16 v[14:17], v[174:177], v[200:203], v[14:17]
	v_mfma_f32_16x16x32_bf16 v[6:9], v[166:169], v[208:211], v[6:9]
	v_mfma_f32_16x16x32_bf16 v[2:5], v[174:177], v[208:211], v[2:5]
	v_mfma_f32_16x16x32_bf16 v[54:57], v[170:173], v[188:191], v[54:57]
	v_mfma_f32_16x16x32_bf16 v[46:49], v[180:183], v[188:191], v[46:49]
	v_mfma_f32_16x16x32_bf16 v[38:41], v[170:173], v[196:199], v[38:41]
	v_mfma_f32_16x16x32_bf16 v[30:33], v[180:183], v[196:199], v[30:33]
	v_mfma_f32_16x16x32_bf16 v[22:25], v[170:173], v[204:207], v[22:25]
	v_mfma_f32_16x16x32_bf16 v[14:17], v[180:183], v[204:207], v[14:17]
	v_mfma_f32_16x16x32_bf16 v[6:9], v[170:173], v[212:215], v[6:9]
	v_mfma_f32_16x16x32_bf16 v[2:5], v[180:183], v[212:215], v[2:5]
	s_barrier
	s_setprio 0
	s_add_i32 s81, 0, 0x18000
	v_add_u32_e32 v1, s81, v136
	s_add_i32 s82, 0, 0x1c000
	ds_read_b128 v[142:145], v1
	ds_read_b128 v[146:149], v1 offset:1024
	ds_read_b128 v[158:161], v1 offset:2048
	ds_read_b128 v[162:165], v1 offset:3072
	v_add_u32_e32 v1, s82, v136
	ds_read_b128 v[166:169], v1
	ds_read_b128 v[170:173], v1 offset:1024
	ds_read_b128 v[174:177], v1 offset:2048
	ds_read_b128 v[180:183], v1 offset:3072
	s_add_u32 s58, s58, 0x80000
	s_addc_u32 s59, s59, 0
	s_mov_b32 m0, s63
	v_lshl_add_u64 v[222:223], s[58:59], 0, v[150:151]
	ds_read_b128 v[184:187], v141 offset:32768
	ds_read_b128 v[188:191], v141 offset:33792
	ds_read_b128 v[192:195], v141 offset:34816
	ds_read_b128 v[196:199], v141 offset:35840
	ds_read_b128 v[200:203], v141 offset:36864
	ds_read_b128 v[204:207], v141 offset:37888
	ds_read_b128 v[208:211], v141 offset:38912
	ds_read_b128 v[212:215], v141 offset:39936
	global_load_lds_dwordx4 v[222:223], off
	v_lshl_add_u64 v[222:223], s[58:59], 0, v[154:155]
	s_mov_b32 m0, s64
	s_nop 0
	global_load_lds_dwordx4 v[222:223], off
	s_waitcnt vmcnt(8)
	s_waitcnt lgkmcnt(0)
	s_setprio 1
	s_barrier
	v_mfma_f32_16x16x32_bf16 v[126:129], v[142:145], v[184:187], v[126:129]
	v_mfma_f32_16x16x32_bf16 v[122:125], v[158:161], v[184:187], v[122:125]
	v_mfma_f32_16x16x32_bf16 v[114:117], v[142:145], v[192:195], v[114:117]
	v_mfma_f32_16x16x32_bf16 v[106:109], v[158:161], v[192:195], v[106:109]
	v_mfma_f32_16x16x32_bf16 v[98:101], v[142:145], v[200:203], v[98:101]
	v_mfma_f32_16x16x32_bf16 v[90:93], v[158:161], v[200:203], v[90:93]
	v_mfma_f32_16x16x32_bf16 v[82:85], v[142:145], v[208:211], v[82:85]
	v_mfma_f32_16x16x32_bf16 v[74:77], v[158:161], v[208:211], v[74:77]
	v_mfma_f32_16x16x32_bf16 v[126:129], v[146:149], v[188:191], v[126:129]
	v_mfma_f32_16x16x32_bf16 v[122:125], v[162:165], v[188:191], v[122:125]
	v_mfma_f32_16x16x32_bf16 v[114:117], v[146:149], v[196:199], v[114:117]
	v_mfma_f32_16x16x32_bf16 v[106:109], v[162:165], v[196:199], v[106:109]
	v_mfma_f32_16x16x32_bf16 v[98:101], v[146:149], v[204:207], v[98:101]
	v_mfma_f32_16x16x32_bf16 v[90:93], v[162:165], v[204:207], v[90:93]
	v_mfma_f32_16x16x32_bf16 v[82:85], v[146:149], v[212:215], v[82:85]
	v_mfma_f32_16x16x32_bf16 v[74:77], v[162:165], v[212:215], v[74:77]
	s_setprio 0
	s_setprio 1
	v_mfma_f32_16x16x32_bf16 v[118:121], v[166:169], v[184:187], v[118:121]
	v_mfma_f32_16x16x32_bf16 v[110:113], v[174:177], v[184:187], v[110:113]
	v_mfma_f32_16x16x32_bf16 v[102:105], v[166:169], v[192:195], v[102:105]
	v_mfma_f32_16x16x32_bf16 v[94:97], v[174:177], v[192:195], v[94:97]
	v_mfma_f32_16x16x32_bf16 v[86:89], v[166:169], v[200:203], v[86:89]
	v_mfma_f32_16x16x32_bf16 v[78:81], v[174:177], v[200:203], v[78:81]
	v_mfma_f32_16x16x32_bf16 v[70:73], v[166:169], v[208:211], v[70:73]
	v_mfma_f32_16x16x32_bf16 v[66:69], v[174:177], v[208:211], v[66:69]
	v_mfma_f32_16x16x32_bf16 v[118:121], v[170:173], v[188:191], v[118:121]
	v_mfma_f32_16x16x32_bf16 v[110:113], v[180:183], v[188:191], v[110:113]
	v_mfma_f32_16x16x32_bf16 v[102:105], v[170:173], v[196:199], v[102:105]
	v_mfma_f32_16x16x32_bf16 v[94:97], v[180:183], v[196:199], v[94:97]
	v_mfma_f32_16x16x32_bf16 v[86:89], v[170:173], v[204:207], v[86:89]
	v_mfma_f32_16x16x32_bf16 v[78:81], v[180:183], v[204:207], v[78:81]
	v_mfma_f32_16x16x32_bf16 v[70:73], v[170:173], v[212:215], v[70:73]
	v_mfma_f32_16x16x32_bf16 v[66:69], v[180:183], v[212:215], v[66:69]
	s_barrier
	s_setprio 0
	s_add_i32 s58, s81, s61
	v_lshl_add_u64 v[134:135], v[134:135], 0, s[4:5]
	s_mov_b32 m0, s58
	ds_read_b128 v[184:187], v141 offset:49152
	ds_read_b128 v[188:191], v141 offset:50176
	ds_read_b128 v[192:195], v141 offset:51200
	ds_read_b128 v[196:199], v141 offset:52224
	ds_read_b128 v[200:203], v141 offset:53248
	ds_read_b128 v[204:207], v141 offset:54272
	ds_read_b128 v[208:211], v141 offset:55296
	ds_read_b128 v[212:215], v141 offset:56320
	global_load_lds_dwordx4 v[134:135], off
	s_add_i32 m0, s58, 0x2000
	s_add_u32 s56, s56, 0x80080
	v_lshl_add_u64 v[134:135], v[216:217], 0, s[4:5]
	s_addc_u32 s57, s57, 0
	s_add_i32 s58, s82, s61
	global_load_lds_dwordx4 v[134:135], off
	v_lshl_add_u64 v[134:135], s[56:57], 0, v[152:153]
	s_mov_b32 m0, s58
	s_nop 0
	global_load_lds_dwordx4 v[134:135], off
	v_lshl_add_u64 v[134:135], s[56:57], 0, v[156:157]
	s_add_i32 m0, s58, 0x2000
	s_nop 0
	global_load_lds_dwordx4 v[134:135], off
	v_lshl_add_u64 v[134:135], v[218:219], 0, s[4:5]
	s_mov_b32 m0, s66
	s_nop 0
	global_load_lds_dwordx4 v[134:135], off
	v_lshl_add_u64 v[134:135], v[220:221], 0, s[4:5]
	s_mov_b32 m0, s67
	s_nop 0
	global_load_lds_dwordx4 v[134:135], off
	s_waitcnt vmcnt(8)
	s_waitcnt lgkmcnt(0)
	s_setprio 1
	s_barrier
	v_mfma_f32_16x16x32_bf16 v[62:65], v[142:145], v[184:187], v[62:65]
	v_mfma_f32_16x16x32_bf16 v[58:61], v[158:161], v[184:187], v[58:61]
	v_mfma_f32_16x16x32_bf16 v[50:53], v[142:145], v[192:195], v[50:53]
	v_mfma_f32_16x16x32_bf16 v[42:45], v[158:161], v[192:195], v[42:45]
	v_mfma_f32_16x16x32_bf16 v[34:37], v[142:145], v[200:203], v[34:37]
	v_mfma_f32_16x16x32_bf16 v[26:29], v[158:161], v[200:203], v[26:29]
	v_mfma_f32_16x16x32_bf16 v[18:21], v[142:145], v[208:211], v[18:21]
	v_mfma_f32_16x16x32_bf16 v[10:13], v[158:161], v[208:211], v[10:13]
	v_mfma_f32_16x16x32_bf16 v[62:65], v[146:149], v[188:191], v[62:65]
	v_mfma_f32_16x16x32_bf16 v[58:61], v[162:165], v[188:191], v[58:61]
	v_mfma_f32_16x16x32_bf16 v[50:53], v[146:149], v[196:199], v[50:53]
	v_mfma_f32_16x16x32_bf16 v[42:45], v[162:165], v[196:199], v[42:45]
	v_mfma_f32_16x16x32_bf16 v[34:37], v[146:149], v[204:207], v[34:37]
	v_mfma_f32_16x16x32_bf16 v[26:29], v[162:165], v[204:207], v[26:29]
	v_mfma_f32_16x16x32_bf16 v[18:21], v[146:149], v[212:215], v[18:21]
	v_mfma_f32_16x16x32_bf16 v[10:13], v[162:165], v[212:215], v[10:13]
	s_setprio 0
	s_setprio 1
	v_mfma_f32_16x16x32_bf16 v[54:57], v[166:169], v[184:187], v[54:57]
	v_mfma_f32_16x16x32_bf16 v[46:49], v[174:177], v[184:187], v[46:49]
	v_mfma_f32_16x16x32_bf16 v[38:41], v[166:169], v[192:195], v[38:41]
	v_mfma_f32_16x16x32_bf16 v[30:33], v[174:177], v[192:195], v[30:33]
	v_mfma_f32_16x16x32_bf16 v[22:25], v[166:169], v[200:203], v[22:25]
	v_mfma_f32_16x16x32_bf16 v[14:17], v[174:177], v[200:203], v[14:17]
	v_mfma_f32_16x16x32_bf16 v[6:9], v[166:169], v[208:211], v[6:9]
	v_mfma_f32_16x16x32_bf16 v[2:5], v[174:177], v[208:211], v[2:5]
	v_mfma_f32_16x16x32_bf16 v[54:57], v[170:173], v[188:191], v[54:57]
	v_mfma_f32_16x16x32_bf16 v[46:49], v[180:183], v[188:191], v[46:49]
	v_mfma_f32_16x16x32_bf16 v[38:41], v[170:173], v[196:199], v[38:41]
	v_mfma_f32_16x16x32_bf16 v[30:33], v[180:183], v[196:199], v[30:33]
	v_mfma_f32_16x16x32_bf16 v[22:25], v[170:173], v[204:207], v[22:25]
	v_mfma_f32_16x16x32_bf16 v[14:17], v[180:183], v[204:207], v[14:17]
	v_mfma_f32_16x16x32_bf16 v[6:9], v[170:173], v[212:215], v[6:9]
	v_mfma_f32_16x16x32_bf16 v[2:5], v[180:183], v[212:215], v[2:5]
	s_barrier
	s_setprio 0
	s_add_i32 s80, s80, 2
	s_add_u32 s54, s54, 0x100
	s_addc_u32 s55, s55, 0
	s_add_u32 s78, s78, 0x100
	s_addc_u32 s79, s79, 0
	s_cmp_gt_u32 s80, 29
	s_cbranch_scc0 .LBB0_725
	s_and_b64 vcc, exec, s[6:7]
	s_cbranch_vccz .LBB0_728
	s_barrier

.LBB0_1328:
	v_add_u32_e32 v1, s58, v197
	s_add_u32 s40, s36, s38
	ds_read_b128 v[134:137], v1
	ds_read_b128 v[138:141], v1 offset:1024
	ds_read_b128 v[142:145], v1 offset:2048
	ds_read_b128 v[146:149], v1 offset:3072
	v_add_u32_e32 v1, s59, v197
	s_addc_u32 s41, s37, s39
	ds_read_b128 v[150:153], v1
	ds_read_b128 v[154:157], v1 offset:1024
	ds_read_b128 v[158:161], v1 offset:2048
	ds_read_b128 v[162:165], v1 offset:3072
	s_add_u32 s40, s40, 0x100
	s_addc_u32 s41, s41, 0
	s_add_u32 s69, s66, s38
	s_addc_u32 s70, s67, s39
	s_cmpk_eq_i32 s38, 0xf00
	s_cselect_b32 s42, s60, s40
	s_cselect_b32 s40, s63, s69
	s_cselect_b32 s43, s17, s41
	s_cselect_b32 s41, s62, s70
	v_lshl_add_u64 v[4:5], v[190:191], 0, s[38:39]
	s_add_i32 m0, s29, 0xc000
	ds_read_b128 v[166:169], v199
	ds_read_b128 v[170:173], v199 offset:1024
	ds_read_b128 v[200:203], v199 offset:2048
	ds_read_b128 v[204:207], v199 offset:3072
	ds_read_b128 v[208:211], v199 offset:4096
	ds_read_b128 v[212:215], v199 offset:5120
	ds_read_b128 v[216:219], v199 offset:6144
	ds_read_b128 v[220:223], v199 offset:7168
	global_load_lds_dwordx4 v[4:5], off
	v_lshl_add_u64 v[4:5], v[192:193], 0, s[38:39]
	s_add_i32 m0, s29, 0xe000
	s_nop 0
	global_load_lds_dwordx4 v[4:5], off
	s_waitcnt vmcnt(8)
	s_waitcnt lgkmcnt(0)
	s_setprio 1
	s_barrier
	v_mfma_f32_16x16x32_bf16 v[130:133], v[134:137], v[166:169], v[130:133]
	v_mfma_f32_16x16x32_bf16 v[126:129], v[142:145], v[166:169], v[126:129]
	v_mfma_f32_16x16x32_bf16 v[114:117], v[134:137], v[200:203], v[114:117]
	v_mfma_f32_16x16x32_bf16 v[110:113], v[142:145], v[200:203], v[110:113]
	v_mfma_f32_16x16x32_bf16 v[98:101], v[134:137], v[208:211], v[98:101]
	v_mfma_f32_16x16x32_bf16 v[94:97], v[142:145], v[208:211], v[94:97]
	v_mfma_f32_16x16x32_bf16 v[82:85], v[134:137], v[216:219], v[82:85]
	v_mfma_f32_16x16x32_bf16 v[78:81], v[142:145], v[216:219], v[78:81]
	v_mfma_f32_16x16x32_bf16 v[130:133], v[138:141], v[170:173], v[130:133]
	v_mfma_f32_16x16x32_bf16 v[126:129], v[146:149], v[170:173], v[126:129]
	v_mfma_f32_16x16x32_bf16 v[114:117], v[138:141], v[204:207], v[114:117]
	v_mfma_f32_16x16x32_bf16 v[110:113], v[146:149], v[204:207], v[110:113]
	v_mfma_f32_16x16x32_bf16 v[98:101], v[138:141], v[212:215], v[98:101]
	v_mfma_f32_16x16x32_bf16 v[94:97], v[146:149], v[212:215], v[94:97]
	v_mfma_f32_16x16x32_bf16 v[82:85], v[138:141], v[220:223], v[82:85]
	v_mfma_f32_16x16x32_bf16 v[78:81], v[146:149], v[220:223], v[78:81]
	s_setprio 0
	s_setprio 1
	v_mfma_f32_16x16x32_bf16 v[122:125], v[150:153], v[166:169], v[122:125]
	v_mfma_f32_16x16x32_bf16 v[118:121], v[158:161], v[166:169], v[118:121]
	v_mfma_f32_16x16x32_bf16 v[106:109], v[150:153], v[200:203], v[106:109]
	v_mfma_f32_16x16x32_bf16 v[102:105], v[158:161], v[200:203], v[102:105]
	v_mfma_f32_16x16x32_bf16 v[90:93], v[150:153], v[208:211], v[90:93]
	v_mfma_f32_16x16x32_bf16 v[86:89], v[158:161], v[208:211], v[86:89]
	v_mfma_f32_16x16x32_bf16 v[74:77], v[150:153], v[216:219], v[74:77]
	v_mfma_f32_16x16x32_bf16 v[70:73], v[158:161], v[216:219], v[70:73]
	v_mfma_f32_16x16x32_bf16 v[122:125], v[154:157], v[170:173], v[122:125]
	v_mfma_f32_16x16x32_bf16 v[118:121], v[162:165], v[170:173], v[118:121]
	v_mfma_f32_16x16x32_bf16 v[106:109], v[154:157], v[204:207], v[106:109]
	v_mfma_f32_16x16x32_bf16 v[102:105], v[162:165], v[204:207], v[102:105]
	v_mfma_f32_16x16x32_bf16 v[90:93], v[154:157], v[212:215], v[90:93]
	v_mfma_f32_16x16x32_bf16 v[86:89], v[162:165], v[212:215], v[86:89]
	v_mfma_f32_16x16x32_bf16 v[74:77], v[154:157], v[220:223], v[74:77]
	v_mfma_f32_16x16x32_bf16 v[70:73], v[162:165], v[220:223], v[70:73]
	s_barrier
	s_setprio 0
	s_add_i32 s69, s58, s28
	v_lshl_add_u64 v[224:225], s[40:41], 0, v[176:177]
	s_mov_b32 m0, s69
	ds_read_b128 v[166:169], v199 offset:16384
	ds_read_b128 v[170:173], v199 offset:17408
	ds_read_b128 v[200:203], v199 offset:18432
	ds_read_b128 v[204:207], v199 offset:19456
	ds_read_b128 v[208:211], v199 offset:20480
	ds_read_b128 v[212:215], v199 offset:21504
	ds_read_b128 v[216:219], v199 offset:22528
	ds_read_b128 v[220:223], v199 offset:23552
	global_load_lds_dwordx4 v[224:225], off
	s_add_i32 m0, s69, 0x2000
	s_add_u32 s70, s40, 0x80000
	v_lshl_add_u64 v[226:227], s[40:41], 0, v[180:181]
	s_addc_u32 s71, s41, 0
	s_add_i32 s69, s59, s28
	global_load_lds_dwordx4 v[226:227], off
	v_lshl_add_u64 v[4:5], s[70:71], 0, v[176:177]
	s_mov_b32 m0, s69
	v_lshl_add_u64 v[228:229], s[42:43], 0, v[174:175]
	global_load_lds_dwordx4 v[4:5], off
	v_lshl_add_u64 v[4:5], s[70:71], 0, v[180:181]
	s_add_i32 m0, s69, 0x2000
	v_lshl_add_u64 v[230:231], s[42:43], 0, v[178:179]
	global_load_lds_dwordx4 v[4:5], off
	s_mov_b32 m0, s29
	s_nop 0
	global_load_lds_dwordx4 v[228:229], off
	s_mov_b32 m0, s44
	s_nop 0
	global_load_lds_dwordx4 v[230:231], off
	s_waitcnt vmcnt(8)
	s_waitcnt lgkmcnt(0)
	s_setprio 1
	s_barrier
	v_mfma_f32_16x16x32_bf16 v[66:69], v[134:137], v[166:169], v[66:69]
	v_mfma_f32_16x16x32_bf16 v[62:65], v[142:145], v[166:169], v[62:65]
	v_mfma_f32_16x16x32_bf16 v[50:53], v[134:137], v[200:203], v[50:53]
	v_mfma_f32_16x16x32_bf16 v[46:49], v[142:145], v[200:203], v[46:49]
	v_mfma_f32_16x16x32_bf16 v[34:37], v[134:137], v[208:211], v[34:37]
	v_mfma_f32_16x16x32_bf16 v[30:33], v[142:145], v[208:211], v[30:33]
	v_mfma_f32_16x16x32_bf16 v[18:21], v[134:137], v[216:219], v[18:21]
	v_mfma_f32_16x16x32_bf16 v[14:17], v[142:145], v[216:219], v[14:17]
	v_mfma_f32_16x16x32_bf16 v[66:69], v[138:141], v[170:173], v[66:69]
	v_mfma_f32_16x16x32_bf16 v[62:65], v[146:149], v[170:173], v[62:65]
	v_mfma_f32_16x16x32_bf16 v[50:53], v[138:141], v[204:207], v[50:53]
	v_mfma_f32_16x16x32_bf16 v[46:49], v[146:149], v[204:207], v[46:49]
	v_mfma_f32_16x16x32_bf16 v[34:37], v[138:141], v[212:215], v[34:37]
	v_mfma_f32_16x16x32_bf16 v[30:33], v[146:149], v[212:215], v[30:33]
	v_mfma_f32_16x16x32_bf16 v[18:21], v[138:141], v[220:223], v[18:21]
	v_mfma_f32_16x16x32_bf16 v[14:17], v[146:149], v[220:223], v[14:17]
	s_setprio 0
	s_setprio 1
	v_mfma_f32_16x16x32_bf16 v[58:61], v[150:153], v[166:169], v[58:61]
	v_mfma_f32_16x16x32_bf16 v[54:57], v[158:161], v[166:169], v[54:57]
	v_mfma_f32_16x16x32_bf16 v[42:45], v[150:153], v[200:203], v[42:45]
	v_mfma_f32_16x16x32_bf16 v[38:41], v[158:161], v[200:203], v[38:41]
	v_mfma_f32_16x16x32_bf16 v[26:29], v[150:153], v[208:211], v[26:29]
	v_mfma_f32_16x16x32_bf16 v[22:25], v[158:161], v[208:211], v[22:25]
	v_mfma_f32_16x16x32_bf16 v[10:13], v[150:153], v[216:219], v[10:13]
	v_mfma_f32_16x16x32_bf16 v[4:7], v[158:161], v[216:219], v[6:9]
	v_mfma_f32_16x16x32_bf16 v[58:61], v[154:157], v[170:173], v[58:61]
	v_mfma_f32_16x16x32_bf16 v[54:57], v[162:165], v[170:173], v[54:57]
	v_mfma_f32_16x16x32_bf16 v[42:45], v[154:157], v[204:207], v[42:45]
	v_mfma_f32_16x16x32_bf16 v[38:41], v[162:165], v[204:207], v[38:41]
	v_mfma_f32_16x16x32_bf16 v[26:29], v[154:157], v[212:215], v[26:29]
	v_mfma_f32_16x16x32_bf16 v[22:25], v[162:165], v[212:215], v[22:25]
	v_mfma_f32_16x16x32_bf16 v[10:13], v[154:157], v[220:223], v[10:13]
	v_mfma_f32_16x16x32_bf16 v[4:7], v[162:165], v[220:223], v[4:7]
	s_barrier
	s_setprio 0
	s_add_i32 s69, 0, 0x18000
	v_add_u32_e32 v1, s69, v197
	s_add_i32 s70, 0, 0x1c000
	ds_read_b128 v[134:137], v1
	ds_read_b128 v[138:141], v1 offset:1024
	ds_read_b128 v[142:145], v1 offset:2048
	ds_read_b128 v[146:149], v1 offset:3072
	v_add_u32_e32 v1, s70, v197
	ds_read_b128 v[150:153], v1
	ds_read_b128 v[154:157], v1 offset:1024
	ds_read_b128 v[158:161], v1 offset:2048
	ds_read_b128 v[162:165], v1 offset:3072
	s_add_u32 s42, s42, 0x80000
	s_addc_u32 s43, s43, 0
	s_mov_b32 m0, s45
	v_lshl_add_u64 v[8:9], s[42:43], 0, v[174:175]
	ds_read_b128 v[166:169], v199 offset:32768
	ds_read_b128 v[170:173], v199 offset:33792
	ds_read_b128 v[200:203], v199 offset:34816
	ds_read_b128 v[204:207], v199 offset:35840
	ds_read_b128 v[208:211], v199 offset:36864
	ds_read_b128 v[212:215], v199 offset:37888
	ds_read_b128 v[216:219], v199 offset:38912
	ds_read_b128 v[220:223], v199 offset:39936
	global_load_lds_dwordx4 v[8:9], off
	v_lshl_add_u64 v[8:9], s[42:43], 0, v[178:179]
	s_mov_b32 m0, s46
	s_nop 0
	global_load_lds_dwordx4 v[8:9], off
	s_waitcnt vmcnt(8)
	s_waitcnt lgkmcnt(0)
	s_setprio 1
	s_barrier
	v_mfma_f32_16x16x32_bf16 v[130:133], v[134:137], v[166:169], v[130:133]
	v_mfma_f32_16x16x32_bf16 v[126:129], v[142:145], v[166:169], v[126:129]
	v_mfma_f32_16x16x32_bf16 v[114:117], v[134:137], v[200:203], v[114:117]
	v_mfma_f32_16x16x32_bf16 v[110:113], v[142:145], v[200:203], v[110:113]
	v_mfma_f32_16x16x32_bf16 v[98:101], v[134:137], v[208:211], v[98:101]
	v_mfma_f32_16x16x32_bf16 v[94:97], v[142:145], v[208:211], v[94:97]
	v_mfma_f32_16x16x32_bf16 v[82:85], v[134:137], v[216:219], v[82:85]
	v_mfma_f32_16x16x32_bf16 v[78:81], v[142:145], v[216:219], v[78:81]
	v_mfma_f32_16x16x32_bf16 v[130:133], v[138:141], v[170:173], v[130:133]
	v_mfma_f32_16x16x32_bf16 v[126:129], v[146:149], v[170:173], v[126:129]
	v_mfma_f32_16x16x32_bf16 v[114:117], v[138:141], v[204:207], v[114:117]
	v_mfma_f32_16x16x32_bf16 v[110:113], v[146:149], v[204:207], v[110:113]
	v_mfma_f32_16x16x32_bf16 v[98:101], v[138:141], v[212:215], v[98:101]
	v_mfma_f32_16x16x32_bf16 v[94:97], v[146:149], v[212:215], v[94:97]
	v_mfma_f32_16x16x32_bf16 v[82:85], v[138:141], v[220:223], v[82:85]
	v_mfma_f32_16x16x32_bf16 v[78:81], v[146:149], v[220:223], v[78:81]
	s_setprio 0
	s_setprio 1
	v_mfma_f32_16x16x32_bf16 v[122:125], v[150:153], v[166:169], v[122:125]
	v_mfma_f32_16x16x32_bf16 v[118:121], v[158:161], v[166:169], v[118:121]
	v_mfma_f32_16x16x32_bf16 v[106:109], v[150:153], v[200:203], v[106:109]
	v_mfma_f32_16x16x32_bf16 v[102:105], v[158:161], v[200:203], v[102:105]
	v_mfma_f32_16x16x32_bf16 v[90:93], v[150:153], v[208:211], v[90:93]
	v_mfma_f32_16x16x32_bf16 v[86:89], v[158:161], v[208:211], v[86:89]
	v_mfma_f32_16x16x32_bf16 v[74:77], v[150:153], v[216:219], v[74:77]
	v_mfma_f32_16x16x32_bf16 v[70:73], v[158:161], v[216:219], v[70:73]
	v_mfma_f32_16x16x32_bf16 v[122:125], v[154:157], v[170:173], v[122:125]
	v_mfma_f32_16x16x32_bf16 v[118:121], v[162:165], v[170:173], v[118:121]
	v_mfma_f32_16x16x32_bf16 v[106:109], v[154:157], v[204:207], v[106:109]
	v_mfma_f32_16x16x32_bf16 v[102:105], v[162:165], v[204:207], v[102:105]
	v_mfma_f32_16x16x32_bf16 v[90:93], v[154:157], v[212:215], v[90:93]
	v_mfma_f32_16x16x32_bf16 v[86:89], v[162:165], v[212:215], v[86:89]
	v_mfma_f32_16x16x32_bf16 v[74:77], v[154:157], v[220:223], v[74:77]
	v_mfma_f32_16x16x32_bf16 v[70:73], v[162:165], v[220:223], v[70:73]
	s_barrier
	s_setprio 0
	s_add_i32 s42, s69, s28
	v_lshl_add_u64 v[8:9], v[224:225], 0, s[8:9]
	s_mov_b32 m0, s42
	ds_read_b128 v[166:169], v199 offset:49152
	ds_read_b128 v[170:173], v199 offset:50176
	ds_read_b128 v[200:203], v199 offset:51200
	ds_read_b128 v[204:207], v199 offset:52224
	ds_read_b128 v[208:211], v199 offset:53248
	ds_read_b128 v[212:215], v199 offset:54272
	ds_read_b128 v[216:219], v199 offset:55296
	ds_read_b128 v[220:223], v199 offset:56320
	global_load_lds_dwordx4 v[8:9], off
	s_add_i32 m0, s42, 0x2000
	s_add_u32 s40, s40, 0x80080
	v_lshl_add_u64 v[8:9], v[226:227], 0, s[8:9]
	s_addc_u32 s41, s41, 0
	s_add_i32 s42, s70, s28
	global_load_lds_dwordx4 v[8:9], off
	v_lshl_add_u64 v[8:9], s[40:41], 0, v[176:177]
	s_mov_b32 m0, s42
	s_nop 0
	global_load_lds_dwordx4 v[8:9], off
	v_lshl_add_u64 v[8:9], s[40:41], 0, v[180:181]
	s_add_i32 m0, s42, 0x2000
	s_nop 0
	global_load_lds_dwordx4 v[8:9], off
	v_lshl_add_u64 v[8:9], v[228:229], 0, s[8:9]
	s_mov_b32 m0, s53
	s_nop 0
	global_load_lds_dwordx4 v[8:9], off
	v_lshl_add_u64 v[8:9], v[230:231], 0, s[8:9]
	s_mov_b32 m0, s54
	s_nop 0
	global_load_lds_dwordx4 v[8:9], off
	s_waitcnt vmcnt(8)
	s_waitcnt lgkmcnt(0)
	s_setprio 1
	s_barrier
	v_mfma_f32_16x16x32_bf16 v[66:69], v[134:137], v[166:169], v[66:69]
	v_mfma_f32_16x16x32_bf16 v[62:65], v[142:145], v[166:169], v[62:65]
	v_mfma_f32_16x16x32_bf16 v[50:53], v[134:137], v[200:203], v[50:53]
	v_mfma_f32_16x16x32_bf16 v[46:49], v[142:145], v[200:203], v[46:49]
	v_mfma_f32_16x16x32_bf16 v[34:37], v[134:137], v[208:211], v[34:37]
	v_mfma_f32_16x16x32_bf16 v[30:33], v[142:145], v[208:211], v[30:33]
	v_mfma_f32_16x16x32_bf16 v[18:21], v[134:137], v[216:219], v[18:21]
	v_mfma_f32_16x16x32_bf16 v[14:17], v[142:145], v[216:219], v[14:17]
	v_mfma_f32_16x16x32_bf16 v[66:69], v[138:141], v[170:173], v[66:69]
	v_mfma_f32_16x16x32_bf16 v[62:65], v[146:149], v[170:173], v[62:65]
	v_mfma_f32_16x16x32_bf16 v[50:53], v[138:141], v[204:207], v[50:53]
	v_mfma_f32_16x16x32_bf16 v[46:49], v[146:149], v[204:207], v[46:49]
	v_mfma_f32_16x16x32_bf16 v[34:37], v[138:141], v[212:215], v[34:37]
	v_mfma_f32_16x16x32_bf16 v[30:33], v[146:149], v[212:215], v[30:33]
	v_mfma_f32_16x16x32_bf16 v[18:21], v[138:141], v[220:223], v[18:21]
	v_mfma_f32_16x16x32_bf16 v[14:17], v[146:149], v[220:223], v[14:17]
	s_setprio 0
	s_setprio 1
	v_mfma_f32_16x16x32_bf16 v[58:61], v[150:153], v[166:169], v[58:61]
	v_mfma_f32_16x16x32_bf16 v[54:57], v[158:161], v[166:169], v[54:57]
	v_mfma_f32_16x16x32_bf16 v[42:45], v[150:153], v[200:203], v[42:45]
	v_mfma_f32_16x16x32_bf16 v[38:41], v[158:161], v[200:203], v[38:41]
	v_mfma_f32_16x16x32_bf16 v[26:29], v[150:153], v[208:211], v[26:29]
	v_mfma_f32_16x16x32_bf16 v[22:25], v[158:161], v[208:211], v[22:25]
	v_mfma_f32_16x16x32_bf16 v[8:11], v[150:153], v[216:219], v[10:13]
	v_mfma_f32_16x16x32_bf16 v[4:7], v[158:161], v[216:219], v[4:7]
	v_mfma_f32_16x16x32_bf16 v[58:61], v[154:157], v[170:173], v[58:61]
	v_mfma_f32_16x16x32_bf16 v[54:57], v[162:165], v[170:173], v[54:57]
	v_mfma_f32_16x16x32_bf16 v[42:45], v[154:157], v[204:207], v[42:45]
	v_mfma_f32_16x16x32_bf16 v[38:41], v[162:165], v[204:207], v[38:41]
	v_mfma_f32_16x16x32_bf16 v[26:29], v[154:157], v[212:215], v[26:29]
	v_mfma_f32_16x16x32_bf16 v[22:25], v[162:165], v[212:215], v[22:25]
	v_mfma_f32_16x16x32_bf16 v[10:13], v[154:157], v[220:223], v[8:11]
	v_mfma_f32_16x16x32_bf16 v[6:9], v[162:165], v[220:223], v[4:7]
	s_barrier
	s_setprio 0
	s_add_i32 s40, s68, 2
	s_add_u32 s38, s38, 0x100
	s_addc_u32 s39, s39, 0
	s_cmp_gt_u32 s68, 29
	s_cbranch_scc1 .LBB0_1330
	s_mov_b32 s68, s40
	s_and_b32 s40, s68, 14
	s_cmp_eq_u32 s40, 8
	s_mov_b64 s[40:41], -1
	s_cbranch_scc0 .LBB0_1325
	s_branch .LBB0_1326

.LBB0_1407:
	s_ashr_i32 s39, s38, 31
	s_lshl_b64 s[40:41], s[38:39], 20
	s_add_u32 s40, s22, s40
	s_addc_u32 s41, s23, s41
	s_and_b64 s[42:43], s[10:11], exec
	s_cselect_b32 s39, s41, s47
	s_cselect_b32 s66, s40, s46
	s_ashr_i32 s37, s36, 31
	s_lshl_b64 s[42:43], s[36:37], 20
	s_add_u32 s42, s28, s42
	s_addc_u32 s43, s29, s43
	s_and_b64 s[52:53], s[10:11], exec
	s_cselect_b32 s37, s43, s49
	s_cselect_b32 s67, s42, s48
	s_add_u32 s46, s46, 0x80080
	s_addc_u32 s47, s47, 0
	s_add_u32 s68, s48, 0x100
	v_mov_b32_e32 v2, 0
	v_mov_b32_e32 v3, 0
	s_addc_u32 s69, s49, 0
	s_mov_b32 s70, -2
	v_mov_b64_e32 v[4:5], v[2:3]
	v_mov_b64_e32 v[6:7], v[2:3]
	v_mov_b64_e32 v[8:9], v[2:3]
	v_mov_b64_e32 v[10:11], v[2:3]
	v_mov_b64_e32 v[12:13], v[2:3]
	v_mov_b64_e32 v[14:15], v[2:3]
	v_mov_b64_e32 v[16:17], v[2:3]
	v_mov_b64_e32 v[18:19], v[2:3]
	v_mov_b64_e32 v[20:21], v[2:3]
	v_mov_b64_e32 v[22:23], v[2:3]
	v_mov_b64_e32 v[24:25], v[2:3]
	v_mov_b64_e32 v[26:27], v[2:3]
	v_mov_b64_e32 v[28:29], v[2:3]
	v_mov_b64_e32 v[30:31], v[2:3]
	v_mov_b64_e32 v[32:33], v[2:3]
	v_mov_b64_e32 v[34:35], v[2:3]
	v_mov_b64_e32 v[36:37], v[2:3]
	v_mov_b64_e32 v[38:39], v[2:3]
	v_mov_b64_e32 v[40:41], v[2:3]
	v_mov_b64_e32 v[42:43], v[2:3]
	v_mov_b64_e32 v[44:45], v[2:3]
	v_mov_b64_e32 v[46:47], v[2:3]
	v_mov_b64_e32 v[48:49], v[2:3]
	v_mov_b64_e32 v[50:51], v[2:3]
	v_mov_b64_e32 v[52:53], v[2:3]
	v_mov_b64_e32 v[54:55], v[2:3]
	v_mov_b64_e32 v[56:57], v[2:3]
	v_mov_b64_e32 v[58:59], v[2:3]
	v_mov_b64_e32 v[60:61], v[2:3]
	v_mov_b64_e32 v[62:63], v[2:3]
	v_mov_b64_e32 v[64:65], v[2:3]
	v_mov_b64_e32 v[66:67], v[2:3]
	v_mov_b64_e32 v[68:69], v[2:3]
	v_mov_b64_e32 v[70:71], v[2:3]
	v_mov_b64_e32 v[72:73], v[2:3]
	v_mov_b64_e32 v[74:75], v[2:3]
	v_mov_b64_e32 v[76:77], v[2:3]
	v_mov_b64_e32 v[78:79], v[2:3]
	v_mov_b64_e32 v[80:81], v[2:3]
	v_mov_b64_e32 v[82:83], v[2:3]
	v_mov_b64_e32 v[84:85], v[2:3]
	v_mov_b64_e32 v[86:87], v[2:3]
	v_mov_b64_e32 v[88:89], v[2:3]
	v_mov_b64_e32 v[90:91], v[2:3]
	v_mov_b64_e32 v[92:93], v[2:3]
	v_mov_b64_e32 v[94:95], v[2:3]
	v_mov_b64_e32 v[96:97], v[2:3]
	v_mov_b64_e32 v[98:99], v[2:3]
	v_mov_b64_e32 v[100:101], v[2:3]
	v_mov_b64_e32 v[102:103], v[2:3]
	v_mov_b64_e32 v[104:105], v[2:3]
	v_mov_b64_e32 v[106:107], v[2:3]
	v_mov_b64_e32 v[108:109], v[2:3]
	v_mov_b64_e32 v[110:111], v[2:3]
	v_mov_b64_e32 v[112:113], v[2:3]
	v_mov_b64_e32 v[114:115], v[2:3]
	v_mov_b64_e32 v[116:117], v[2:3]
	v_mov_b64_e32 v[118:119], v[2:3]
	v_mov_b64_e32 v[120:121], v[2:3]
	v_mov_b64_e32 v[122:123], v[2:3]
	v_mov_b64_e32 v[124:125], v[2:3]
	v_mov_b64_e32 v[126:127], v[2:3]
	v_mov_b64_e32 v[128:129], v[2:3]
.LBB0_1408:
	ds_read_b128 v[130:133], v183
	ds_read_b128 v[134:137], v183 offset:1024
	ds_read_b128 v[138:141], v183 offset:2048
	ds_read_b128 v[142:145], v183 offset:3072
	ds_read_b128 v[162:165], v184
	ds_read_b128 v[166:169], v184 offset:1024
	ds_read_b128 v[170:173], v184 offset:2048
	ds_read_b128 v[174:177], v184 offset:3072
	s_add_u32 s48, s46, 0xfff80080
	s_addc_u32 s49, s47, -1
	s_cmp_eq_u32 s70, 28
	s_cselect_b32 s53, s39, s49
	s_cselect_b32 s52, s66, s48
	s_cselect_b32 s49, s37, s69
	s_cselect_b32 s48, s67, s68
	v_lshl_add_u64 v[178:179], s[46:47], 0, v[154:155]
	s_add_i32 m0, s45, 0xc000
	ds_read_b128 v[188:191], v185
	ds_read_b128 v[192:195], v185 offset:1024
	ds_read_b128 v[196:199], v185 offset:2048
	ds_read_b128 v[200:203], v185 offset:3072
	ds_read_b128 v[204:207], v185 offset:4096
	ds_read_b128 v[208:211], v185 offset:5120
	ds_read_b128 v[212:215], v185 offset:6144
	ds_read_b128 v[216:219], v185 offset:7168
	global_load_lds_dwordx4 v[178:179], off
	v_lshl_add_u64 v[178:179], s[46:47], 0, v[156:157]
	s_add_i32 m0, s45, 0xe000
	s_nop 0
	global_load_lds_dwordx4 v[178:179], off
	s_waitcnt vmcnt(8)
	s_waitcnt lgkmcnt(0)
	s_setprio 1
	s_barrier
	v_mfma_f32_16x16x32_bf16 v[126:129], v[130:133], v[188:191], v[126:129]
	v_mfma_f32_16x16x32_bf16 v[122:125], v[138:141], v[188:191], v[122:125]
	v_mfma_f32_16x16x32_bf16 v[110:113], v[130:133], v[196:199], v[110:113]
	v_mfma_f32_16x16x32_bf16 v[106:109], v[138:141], v[196:199], v[106:109]
	v_mfma_f32_16x16x32_bf16 v[94:97], v[130:133], v[204:207], v[94:97]
	v_mfma_f32_16x16x32_bf16 v[90:93], v[138:141], v[204:207], v[90:93]
	v_mfma_f32_16x16x32_bf16 v[78:81], v[130:133], v[212:215], v[78:81]
	v_mfma_f32_16x16x32_bf16 v[74:77], v[138:141], v[212:215], v[74:77]
	v_mfma_f32_16x16x32_bf16 v[126:129], v[134:137], v[192:195], v[126:129]
	v_mfma_f32_16x16x32_bf16 v[122:125], v[142:145], v[192:195], v[122:125]
	v_mfma_f32_16x16x32_bf16 v[110:113], v[134:137], v[200:203], v[110:113]
	v_mfma_f32_16x16x32_bf16 v[106:109], v[142:145], v[200:203], v[106:109]
	v_mfma_f32_16x16x32_bf16 v[94:97], v[134:137], v[208:211], v[94:97]
	v_mfma_f32_16x16x32_bf16 v[90:93], v[142:145], v[208:211], v[90:93]
	v_mfma_f32_16x16x32_bf16 v[78:81], v[134:137], v[216:219], v[78:81]
	v_mfma_f32_16x16x32_bf16 v[74:77], v[142:145], v[216:219], v[74:77]
	s_setprio 0
	s_setprio 1
	v_mfma_f32_16x16x32_bf16 v[118:121], v[162:165], v[188:191], v[118:121]
	v_mfma_f32_16x16x32_bf16 v[114:117], v[170:173], v[188:191], v[114:117]
	v_mfma_f32_16x16x32_bf16 v[102:105], v[162:165], v[196:199], v[102:105]
	v_mfma_f32_16x16x32_bf16 v[98:101], v[170:173], v[196:199], v[98:101]
	v_mfma_f32_16x16x32_bf16 v[86:89], v[162:165], v[204:207], v[86:89]
	v_mfma_f32_16x16x32_bf16 v[82:85], v[170:173], v[204:207], v[82:85]
	v_mfma_f32_16x16x32_bf16 v[70:73], v[162:165], v[212:215], v[70:73]
	v_mfma_f32_16x16x32_bf16 v[66:69], v[170:173], v[212:215], v[66:69]
	v_mfma_f32_16x16x32_bf16 v[118:121], v[166:169], v[192:195], v[118:121]
	v_mfma_f32_16x16x32_bf16 v[114:117], v[174:177], v[192:195], v[114:117]
	v_mfma_f32_16x16x32_bf16 v[102:105], v[166:169], v[200:203], v[102:105]
	v_mfma_f32_16x16x32_bf16 v[98:101], v[174:177], v[200:203], v[98:101]
	v_mfma_f32_16x16x32_bf16 v[86:89], v[166:169], v[208:211], v[86:89]
	v_mfma_f32_16x16x32_bf16 v[82:85], v[174:177], v[208:211], v[82:85]
	v_mfma_f32_16x16x32_bf16 v[70:73], v[166:169], v[216:219], v[70:73]
	v_mfma_f32_16x16x32_bf16 v[66:69], v[174:177], v[216:219], v[66:69]
	s_barrier
	s_setprio 0
	s_add_i32 s71, s63, s54
	v_lshl_add_u64 v[178:179], s[48:49], 0, v[148:149]
	s_mov_b32 m0, s71
	ds_read_b128 v[188:191], v185 offset:16384
	ds_read_b128 v[192:195], v185 offset:17408
	ds_read_b128 v[196:199], v185 offset:18432
	ds_read_b128 v[200:203], v185 offset:19456
	ds_read_b128 v[204:207], v185 offset:20480
	ds_read_b128 v[208:211], v185 offset:21504
	ds_read_b128 v[212:215], v185 offset:22528
	ds_read_b128 v[216:219], v185 offset:23552
	global_load_lds_dwordx4 v[178:179], off
	s_add_i32 m0, s71, 0x2000
	s_add_u32 s72, s48, 0x80000
	v_lshl_add_u64 v[220:221], s[48:49], 0, v[152:153]
	s_addc_u32 s73, s49, 0
	s_add_i32 s71, s64, s54
	global_load_lds_dwordx4 v[220:221], off
	v_lshl_add_u64 v[222:223], s[72:73], 0, v[148:149]
	s_mov_b32 m0, s71
	v_lshl_add_u64 v[224:225], s[52:53], 0, v[150:151]
	global_load_lds_dwordx4 v[222:223], off
	v_lshl_add_u64 v[222:223], s[72:73], 0, v[152:153]
	s_add_i32 m0, s71, 0x2000
	s_nop 0
	global_load_lds_dwordx4 v[222:223], off
	v_lshl_add_u64 v[222:223], s[52:53], 0, v[146:147]
	s_mov_b32 m0, s45
	s_nop 0
	global_load_lds_dwordx4 v[222:223], off
	s_mov_b32 m0, s55
	s_nop 0
	global_load_lds_dwordx4 v[224:225], off
	s_waitcnt vmcnt(8)
	s_waitcnt lgkmcnt(0)
	s_setprio 1
	s_barrier
	v_mfma_f32_16x16x32_bf16 v[62:65], v[130:133], v[188:191], v[62:65]
	v_mfma_f32_16x16x32_bf16 v[58:61], v[138:141], v[188:191], v[58:61]
	v_mfma_f32_16x16x32_bf16 v[46:49], v[130:133], v[196:199], v[46:49]
	v_mfma_f32_16x16x32_bf16 v[42:45], v[138:141], v[196:199], v[42:45]
	v_mfma_f32_16x16x32_bf16 v[30:33], v[130:133], v[204:207], v[30:33]
	v_mfma_f32_16x16x32_bf16 v[26:29], v[138:141], v[204:207], v[26:29]
	v_mfma_f32_16x16x32_bf16 v[14:17], v[130:133], v[212:215], v[14:17]
	v_mfma_f32_16x16x32_bf16 v[10:13], v[138:141], v[212:215], v[10:13]
	v_mfma_f32_16x16x32_bf16 v[62:65], v[134:137], v[192:195], v[62:65]
	v_mfma_f32_16x16x32_bf16 v[58:61], v[142:145], v[192:195], v[58:61]
	v_mfma_f32_16x16x32_bf16 v[46:49], v[134:137], v[200:203], v[46:49]
	v_mfma_f32_16x16x32_bf16 v[42:45], v[142:145], v[200:203], v[42:45]
	v_mfma_f32_16x16x32_bf16 v[30:33], v[134:137], v[208:211], v[30:33]
	v_mfma_f32_16x16x32_bf16 v[26:29], v[142:145], v[208:211], v[26:29]
	v_mfma_f32_16x16x32_bf16 v[14:17], v[134:137], v[216:219], v[14:17]
	v_mfma_f32_16x16x32_bf16 v[10:13], v[142:145], v[216:219], v[10:13]
	s_setprio 0
	s_setprio 1
	v_mfma_f32_16x16x32_bf16 v[54:57], v[162:165], v[188:191], v[54:57]
	v_mfma_f32_16x16x32_bf16 v[50:53], v[170:173], v[188:191], v[50:53]
	v_mfma_f32_16x16x32_bf16 v[38:41], v[162:165], v[196:199], v[38:41]
	v_mfma_f32_16x16x32_bf16 v[34:37], v[170:173], v[196:199], v[34:37]
	v_mfma_f32_16x16x32_bf16 v[22:25], v[162:165], v[204:207], v[22:25]
	v_mfma_f32_16x16x32_bf16 v[18:21], v[170:173], v[204:207], v[18:21]
	v_mfma_f32_16x16x32_bf16 v[6:9], v[162:165], v[212:215], v[6:9]
	v_mfma_f32_16x16x32_bf16 v[2:5], v[170:173], v[212:215], v[2:5]
	v_mfma_f32_16x16x32_bf16 v[54:57], v[166:169], v[192:195], v[54:57]
	v_mfma_f32_16x16x32_bf16 v[50:53], v[174:177], v[192:195], v[50:53]
	v_mfma_f32_16x16x32_bf16 v[38:41], v[166:169], v[200:203], v[38:41]
	v_mfma_f32_16x16x32_bf16 v[34:37], v[174:177], v[200:203], v[34:37]
	v_mfma_f32_16x16x32_bf16 v[22:25], v[166:169], v[208:211], v[22:25]
	v_mfma_f32_16x16x32_bf16 v[18:21], v[174:177], v[208:211], v[18:21]
	v_mfma_f32_16x16x32_bf16 v[6:9], v[166:169], v[216:219], v[6:9]
	v_mfma_f32_16x16x32_bf16 v[2:5], v[174:177], v[216:219], v[2:5]
	s_barrier
	s_setprio 0
	s_add_i32 s71, 0, 0x18000
	v_add_u32_e32 v1, s71, v181
	s_add_i32 s72, 0, 0x1c000
	ds_read_b128 v[130:133], v1
	ds_read_b128 v[134:137], v1 offset:1024
	ds_read_b128 v[138:141], v1 offset:2048
	ds_read_b128 v[142:145], v1 offset:3072
	v_add_u32_e32 v1, s72, v181
	ds_read_b128 v[162:165], v1
	ds_read_b128 v[166:169], v1 offset:1024
	ds_read_b128 v[170:173], v1 offset:2048
	ds_read_b128 v[174:177], v1 offset:3072
	s_add_u32 s52, s52, 0x80000
	s_addc_u32 s53, s53, 0
	s_mov_b32 m0, s56
	v_lshl_add_u64 v[226:227], s[52:53], 0, v[146:147]
	ds_read_b128 v[188:191], v185 offset:32768
	ds_read_b128 v[192:195], v185 offset:33792
	ds_read_b128 v[196:199], v185 offset:34816
	ds_read_b128 v[200:203], v185 offset:35840
	ds_read_b128 v[204:207], v185 offset:36864
	ds_read_b128 v[208:211], v185 offset:37888
	ds_read_b128 v[212:215], v185 offset:38912
	ds_read_b128 v[216:219], v185 offset:39936
	global_load_lds_dwordx4 v[226:227], off
	v_lshl_add_u64 v[226:227], s[52:53], 0, v[150:151]
	s_mov_b32 m0, s57
	s_nop 0
	global_load_lds_dwordx4 v[226:227], off
	s_waitcnt vmcnt(8)
	s_waitcnt lgkmcnt(0)
	s_setprio 1
	s_barrier
	v_mfma_f32_16x16x32_bf16 v[126:129], v[130:133], v[188:191], v[126:129]
	v_mfma_f32_16x16x32_bf16 v[122:125], v[138:141], v[188:191], v[122:125]
	v_mfma_f32_16x16x32_bf16 v[110:113], v[130:133], v[196:199], v[110:113]
	v_mfma_f32_16x16x32_bf16 v[106:109], v[138:141], v[196:199], v[106:109]
	v_mfma_f32_16x16x32_bf16 v[94:97], v[130:133], v[204:207], v[94:97]
	v_mfma_f32_16x16x32_bf16 v[90:93], v[138:141], v[204:207], v[90:93]
	v_mfma_f32_16x16x32_bf16 v[78:81], v[130:133], v[212:215], v[78:81]
	v_mfma_f32_16x16x32_bf16 v[74:77], v[138:141], v[212:215], v[74:77]
	v_mfma_f32_16x16x32_bf16 v[126:129], v[134:137], v[192:195], v[126:129]
	v_mfma_f32_16x16x32_bf16 v[122:125], v[142:145], v[192:195], v[122:125]
	v_mfma_f32_16x16x32_bf16 v[110:113], v[134:137], v[200:203], v[110:113]
	v_mfma_f32_16x16x32_bf16 v[106:109], v[142:145], v[200:203], v[106:109]
	v_mfma_f32_16x16x32_bf16 v[94:97], v[134:137], v[208:211], v[94:97]
	v_mfma_f32_16x16x32_bf16 v[90:93], v[142:145], v[208:211], v[90:93]
	v_mfma_f32_16x16x32_bf16 v[78:81], v[134:137], v[216:219], v[78:81]
	v_mfma_f32_16x16x32_bf16 v[74:77], v[142:145], v[216:219], v[74:77]
	s_setprio 0
	s_setprio 1
	v_mfma_f32_16x16x32_bf16 v[118:121], v[162:165], v[188:191], v[118:121]
	v_mfma_f32_16x16x32_bf16 v[114:117], v[170:173], v[188:191], v[114:117]
	v_mfma_f32_16x16x32_bf16 v[102:105], v[162:165], v[196:199], v[102:105]
	v_mfma_f32_16x16x32_bf16 v[98:101], v[170:173], v[196:199], v[98:101]
	v_mfma_f32_16x16x32_bf16 v[86:89], v[162:165], v[204:207], v[86:89]
	v_mfma_f32_16x16x32_bf16 v[82:85], v[170:173], v[204:207], v[82:85]
	v_mfma_f32_16x16x32_bf16 v[70:73], v[162:165], v[212:215], v[70:73]
	v_mfma_f32_16x16x32_bf16 v[66:69], v[170:173], v[212:215], v[66:69]
	v_mfma_f32_16x16x32_bf16 v[118:121], v[166:169], v[192:195], v[118:121]
	v_mfma_f32_16x16x32_bf16 v[114:117], v[174:177], v[192:195], v[114:117]
	v_mfma_f32_16x16x32_bf16 v[102:105], v[166:169], v[200:203], v[102:105]
	v_mfma_f32_16x16x32_bf16 v[98:101], v[174:177], v[200:203], v[98:101]
	v_mfma_f32_16x16x32_bf16 v[86:89], v[166:169], v[208:211], v[86:89]
	v_mfma_f32_16x16x32_bf16 v[82:85], v[174:177], v[208:211], v[82:85]
	v_mfma_f32_16x16x32_bf16 v[70:73], v[166:169], v[216:219], v[70:73]
	v_mfma_f32_16x16x32_bf16 v[66:69], v[174:177], v[216:219], v[66:69]
	s_barrier
	s_setprio 0
	s_add_i32 s52, s71, s54
	v_lshl_add_u64 v[178:179], v[178:179], 0, s[30:31]
	s_mov_b32 m0, s52
	ds_read_b128 v[188:191], v185 offset:49152
	ds_read_b128 v[192:195], v185 offset:50176
	ds_read_b128 v[196:199], v185 offset:51200
	ds_read_b128 v[200:203], v185 offset:52224
	ds_read_b128 v[204:207], v185 offset:53248
	ds_read_b128 v[208:211], v185 offset:54272
	ds_read_b128 v[212:215], v185 offset:55296
	ds_read_b128 v[216:219], v185 offset:56320
	global_load_lds_dwordx4 v[178:179], off
	s_add_i32 m0, s52, 0x2000
	s_add_u32 s48, s48, 0x80080
	v_lshl_add_u64 v[178:179], v[220:221], 0, s[30:31]
	s_addc_u32 s49, s49, 0
	s_add_i32 s52, s72, s54
	global_load_lds_dwordx4 v[178:179], off
	v_lshl_add_u64 v[178:179], s[48:49], 0, v[148:149]
	s_mov_b32 m0, s52
	s_nop 0
	global_load_lds_dwordx4 v[178:179], off
	v_lshl_add_u64 v[178:179], s[48:49], 0, v[152:153]
	s_add_i32 m0, s52, 0x2000
	s_nop 0
	global_load_lds_dwordx4 v[178:179], off
	v_lshl_add_u64 v[178:179], v[222:223], 0, s[30:31]
	s_mov_b32 m0, s60
	s_nop 0
	global_load_lds_dwordx4 v[178:179], off
	v_lshl_add_u64 v[178:179], v[224:225], 0, s[30:31]
	s_mov_b32 m0, s61
	s_nop 0
	global_load_lds_dwordx4 v[178:179], off
	s_waitcnt vmcnt(8)
	s_waitcnt lgkmcnt(0)
	s_setprio 1
	s_barrier
	v_mfma_f32_16x16x32_bf16 v[62:65], v[130:133], v[188:191], v[62:65]
	v_mfma_f32_16x16x32_bf16 v[58:61], v[138:141], v[188:191], v[58:61]
	v_mfma_f32_16x16x32_bf16 v[46:49], v[130:133], v[196:199], v[46:49]
	v_mfma_f32_16x16x32_bf16 v[42:45], v[138:141], v[196:199], v[42:45]
	v_mfma_f32_16x16x32_bf16 v[30:33], v[130:133], v[204:207], v[30:33]
	v_mfma_f32_16x16x32_bf16 v[26:29], v[138:141], v[204:207], v[26:29]
	v_mfma_f32_16x16x32_bf16 v[14:17], v[130:133], v[212:215], v[14:17]
	v_mfma_f32_16x16x32_bf16 v[10:13], v[138:141], v[212:215], v[10:13]
	v_mfma_f32_16x16x32_bf16 v[62:65], v[134:137], v[192:195], v[62:65]
	v_mfma_f32_16x16x32_bf16 v[58:61], v[142:145], v[192:195], v[58:61]
	v_mfma_f32_16x16x32_bf16 v[46:49], v[134:137], v[200:203], v[46:49]
	v_mfma_f32_16x16x32_bf16 v[42:45], v[142:145], v[200:203], v[42:45]
	v_mfma_f32_16x16x32_bf16 v[30:33], v[134:137], v[208:211], v[30:33]
	v_mfma_f32_16x16x32_bf16 v[26:29], v[142:145], v[208:211], v[26:29]
	v_mfma_f32_16x16x32_bf16 v[14:17], v[134:137], v[216:219], v[14:17]
	v_mfma_f32_16x16x32_bf16 v[10:13], v[142:145], v[216:219], v[10:13]
	s_setprio 0
	s_setprio 1
	v_mfma_f32_16x16x32_bf16 v[54:57], v[162:165], v[188:191], v[54:57]
	v_mfma_f32_16x16x32_bf16 v[50:53], v[170:173], v[188:191], v[50:53]
	v_mfma_f32_16x16x32_bf16 v[38:41], v[162:165], v[196:199], v[38:41]
	v_mfma_f32_16x16x32_bf16 v[34:37], v[170:173], v[196:199], v[34:37]
	v_mfma_f32_16x16x32_bf16 v[22:25], v[162:165], v[204:207], v[22:25]
	v_mfma_f32_16x16x32_bf16 v[18:21], v[170:173], v[204:207], v[18:21]
	v_mfma_f32_16x16x32_bf16 v[6:9], v[162:165], v[212:215], v[6:9]
	v_mfma_f32_16x16x32_bf16 v[2:5], v[170:173], v[212:215], v[2:5]
	v_mfma_f32_16x16x32_bf16 v[54:57], v[166:169], v[192:195], v[54:57]
	v_mfma_f32_16x16x32_bf16 v[50:53], v[174:177], v[192:195], v[50:53]
	v_mfma_f32_16x16x32_bf16 v[38:41], v[166:169], v[200:203], v[38:41]
	v_mfma_f32_16x16x32_bf16 v[34:37], v[174:177], v[200:203], v[34:37]
	v_mfma_f32_16x16x32_bf16 v[22:25], v[166:169], v[208:211], v[22:25]
	v_mfma_f32_16x16x32_bf16 v[18:21], v[174:177], v[208:211], v[18:21]
	v_mfma_f32_16x16x32_bf16 v[6:9], v[166:169], v[216:219], v[6:9]
	v_mfma_f32_16x16x32_bf16 v[2:5], v[174:177], v[216:219], v[2:5]
	s_barrier
	s_setprio 0
	s_add_i32 s70, s70, 2
	s_add_u32 s46, s46, 0x100
	s_addc_u32 s47, s47, 0
	s_add_u32 s68, s68, 0x100
	s_addc_u32 s69, s69, 0
	s_cmp_gt_u32 s70, 29
	s_cbranch_scc0 .LBB0_1408
	s_and_b64 vcc, exec, s[34:35]
	s_cbranch_vccz .LBB0_1411
	s_barrier

.LBB0_1478:
	s_ashr_i32 s11, s10, 31
	s_lshl_b64 s[6:7], s[10:11], 20
	s_add_u32 s38, s19, s6
	s_addc_u32 s39, s22, s7
	s_and_b64 s[6:7], s[2:3], exec
	s_cselect_b32 s9, s39, s1
	s_cselect_b32 s11, s38, s0
	s_ashr_i32 s37, s36, 31
	s_lshl_b64 s[6:7], s[36:37], 20
	s_add_u32 s40, s23, s6
	s_addc_u32 s41, s28, s7
	s_and_b64 s[6:7], s[2:3], exec
	s_cselect_b32 s37, s41, s5
	s_cselect_b32 s60, s40, s4
	s_add_u32 s0, s0, 0x80080
	s_addc_u32 s1, s1, 0
	s_add_u32 s61, s4, 0x100
	v_mov_b32_e32 v2, 0
	v_mov_b32_e32 v3, 0
	s_addc_u32 s62, s5, 0
	s_mov_b32 s63, -2
	v_mov_b64_e32 v[4:5], v[2:3]
	v_mov_b64_e32 v[6:7], v[2:3]
	v_mov_b64_e32 v[8:9], v[2:3]
	v_mov_b64_e32 v[10:11], v[2:3]
	v_mov_b64_e32 v[12:13], v[2:3]
	v_mov_b64_e32 v[14:15], v[2:3]
	v_mov_b64_e32 v[16:17], v[2:3]
	v_mov_b64_e32 v[18:19], v[2:3]
	v_mov_b64_e32 v[20:21], v[2:3]
	v_mov_b64_e32 v[22:23], v[2:3]
	v_mov_b64_e32 v[24:25], v[2:3]
	v_mov_b64_e32 v[26:27], v[2:3]
	v_mov_b64_e32 v[28:29], v[2:3]
	v_mov_b64_e32 v[30:31], v[2:3]
	v_mov_b64_e32 v[32:33], v[2:3]
	v_mov_b64_e32 v[34:35], v[2:3]
	v_mov_b64_e32 v[36:37], v[2:3]
	v_mov_b64_e32 v[38:39], v[2:3]
	v_mov_b64_e32 v[40:41], v[2:3]
	v_mov_b64_e32 v[42:43], v[2:3]
	v_mov_b64_e32 v[44:45], v[2:3]
	v_mov_b64_e32 v[46:47], v[2:3]
	v_mov_b64_e32 v[48:49], v[2:3]
	v_mov_b64_e32 v[50:51], v[2:3]
	v_mov_b64_e32 v[52:53], v[2:3]
	v_mov_b64_e32 v[54:55], v[2:3]
	v_mov_b64_e32 v[56:57], v[2:3]
	v_mov_b64_e32 v[58:59], v[2:3]
	v_mov_b64_e32 v[60:61], v[2:3]
	v_mov_b64_e32 v[62:63], v[2:3]
	v_mov_b64_e32 v[64:65], v[2:3]
	v_mov_b64_e32 v[68:69], v[2:3]
	v_mov_b64_e32 v[70:71], v[2:3]
	v_mov_b64_e32 v[72:73], v[2:3]
	v_mov_b64_e32 v[74:75], v[2:3]
	v_mov_b64_e32 v[76:77], v[2:3]
	v_mov_b64_e32 v[78:79], v[2:3]
	v_mov_b64_e32 v[80:81], v[2:3]
	v_mov_b64_e32 v[82:83], v[2:3]
	v_mov_b64_e32 v[84:85], v[2:3]
	v_mov_b64_e32 v[86:87], v[2:3]
	v_mov_b64_e32 v[88:89], v[2:3]
	v_mov_b64_e32 v[90:91], v[2:3]
	v_mov_b64_e32 v[92:93], v[2:3]
	v_mov_b64_e32 v[94:95], v[2:3]
	v_mov_b64_e32 v[96:97], v[2:3]
	v_mov_b64_e32 v[98:99], v[2:3]
	v_mov_b64_e32 v[100:101], v[2:3]
	v_mov_b64_e32 v[102:103], v[2:3]
	v_mov_b64_e32 v[104:105], v[2:3]
	v_mov_b64_e32 v[106:107], v[2:3]
	v_mov_b64_e32 v[108:109], v[2:3]
	v_mov_b64_e32 v[110:111], v[2:3]
	v_mov_b64_e32 v[112:113], v[2:3]
	v_mov_b64_e32 v[114:115], v[2:3]
	v_mov_b64_e32 v[116:117], v[2:3]
	v_mov_b64_e32 v[118:119], v[2:3]
	v_mov_b64_e32 v[120:121], v[2:3]
	v_mov_b64_e32 v[122:123], v[2:3]
	v_mov_b64_e32 v[124:125], v[2:3]
	v_mov_b64_e32 v[126:127], v[2:3]
	v_mov_b64_e32 v[128:129], v[2:3]
	v_mov_b64_e32 v[130:131], v[2:3]
.LBB0_1479:
	ds_read_b128 v[132:135], v174
	ds_read_b128 v[158:161], v174 offset:1024
	ds_read_b128 v[166:169], v174 offset:2048
	ds_read_b128 v[170:173], v174 offset:3072
	ds_read_b128 v[182:185], v175
	ds_read_b128 v[186:189], v175 offset:1024
	ds_read_b128 v[190:193], v175 offset:2048
	ds_read_b128 v[194:197], v175 offset:3072
	s_add_u32 s4, s0, 0xfff80080
	s_addc_u32 s5, s1, -1
	s_cmp_eq_u32 s63, 28
	s_cselect_b32 s7, s9, s5
	s_cselect_b32 s6, s11, s4
	s_cselect_b32 s5, s37, s62
	s_cselect_b32 s4, s60, s61
	v_lshl_add_u64 v[136:137], s[0:1], 0, v[146:147]
	s_add_i32 m0, s44, 0xc000
	ds_read_b128 v[198:201], v176
	ds_read_b128 v[202:205], v176 offset:1024
	ds_read_b128 v[206:209], v176 offset:2048
	ds_read_b128 v[210:213], v176 offset:3072
	ds_read_b128 v[214:217], v176 offset:4096
	ds_read_b128 v[218:221], v176 offset:5120
	ds_read_b128 v[222:225], v176 offset:6144
	ds_read_b128 v[226:229], v176 offset:7168
	global_load_lds_dwordx4 v[136:137], off
	v_lshl_add_u64 v[136:137], s[0:1], 0, v[148:149]
	s_add_i32 m0, s44, 0xe000
	s_nop 0
	global_load_lds_dwordx4 v[136:137], off
	s_waitcnt vmcnt(8)
	s_waitcnt lgkmcnt(0)
	s_setprio 1
	s_barrier
	v_mfma_f32_16x16x32_bf16 v[128:131], v[132:135], v[198:201], v[128:131]
	v_mfma_f32_16x16x32_bf16 v[124:127], v[166:169], v[198:201], v[124:127]
	v_mfma_f32_16x16x32_bf16 v[112:115], v[132:135], v[206:209], v[112:115]
	v_mfma_f32_16x16x32_bf16 v[108:111], v[166:169], v[206:209], v[108:111]
	v_mfma_f32_16x16x32_bf16 v[96:99], v[132:135], v[214:217], v[96:99]
	v_mfma_f32_16x16x32_bf16 v[92:95], v[166:169], v[214:217], v[92:95]
	v_mfma_f32_16x16x32_bf16 v[80:83], v[132:135], v[222:225], v[80:83]
	v_mfma_f32_16x16x32_bf16 v[76:79], v[166:169], v[222:225], v[76:79]
	v_mfma_f32_16x16x32_bf16 v[128:131], v[158:161], v[202:205], v[128:131]
	v_mfma_f32_16x16x32_bf16 v[124:127], v[170:173], v[202:205], v[124:127]
	v_mfma_f32_16x16x32_bf16 v[112:115], v[158:161], v[210:213], v[112:115]
	v_mfma_f32_16x16x32_bf16 v[108:111], v[170:173], v[210:213], v[108:111]
	v_mfma_f32_16x16x32_bf16 v[96:99], v[158:161], v[218:221], v[96:99]
	v_mfma_f32_16x16x32_bf16 v[92:95], v[170:173], v[218:221], v[92:95]
	v_mfma_f32_16x16x32_bf16 v[80:83], v[158:161], v[226:229], v[80:83]
	v_mfma_f32_16x16x32_bf16 v[76:79], v[170:173], v[226:229], v[76:79]
	s_setprio 0
	s_setprio 1
	v_mfma_f32_16x16x32_bf16 v[120:123], v[182:185], v[198:201], v[120:123]
	v_mfma_f32_16x16x32_bf16 v[116:119], v[190:193], v[198:201], v[116:119]
	v_mfma_f32_16x16x32_bf16 v[104:107], v[182:185], v[206:209], v[104:107]
	v_mfma_f32_16x16x32_bf16 v[100:103], v[190:193], v[206:209], v[100:103]
	v_mfma_f32_16x16x32_bf16 v[88:91], v[182:185], v[214:217], v[88:91]
	v_mfma_f32_16x16x32_bf16 v[84:87], v[190:193], v[214:217], v[84:87]
	v_mfma_f32_16x16x32_bf16 v[72:75], v[182:185], v[222:225], v[72:75]
	v_mfma_f32_16x16x32_bf16 v[68:71], v[190:193], v[222:225], v[68:71]
	v_mfma_f32_16x16x32_bf16 v[120:123], v[186:189], v[202:205], v[120:123]
	v_mfma_f32_16x16x32_bf16 v[116:119], v[194:197], v[202:205], v[116:119]
	v_mfma_f32_16x16x32_bf16 v[104:107], v[186:189], v[210:213], v[104:107]
	v_mfma_f32_16x16x32_bf16 v[100:103], v[194:197], v[210:213], v[100:103]
	v_mfma_f32_16x16x32_bf16 v[88:91], v[186:189], v[218:221], v[88:91]
	v_mfma_f32_16x16x32_bf16 v[84:87], v[194:197], v[218:221], v[84:87]
	v_mfma_f32_16x16x32_bf16 v[72:75], v[186:189], v[226:229], v[72:75]
	v_mfma_f32_16x16x32_bf16 v[68:71], v[194:197], v[226:229], v[68:71]
	s_barrier
	s_setprio 0
	s_add_i32 s64, s54, s29
	v_lshl_add_u64 v[136:137], s[4:5], 0, v[142:143]
	s_mov_b32 m0, s64
	ds_read_b128 v[198:201], v176 offset:16384
	ds_read_b128 v[202:205], v176 offset:17408
	ds_read_b128 v[206:209], v176 offset:18432
	ds_read_b128 v[210:213], v176 offset:19456
	ds_read_b128 v[214:217], v176 offset:20480
	ds_read_b128 v[218:221], v176 offset:21504
	ds_read_b128 v[222:225], v176 offset:22528
	ds_read_b128 v[226:229], v176 offset:23552
	global_load_lds_dwordx4 v[136:137], off
	s_add_i32 m0, s64, 0x2000
	s_add_u32 s64, s4, 0x80000
	v_lshl_add_u64 v[230:231], s[4:5], 0, v[138:139]
	s_addc_u32 s65, s5, 0
	s_add_i32 s66, s55, s29
	global_load_lds_dwordx4 v[230:231], off
	v_lshl_add_u64 v[232:233], s[64:65], 0, v[142:143]
	s_mov_b32 m0, s66
	v_lshl_add_u64 v[234:235], s[6:7], 0, v[140:141]
	global_load_lds_dwordx4 v[232:233], off
	v_lshl_add_u64 v[232:233], s[64:65], 0, v[138:139]
	s_add_i32 m0, s66, 0x2000
	s_nop 0
	global_load_lds_dwordx4 v[232:233], off
	v_lshl_add_u64 v[232:233], s[6:7], 0, v[144:145]
	s_mov_b32 m0, s44
	s_nop 0
	global_load_lds_dwordx4 v[232:233], off
	s_mov_b32 m0, s45
	s_nop 0
	global_load_lds_dwordx4 v[234:235], off
	s_waitcnt vmcnt(8)
	s_waitcnt lgkmcnt(0)
	s_setprio 1
	s_barrier
	v_mfma_f32_16x16x32_bf16 v[62:65], v[132:135], v[198:201], v[62:65]
	v_mfma_f32_16x16x32_bf16 v[58:61], v[166:169], v[198:201], v[58:61]
	v_mfma_f32_16x16x32_bf16 v[46:49], v[132:135], v[206:209], v[46:49]
	v_mfma_f32_16x16x32_bf16 v[42:45], v[166:169], v[206:209], v[42:45]
	v_mfma_f32_16x16x32_bf16 v[30:33], v[132:135], v[214:217], v[30:33]
	v_mfma_f32_16x16x32_bf16 v[26:29], v[166:169], v[214:217], v[26:29]
	v_mfma_f32_16x16x32_bf16 v[14:17], v[132:135], v[222:225], v[14:17]
	v_mfma_f32_16x16x32_bf16 v[10:13], v[166:169], v[222:225], v[10:13]
	v_mfma_f32_16x16x32_bf16 v[62:65], v[158:161], v[202:205], v[62:65]
	v_mfma_f32_16x16x32_bf16 v[58:61], v[170:173], v[202:205], v[58:61]
	v_mfma_f32_16x16x32_bf16 v[46:49], v[158:161], v[210:213], v[46:49]
	v_mfma_f32_16x16x32_bf16 v[42:45], v[170:173], v[210:213], v[42:45]
	v_mfma_f32_16x16x32_bf16 v[30:33], v[158:161], v[218:221], v[30:33]
	v_mfma_f32_16x16x32_bf16 v[26:29], v[170:173], v[218:221], v[26:29]
	v_mfma_f32_16x16x32_bf16 v[14:17], v[158:161], v[226:229], v[14:17]
	v_mfma_f32_16x16x32_bf16 v[10:13], v[170:173], v[226:229], v[10:13]
	s_setprio 0
	s_setprio 1
	v_mfma_f32_16x16x32_bf16 v[54:57], v[182:185], v[198:201], v[54:57]
	v_mfma_f32_16x16x32_bf16 v[50:53], v[190:193], v[198:201], v[50:53]
	v_mfma_f32_16x16x32_bf16 v[38:41], v[182:185], v[206:209], v[38:41]
	v_mfma_f32_16x16x32_bf16 v[34:37], v[190:193], v[206:209], v[34:37]
	v_mfma_f32_16x16x32_bf16 v[22:25], v[182:185], v[214:217], v[22:25]
	v_mfma_f32_16x16x32_bf16 v[18:21], v[190:193], v[214:217], v[18:21]
	v_mfma_f32_16x16x32_bf16 v[6:9], v[182:185], v[222:225], v[6:9]
	v_mfma_f32_16x16x32_bf16 v[2:5], v[190:193], v[222:225], v[2:5]
	v_mfma_f32_16x16x32_bf16 v[54:57], v[186:189], v[202:205], v[54:57]
	v_mfma_f32_16x16x32_bf16 v[50:53], v[194:197], v[202:205], v[50:53]
	v_mfma_f32_16x16x32_bf16 v[38:41], v[186:189], v[210:213], v[38:41]
	v_mfma_f32_16x16x32_bf16 v[34:37], v[194:197], v[210:213], v[34:37]
	v_mfma_f32_16x16x32_bf16 v[22:25], v[186:189], v[218:221], v[22:25]
	v_mfma_f32_16x16x32_bf16 v[18:21], v[194:197], v[218:221], v[18:21]
	v_mfma_f32_16x16x32_bf16 v[6:9], v[186:189], v[226:229], v[6:9]
	v_mfma_f32_16x16x32_bf16 v[2:5], v[194:197], v[226:229], v[2:5]
	s_barrier
	s_setprio 0
	s_add_i32 s64, 0, 0x18000
	v_add_u32_e32 v162, s64, v163
	s_add_i32 s65, 0, 0x1c000
	ds_read_b128 v[132:135], v162
	ds_read_b128 v[158:161], v162 offset:1024
	ds_read_b128 v[166:169], v162 offset:2048
	ds_read_b128 v[170:173], v162 offset:3072
	v_add_u32_e32 v162, s65, v163
	ds_read_b128 v[182:185], v162
	ds_read_b128 v[186:189], v162 offset:1024
	ds_read_b128 v[190:193], v162 offset:2048
	ds_read_b128 v[194:197], v162 offset:3072
	s_add_u32 s6, s6, 0x80000
	s_addc_u32 s7, s7, 0
	s_mov_b32 m0, s46
	v_lshl_add_u64 v[236:237], s[6:7], 0, v[144:145]
	ds_read_b128 v[198:201], v176 offset:32768
	ds_read_b128 v[202:205], v176 offset:33792
	ds_read_b128 v[206:209], v176 offset:34816
	ds_read_b128 v[210:213], v176 offset:35840
	ds_read_b128 v[214:217], v176 offset:36864
	ds_read_b128 v[218:221], v176 offset:37888
	ds_read_b128 v[222:225], v176 offset:38912
	ds_read_b128 v[226:229], v176 offset:39936
	global_load_lds_dwordx4 v[236:237], off
	v_lshl_add_u64 v[236:237], s[6:7], 0, v[140:141]
	s_mov_b32 m0, s47
	s_nop 0
	global_load_lds_dwordx4 v[236:237], off
	s_waitcnt vmcnt(8)
	s_waitcnt lgkmcnt(0)
	s_setprio 1
	s_barrier
	v_mfma_f32_16x16x32_bf16 v[128:131], v[132:135], v[198:201], v[128:131]
	v_mfma_f32_16x16x32_bf16 v[124:127], v[166:169], v[198:201], v[124:127]
	v_mfma_f32_16x16x32_bf16 v[112:115], v[132:135], v[206:209], v[112:115]
	v_mfma_f32_16x16x32_bf16 v[108:111], v[166:169], v[206:209], v[108:111]
	v_mfma_f32_16x16x32_bf16 v[96:99], v[132:135], v[214:217], v[96:99]
	v_mfma_f32_16x16x32_bf16 v[92:95], v[166:169], v[214:217], v[92:95]
	v_mfma_f32_16x16x32_bf16 v[80:83], v[132:135], v[222:225], v[80:83]
	v_mfma_f32_16x16x32_bf16 v[76:79], v[166:169], v[222:225], v[76:79]
	v_mfma_f32_16x16x32_bf16 v[128:131], v[158:161], v[202:205], v[128:131]
	v_mfma_f32_16x16x32_bf16 v[124:127], v[170:173], v[202:205], v[124:127]
	v_mfma_f32_16x16x32_bf16 v[112:115], v[158:161], v[210:213], v[112:115]
	v_mfma_f32_16x16x32_bf16 v[108:111], v[170:173], v[210:213], v[108:111]
	v_mfma_f32_16x16x32_bf16 v[96:99], v[158:161], v[218:221], v[96:99]
	v_mfma_f32_16x16x32_bf16 v[92:95], v[170:173], v[218:221], v[92:95]
	v_mfma_f32_16x16x32_bf16 v[80:83], v[158:161], v[226:229], v[80:83]
	v_mfma_f32_16x16x32_bf16 v[76:79], v[170:173], v[226:229], v[76:79]
	s_setprio 0
	s_setprio 1
	v_mfma_f32_16x16x32_bf16 v[120:123], v[182:185], v[198:201], v[120:123]
	v_mfma_f32_16x16x32_bf16 v[116:119], v[190:193], v[198:201], v[116:119]
	v_mfma_f32_16x16x32_bf16 v[104:107], v[182:185], v[206:209], v[104:107]
	v_mfma_f32_16x16x32_bf16 v[100:103], v[190:193], v[206:209], v[100:103]
	v_mfma_f32_16x16x32_bf16 v[88:91], v[182:185], v[214:217], v[88:91]
	v_mfma_f32_16x16x32_bf16 v[84:87], v[190:193], v[214:217], v[84:87]
	v_mfma_f32_16x16x32_bf16 v[72:75], v[182:185], v[222:225], v[72:75]
	v_mfma_f32_16x16x32_bf16 v[68:71], v[190:193], v[222:225], v[68:71]
	v_mfma_f32_16x16x32_bf16 v[120:123], v[186:189], v[202:205], v[120:123]
	v_mfma_f32_16x16x32_bf16 v[116:119], v[194:197], v[202:205], v[116:119]
	v_mfma_f32_16x16x32_bf16 v[104:107], v[186:189], v[210:213], v[104:107]
	v_mfma_f32_16x16x32_bf16 v[100:103], v[194:197], v[210:213], v[100:103]
	v_mfma_f32_16x16x32_bf16 v[88:91], v[186:189], v[218:221], v[88:91]
	v_mfma_f32_16x16x32_bf16 v[84:87], v[194:197], v[218:221], v[84:87]
	v_mfma_f32_16x16x32_bf16 v[72:75], v[186:189], v[226:229], v[72:75]
	v_mfma_f32_16x16x32_bf16 v[68:71], v[194:197], v[226:229], v[68:71]
	s_barrier
	s_setprio 0
	s_add_i32 s6, s64, s29
	v_lshl_add_u64 v[136:137], v[136:137], 0, s[30:31]
	s_mov_b32 m0, s6
	ds_read_b128 v[198:201], v176 offset:49152
	ds_read_b128 v[202:205], v176 offset:50176
	ds_read_b128 v[206:209], v176 offset:51200
	ds_read_b128 v[210:213], v176 offset:52224
	ds_read_b128 v[214:217], v176 offset:53248
	ds_read_b128 v[218:221], v176 offset:54272
	ds_read_b128 v[222:225], v176 offset:55296
	ds_read_b128 v[226:229], v176 offset:56320
	global_load_lds_dwordx4 v[136:137], off
	s_add_i32 m0, s6, 0x2000
	s_add_u32 s4, s4, 0x80080
	v_lshl_add_u64 v[136:137], v[230:231], 0, s[30:31]
	s_addc_u32 s5, s5, 0
	s_add_i32 s6, s65, s29
	global_load_lds_dwordx4 v[136:137], off
	v_lshl_add_u64 v[136:137], s[4:5], 0, v[142:143]
	s_mov_b32 m0, s6
	s_nop 0
	global_load_lds_dwordx4 v[136:137], off
	v_lshl_add_u64 v[136:137], s[4:5], 0, v[138:139]
	s_add_i32 m0, s6, 0x2000
	s_nop 0
	global_load_lds_dwordx4 v[136:137], off
	v_lshl_add_u64 v[136:137], v[232:233], 0, s[30:31]
	s_mov_b32 m0, s48
	s_nop 0
	global_load_lds_dwordx4 v[136:137], off
	v_lshl_add_u64 v[136:137], v[234:235], 0, s[30:31]
	s_mov_b32 m0, s49
	s_nop 0
	global_load_lds_dwordx4 v[136:137], off
	s_waitcnt vmcnt(8)
	s_waitcnt lgkmcnt(0)
	s_setprio 1
	s_barrier
	v_mfma_f32_16x16x32_bf16 v[62:65], v[132:135], v[198:201], v[62:65]
	v_mfma_f32_16x16x32_bf16 v[58:61], v[166:169], v[198:201], v[58:61]
	v_mfma_f32_16x16x32_bf16 v[46:49], v[132:135], v[206:209], v[46:49]
	v_mfma_f32_16x16x32_bf16 v[42:45], v[166:169], v[206:209], v[42:45]
	v_mfma_f32_16x16x32_bf16 v[30:33], v[132:135], v[214:217], v[30:33]
	v_mfma_f32_16x16x32_bf16 v[26:29], v[166:169], v[214:217], v[26:29]
	v_mfma_f32_16x16x32_bf16 v[14:17], v[132:135], v[222:225], v[14:17]
	v_mfma_f32_16x16x32_bf16 v[10:13], v[166:169], v[222:225], v[10:13]
	v_mfma_f32_16x16x32_bf16 v[62:65], v[158:161], v[202:205], v[62:65]
	v_mfma_f32_16x16x32_bf16 v[58:61], v[170:173], v[202:205], v[58:61]
	v_mfma_f32_16x16x32_bf16 v[46:49], v[158:161], v[210:213], v[46:49]
	v_mfma_f32_16x16x32_bf16 v[42:45], v[170:173], v[210:213], v[42:45]
	v_mfma_f32_16x16x32_bf16 v[30:33], v[158:161], v[218:221], v[30:33]
	v_mfma_f32_16x16x32_bf16 v[26:29], v[170:173], v[218:221], v[26:29]
	v_mfma_f32_16x16x32_bf16 v[14:17], v[158:161], v[226:229], v[14:17]
	v_mfma_f32_16x16x32_bf16 v[10:13], v[170:173], v[226:229], v[10:13]
	s_setprio 0
	s_setprio 1
	v_mfma_f32_16x16x32_bf16 v[54:57], v[182:185], v[198:201], v[54:57]
	v_mfma_f32_16x16x32_bf16 v[50:53], v[190:193], v[198:201], v[50:53]
	v_mfma_f32_16x16x32_bf16 v[38:41], v[182:185], v[206:209], v[38:41]
	v_mfma_f32_16x16x32_bf16 v[34:37], v[190:193], v[206:209], v[34:37]
	v_mfma_f32_16x16x32_bf16 v[22:25], v[182:185], v[214:217], v[22:25]
	v_mfma_f32_16x16x32_bf16 v[18:21], v[190:193], v[214:217], v[18:21]
	v_mfma_f32_16x16x32_bf16 v[6:9], v[182:185], v[222:225], v[6:9]
	v_mfma_f32_16x16x32_bf16 v[2:5], v[190:193], v[222:225], v[2:5]
	v_mfma_f32_16x16x32_bf16 v[54:57], v[186:189], v[202:205], v[54:57]
	v_mfma_f32_16x16x32_bf16 v[50:53], v[194:197], v[202:205], v[50:53]
	v_mfma_f32_16x16x32_bf16 v[38:41], v[186:189], v[210:213], v[38:41]
	v_mfma_f32_16x16x32_bf16 v[34:37], v[194:197], v[210:213], v[34:37]
	v_mfma_f32_16x16x32_bf16 v[22:25], v[186:189], v[218:221], v[22:25]
	v_mfma_f32_16x16x32_bf16 v[18:21], v[194:197], v[218:221], v[18:21]
	v_mfma_f32_16x16x32_bf16 v[6:9], v[186:189], v[226:229], v[6:9]
	v_mfma_f32_16x16x32_bf16 v[2:5], v[194:197], v[226:229], v[2:5]
	s_barrier
	s_setprio 0
	s_add_i32 s63, s63, 2
	s_add_u32 s0, s0, 0x100
	s_addc_u32 s1, s1, 0
	s_add_u32 s61, s61, 0x100
	s_addc_u32 s62, s62, 0
	s_cmp_gt_u32 s63, 29
	s_cbranch_scc0 .LBB0_1479
	s_and_b64 vcc, exec, s[34:35]
	s_cbranch_vccz .LBB0_1482
	s_barrier

.LBB0_1565:
	s_add_u32 s16, s16, 0x160080
	s_addc_u32 s17, s17, 0
	s_add_u32 s46, s20, 0x100
	v_mov_b32_e32 v4, 0
	v_mov_b32_e32 v5, 0
	s_addc_u32 s47, s21, 0
	s_mov_b32 s48, -2
	v_mov_b64_e32 v[0:1], v[4:5]
	v_mov_b64_e32 v[2:3], v[4:5]
	v_mov_b64_e32 v[6:7], v[4:5]
	v_mov_b64_e32 v[8:9], v[4:5]
	v_mov_b64_e32 v[10:11], v[4:5]
	v_mov_b64_e32 v[12:13], v[4:5]
	v_mov_b64_e32 v[14:15], v[4:5]
	v_mov_b64_e32 v[16:17], v[4:5]
	v_mov_b64_e32 v[18:19], v[4:5]
	v_mov_b64_e32 v[20:21], v[4:5]
	v_mov_b64_e32 v[22:23], v[4:5]
	v_mov_b64_e32 v[24:25], v[4:5]
	v_mov_b64_e32 v[26:27], v[4:5]
	v_mov_b64_e32 v[28:29], v[4:5]
	v_mov_b64_e32 v[30:31], v[4:5]
	v_mov_b64_e32 v[32:33], v[4:5]
	v_mov_b64_e32 v[34:35], v[4:5]
	v_mov_b64_e32 v[36:37], v[4:5]
	v_mov_b64_e32 v[38:39], v[4:5]
	v_mov_b64_e32 v[40:41], v[4:5]
	v_mov_b64_e32 v[42:43], v[4:5]
	v_mov_b64_e32 v[44:45], v[4:5]
	v_mov_b64_e32 v[46:47], v[4:5]
	v_mov_b64_e32 v[48:49], v[4:5]
	v_mov_b64_e32 v[50:51], v[4:5]
	v_mov_b64_e32 v[52:53], v[4:5]
	v_mov_b64_e32 v[54:55], v[4:5]
	v_mov_b64_e32 v[56:57], v[4:5]
	v_mov_b64_e32 v[58:59], v[4:5]
	v_mov_b64_e32 v[60:61], v[4:5]
	v_mov_b64_e32 v[62:63], v[4:5]
	v_mov_b64_e32 v[64:65], v[4:5]
	v_mov_b64_e32 v[66:67], v[4:5]
	v_mov_b64_e32 v[68:69], v[4:5]
	v_mov_b64_e32 v[70:71], v[4:5]
	v_mov_b64_e32 v[72:73], v[4:5]
	v_mov_b64_e32 v[74:75], v[4:5]
	v_mov_b64_e32 v[76:77], v[4:5]
	v_mov_b64_e32 v[78:79], v[4:5]
	v_mov_b64_e32 v[80:81], v[4:5]
	v_mov_b64_e32 v[82:83], v[4:5]
	v_mov_b64_e32 v[84:85], v[4:5]
	v_mov_b64_e32 v[86:87], v[4:5]
	v_mov_b64_e32 v[88:89], v[4:5]
	v_mov_b64_e32 v[90:91], v[4:5]
	v_mov_b64_e32 v[92:93], v[4:5]
	v_mov_b64_e32 v[94:95], v[4:5]
	v_mov_b64_e32 v[96:97], v[4:5]
	v_mov_b64_e32 v[98:99], v[4:5]
	v_mov_b64_e32 v[100:101], v[4:5]
	v_mov_b64_e32 v[102:103], v[4:5]
	v_mov_b64_e32 v[104:105], v[4:5]
	v_mov_b64_e32 v[106:107], v[4:5]
	v_mov_b64_e32 v[108:109], v[4:5]
	v_mov_b64_e32 v[110:111], v[4:5]
	v_mov_b64_e32 v[112:113], v[4:5]
	v_mov_b64_e32 v[114:115], v[4:5]
	v_mov_b64_e32 v[116:117], v[4:5]
	v_mov_b64_e32 v[118:119], v[4:5]
	v_mov_b64_e32 v[120:121], v[4:5]
	v_mov_b64_e32 v[122:123], v[4:5]
	v_mov_b64_e32 v[124:125], v[4:5]
	v_mov_b64_e32 v[126:127], v[4:5]
.LBB0_1566:
	ds_read_b128 v[144:147], v151
	ds_read_b128 v[154:157], v151 offset:1024
	ds_read_b128 v[158:161], v151 offset:2048
	ds_read_b128 v[162:165], v151 offset:3072
	ds_read_b128 v[166:169], v152
	ds_read_b128 v[170:173], v152 offset:1024
	ds_read_b128 v[174:177], v152 offset:2048
	ds_read_b128 v[178:181], v152 offset:3072
	s_add_u32 s20, s16, 0xffea0080
	s_addc_u32 s21, s17, -1
	s_cmpk_eq_i32 s48, 0x54
	s_cselect_b32 s27, s5, s21
	s_cselect_b32 s26, s4, s20
	s_cselect_b32 s21, s15, s47
	s_cselect_b32 s20, s14, s46
	v_lshl_add_u64 v[214:215], s[16:17], 0, v[136:137]
	s_add_i32 m0, s30, 0xc000
	ds_read_b128 v[182:185], v153
	ds_read_b128 v[186:189], v153 offset:1024
	ds_read_b128 v[190:193], v153 offset:2048
	ds_read_b128 v[194:197], v153 offset:3072
	ds_read_b128 v[198:201], v153 offset:4096
	ds_read_b128 v[202:205], v153 offset:5120
	ds_read_b128 v[206:209], v153 offset:6144
	ds_read_b128 v[210:213], v153 offset:7168
	global_load_lds_dwordx4 v[214:215], off
	v_lshl_add_u64 v[214:215], s[16:17], 0, v[138:139]
	s_add_i32 m0, s30, 0xe000
	s_nop 0
	global_load_lds_dwordx4 v[214:215], off
	s_waitcnt vmcnt(8)
	s_waitcnt lgkmcnt(0)
	s_setprio 1
	s_barrier
	v_mfma_f32_16x16x32_bf16 v[124:127], v[144:147], v[182:185], v[124:127]
	v_mfma_f32_16x16x32_bf16 v[120:123], v[158:161], v[182:185], v[120:123]
	v_mfma_f32_16x16x32_bf16 v[108:111], v[144:147], v[190:193], v[108:111]
	v_mfma_f32_16x16x32_bf16 v[104:107], v[158:161], v[190:193], v[104:107]
	v_mfma_f32_16x16x32_bf16 v[88:91], v[144:147], v[198:201], v[88:91]
	v_mfma_f32_16x16x32_bf16 v[92:95], v[158:161], v[198:201], v[92:95]
	v_mfma_f32_16x16x32_bf16 v[72:75], v[144:147], v[206:209], v[72:75]
	v_mfma_f32_16x16x32_bf16 v[76:79], v[158:161], v[206:209], v[76:79]
	v_mfma_f32_16x16x32_bf16 v[124:127], v[154:157], v[186:189], v[124:127]
	v_mfma_f32_16x16x32_bf16 v[120:123], v[162:165], v[186:189], v[120:123]
	v_mfma_f32_16x16x32_bf16 v[108:111], v[154:157], v[194:197], v[108:111]
	v_mfma_f32_16x16x32_bf16 v[104:107], v[162:165], v[194:197], v[104:107]
	v_mfma_f32_16x16x32_bf16 v[88:91], v[154:157], v[202:205], v[88:91]
	v_mfma_f32_16x16x32_bf16 v[92:95], v[162:165], v[202:205], v[92:95]
	v_mfma_f32_16x16x32_bf16 v[72:75], v[154:157], v[210:213], v[72:75]
	v_mfma_f32_16x16x32_bf16 v[76:79], v[162:165], v[210:213], v[76:79]
	s_setprio 0
	s_setprio 1
	v_mfma_f32_16x16x32_bf16 v[116:119], v[166:169], v[182:185], v[116:119]
	v_mfma_f32_16x16x32_bf16 v[112:115], v[174:177], v[182:185], v[112:115]
	v_mfma_f32_16x16x32_bf16 v[96:99], v[166:169], v[190:193], v[96:99]
	v_mfma_f32_16x16x32_bf16 v[100:103], v[174:177], v[190:193], v[100:103]
	v_mfma_f32_16x16x32_bf16 v[80:83], v[166:169], v[198:201], v[80:83]
	v_mfma_f32_16x16x32_bf16 v[84:87], v[174:177], v[198:201], v[84:87]
	v_mfma_f32_16x16x32_bf16 v[64:67], v[166:169], v[206:209], v[64:67]
	v_mfma_f32_16x16x32_bf16 v[68:71], v[174:177], v[206:209], v[68:71]
	v_mfma_f32_16x16x32_bf16 v[116:119], v[170:173], v[186:189], v[116:119]
	v_mfma_f32_16x16x32_bf16 v[112:115], v[178:181], v[186:189], v[112:115]
	v_mfma_f32_16x16x32_bf16 v[96:99], v[170:173], v[194:197], v[96:99]
	v_mfma_f32_16x16x32_bf16 v[100:103], v[178:181], v[194:197], v[100:103]
	v_mfma_f32_16x16x32_bf16 v[80:83], v[170:173], v[202:205], v[80:83]
	v_mfma_f32_16x16x32_bf16 v[84:87], v[178:181], v[202:205], v[84:87]
	v_mfma_f32_16x16x32_bf16 v[64:67], v[170:173], v[210:213], v[64:67]
	v_mfma_f32_16x16x32_bf16 v[68:71], v[178:181], v[210:213], v[68:71]
	s_barrier
	s_setprio 0
	s_add_i32 s49, s40, s29
	v_lshl_add_u64 v[214:215], s[20:21], 0, v[130:131]
	s_mov_b32 m0, s49
	ds_read_b128 v[182:185], v153 offset:16384
	ds_read_b128 v[186:189], v153 offset:17408
	ds_read_b128 v[190:193], v153 offset:18432
	ds_read_b128 v[194:197], v153 offset:19456
	ds_read_b128 v[198:201], v153 offset:20480
	ds_read_b128 v[202:205], v153 offset:21504
	ds_read_b128 v[206:209], v153 offset:22528
	ds_read_b128 v[210:213], v153 offset:23552
	global_load_lds_dwordx4 v[214:215], off
	s_add_i32 m0, s49, 0x2000
	s_add_u32 s52, s20, 0x160000
	v_lshl_add_u64 v[216:217], s[20:21], 0, v[134:135]
	s_addc_u32 s53, s21, 0
	s_add_i32 s49, s41, s29
	global_load_lds_dwordx4 v[216:217], off
	v_lshl_add_u64 v[218:219], s[52:53], 0, v[130:131]
	s_mov_b32 m0, s49
	v_lshl_add_u64 v[220:221], s[26:27], 0, v[132:133]
	global_load_lds_dwordx4 v[218:219], off
	v_lshl_add_u64 v[218:219], s[52:53], 0, v[134:135]
	s_add_i32 m0, s49, 0x2000
	s_nop 0
	global_load_lds_dwordx4 v[218:219], off
	v_lshl_add_u64 v[218:219], s[26:27], 0, v[128:129]
	s_mov_b32 m0, s30
	s_nop 0
	global_load_lds_dwordx4 v[218:219], off
	s_mov_b32 m0, s31
	s_nop 0
	global_load_lds_dwordx4 v[220:221], off
	s_waitcnt vmcnt(8)
	s_waitcnt lgkmcnt(0)
	s_setprio 1
	s_barrier
	v_mfma_f32_16x16x32_bf16 v[56:59], v[144:147], v[182:185], v[56:59]
	v_mfma_f32_16x16x32_bf16 v[60:63], v[158:161], v[182:185], v[60:63]
	v_mfma_f32_16x16x32_bf16 v[40:43], v[144:147], v[190:193], v[40:43]
	v_mfma_f32_16x16x32_bf16 v[44:47], v[158:161], v[190:193], v[44:47]
	v_mfma_f32_16x16x32_bf16 v[24:27], v[144:147], v[198:201], v[24:27]
	v_mfma_f32_16x16x32_bf16 v[28:31], v[158:161], v[198:201], v[28:31]
	v_mfma_f32_16x16x32_bf16 v[8:11], v[144:147], v[206:209], v[8:11]
	v_mfma_f32_16x16x32_bf16 v[12:15], v[158:161], v[206:209], v[12:15]
	v_mfma_f32_16x16x32_bf16 v[56:59], v[154:157], v[186:189], v[56:59]
	v_mfma_f32_16x16x32_bf16 v[60:63], v[162:165], v[186:189], v[60:63]
	v_mfma_f32_16x16x32_bf16 v[40:43], v[154:157], v[194:197], v[40:43]
	v_mfma_f32_16x16x32_bf16 v[44:47], v[162:165], v[194:197], v[44:47]
	v_mfma_f32_16x16x32_bf16 v[24:27], v[154:157], v[202:205], v[24:27]
	v_mfma_f32_16x16x32_bf16 v[28:31], v[162:165], v[202:205], v[28:31]
	v_mfma_f32_16x16x32_bf16 v[8:11], v[154:157], v[210:213], v[8:11]
	v_mfma_f32_16x16x32_bf16 v[12:15], v[162:165], v[210:213], v[12:15]
	s_setprio 0
	s_setprio 1
	v_mfma_f32_16x16x32_bf16 v[48:51], v[166:169], v[182:185], v[48:51]
	v_mfma_f32_16x16x32_bf16 v[52:55], v[174:177], v[182:185], v[52:55]
	v_mfma_f32_16x16x32_bf16 v[32:35], v[166:169], v[190:193], v[32:35]
	v_mfma_f32_16x16x32_bf16 v[36:39], v[174:177], v[190:193], v[36:39]
	v_mfma_f32_16x16x32_bf16 v[16:19], v[166:169], v[198:201], v[16:19]
	v_mfma_f32_16x16x32_bf16 v[20:23], v[174:177], v[198:201], v[20:23]
	v_mfma_f32_16x16x32_bf16 v[0:3], v[166:169], v[206:209], v[0:3]
	v_mfma_f32_16x16x32_bf16 v[4:7], v[174:177], v[206:209], v[4:7]
	v_mfma_f32_16x16x32_bf16 v[48:51], v[170:173], v[186:189], v[48:51]
	v_mfma_f32_16x16x32_bf16 v[52:55], v[178:181], v[186:189], v[52:55]
	v_mfma_f32_16x16x32_bf16 v[32:35], v[170:173], v[194:197], v[32:35]
	v_mfma_f32_16x16x32_bf16 v[36:39], v[178:181], v[194:197], v[36:39]
	v_mfma_f32_16x16x32_bf16 v[16:19], v[170:173], v[202:205], v[16:19]
	v_mfma_f32_16x16x32_bf16 v[20:23], v[178:181], v[202:205], v[20:23]
	v_mfma_f32_16x16x32_bf16 v[0:3], v[170:173], v[210:213], v[0:3]
	v_mfma_f32_16x16x32_bf16 v[4:7], v[178:181], v[210:213], v[4:7]
	s_barrier
	s_setprio 0
	s_add_i32 s49, 0, 0x18000
	s_add_i32 s52, 0, 0x1c000
	v_add_u32_e32 v162, s49, v149
	v_add_u32_e32 v178, s52, v149
	ds_read_b128 v[144:147], v162
	ds_read_b128 v[154:157], v162 offset:1024
	ds_read_b128 v[158:161], v162 offset:2048
	ds_read_b128 v[162:165], v162 offset:3072
	ds_read_b128 v[166:169], v178
	ds_read_b128 v[170:173], v178 offset:1024
	ds_read_b128 v[174:177], v178 offset:2048
	ds_read_b128 v[178:181], v178 offset:3072
	s_add_u32 s26, s26, 0x160000
	s_addc_u32 s27, s27, 0
	s_mov_b32 m0, s34
	v_lshl_add_u64 v[222:223], s[26:27], 0, v[128:129]
	ds_read_b128 v[182:185], v153 offset:32768
	ds_read_b128 v[186:189], v153 offset:33792
	ds_read_b128 v[190:193], v153 offset:34816
	ds_read_b128 v[194:197], v153 offset:35840
	ds_read_b128 v[198:201], v153 offset:36864
	ds_read_b128 v[202:205], v153 offset:37888
	ds_read_b128 v[206:209], v153 offset:38912
	ds_read_b128 v[210:213], v153 offset:39936
	global_load_lds_dwordx4 v[222:223], off
	v_lshl_add_u64 v[222:223], s[26:27], 0, v[132:133]
	s_mov_b32 m0, s35
	s_nop 0
	global_load_lds_dwordx4 v[222:223], off
	s_waitcnt vmcnt(8)
	s_waitcnt lgkmcnt(0)
	s_setprio 1
	s_barrier
	v_mfma_f32_16x16x32_bf16 v[124:127], v[144:147], v[182:185], v[124:127]
	v_mfma_f32_16x16x32_bf16 v[120:123], v[158:161], v[182:185], v[120:123]
	v_mfma_f32_16x16x32_bf16 v[108:111], v[144:147], v[190:193], v[108:111]
	v_mfma_f32_16x16x32_bf16 v[104:107], v[158:161], v[190:193], v[104:107]
	v_mfma_f32_16x16x32_bf16 v[88:91], v[144:147], v[198:201], v[88:91]
	v_mfma_f32_16x16x32_bf16 v[92:95], v[158:161], v[198:201], v[92:95]
	v_mfma_f32_16x16x32_bf16 v[72:75], v[144:147], v[206:209], v[72:75]
	v_mfma_f32_16x16x32_bf16 v[76:79], v[158:161], v[206:209], v[76:79]
	v_mfma_f32_16x16x32_bf16 v[124:127], v[154:157], v[186:189], v[124:127]
	v_mfma_f32_16x16x32_bf16 v[120:123], v[162:165], v[186:189], v[120:123]
	v_mfma_f32_16x16x32_bf16 v[108:111], v[154:157], v[194:197], v[108:111]
	v_mfma_f32_16x16x32_bf16 v[104:107], v[162:165], v[194:197], v[104:107]
	v_mfma_f32_16x16x32_bf16 v[88:91], v[154:157], v[202:205], v[88:91]
	v_mfma_f32_16x16x32_bf16 v[92:95], v[162:165], v[202:205], v[92:95]
	v_mfma_f32_16x16x32_bf16 v[72:75], v[154:157], v[210:213], v[72:75]
	v_mfma_f32_16x16x32_bf16 v[76:79], v[162:165], v[210:213], v[76:79]
	s_setprio 0
	s_setprio 1
	v_mfma_f32_16x16x32_bf16 v[116:119], v[166:169], v[182:185], v[116:119]
	v_mfma_f32_16x16x32_bf16 v[112:115], v[174:177], v[182:185], v[112:115]
	v_mfma_f32_16x16x32_bf16 v[96:99], v[166:169], v[190:193], v[96:99]
	v_mfma_f32_16x16x32_bf16 v[100:103], v[174:177], v[190:193], v[100:103]
	v_mfma_f32_16x16x32_bf16 v[80:83], v[166:169], v[198:201], v[80:83]
	v_mfma_f32_16x16x32_bf16 v[84:87], v[174:177], v[198:201], v[84:87]
	v_mfma_f32_16x16x32_bf16 v[64:67], v[166:169], v[206:209], v[64:67]
	v_mfma_f32_16x16x32_bf16 v[68:71], v[174:177], v[206:209], v[68:71]
	v_mfma_f32_16x16x32_bf16 v[116:119], v[170:173], v[186:189], v[116:119]
	v_mfma_f32_16x16x32_bf16 v[112:115], v[178:181], v[186:189], v[112:115]
	v_mfma_f32_16x16x32_bf16 v[96:99], v[170:173], v[194:197], v[96:99]
	v_mfma_f32_16x16x32_bf16 v[100:103], v[178:181], v[194:197], v[100:103]
	v_mfma_f32_16x16x32_bf16 v[80:83], v[170:173], v[202:205], v[80:83]
	v_mfma_f32_16x16x32_bf16 v[84:87], v[178:181], v[202:205], v[84:87]
	v_mfma_f32_16x16x32_bf16 v[64:67], v[170:173], v[210:213], v[64:67]
	v_mfma_f32_16x16x32_bf16 v[68:71], v[178:181], v[210:213], v[68:71]
	s_barrier
	s_setprio 0
	s_add_i32 s26, s49, s29
	v_lshl_add_u64 v[214:215], v[214:215], 0, s[8:9]
	s_mov_b32 m0, s26
	ds_read_b128 v[182:185], v153 offset:49152
	ds_read_b128 v[186:189], v153 offset:50176
	ds_read_b128 v[190:193], v153 offset:51200
	ds_read_b128 v[194:197], v153 offset:52224
	ds_read_b128 v[198:201], v153 offset:53248
	ds_read_b128 v[202:205], v153 offset:54272
	ds_read_b128 v[206:209], v153 offset:55296
	ds_read_b128 v[210:213], v153 offset:56320
	global_load_lds_dwordx4 v[214:215], off
	s_add_i32 m0, s26, 0x2000
	s_add_u32 s20, s20, 0x160080
	v_lshl_add_u64 v[214:215], v[216:217], 0, s[8:9]
	s_addc_u32 s21, s21, 0
	s_add_i32 s26, s52, s29
	global_load_lds_dwordx4 v[214:215], off
	v_lshl_add_u64 v[214:215], s[20:21], 0, v[130:131]
	s_mov_b32 m0, s26
	s_nop 0
	global_load_lds_dwordx4 v[214:215], off
	v_lshl_add_u64 v[214:215], s[20:21], 0, v[134:135]
	s_add_i32 m0, s26, 0x2000
	s_nop 0
	global_load_lds_dwordx4 v[214:215], off
	v_lshl_add_u64 v[214:215], v[218:219], 0, s[8:9]
	s_mov_b32 m0, s37
	s_nop 0
	global_load_lds_dwordx4 v[214:215], off
	v_lshl_add_u64 v[214:215], v[220:221], 0, s[8:9]
	s_mov_b32 m0, s38
	s_nop 0
	global_load_lds_dwordx4 v[214:215], off
	s_waitcnt vmcnt(8)
	s_waitcnt lgkmcnt(0)
	s_setprio 1
	s_barrier
	v_mfma_f32_16x16x32_bf16 v[56:59], v[144:147], v[182:185], v[56:59]
	v_mfma_f32_16x16x32_bf16 v[60:63], v[158:161], v[182:185], v[60:63]
	v_mfma_f32_16x16x32_bf16 v[40:43], v[144:147], v[190:193], v[40:43]
	v_mfma_f32_16x16x32_bf16 v[44:47], v[158:161], v[190:193], v[44:47]
	v_mfma_f32_16x16x32_bf16 v[24:27], v[144:147], v[198:201], v[24:27]
	v_mfma_f32_16x16x32_bf16 v[28:31], v[158:161], v[198:201], v[28:31]
	v_mfma_f32_16x16x32_bf16 v[8:11], v[144:147], v[206:209], v[8:11]
	v_mfma_f32_16x16x32_bf16 v[12:15], v[158:161], v[206:209], v[12:15]
	v_mfma_f32_16x16x32_bf16 v[56:59], v[154:157], v[186:189], v[56:59]
	v_mfma_f32_16x16x32_bf16 v[60:63], v[162:165], v[186:189], v[60:63]
	v_mfma_f32_16x16x32_bf16 v[40:43], v[154:157], v[194:197], v[40:43]
	v_mfma_f32_16x16x32_bf16 v[44:47], v[162:165], v[194:197], v[44:47]
	v_mfma_f32_16x16x32_bf16 v[24:27], v[154:157], v[202:205], v[24:27]
	v_mfma_f32_16x16x32_bf16 v[28:31], v[162:165], v[202:205], v[28:31]
	v_mfma_f32_16x16x32_bf16 v[8:11], v[154:157], v[210:213], v[8:11]
	v_mfma_f32_16x16x32_bf16 v[12:15], v[162:165], v[210:213], v[12:15]
	s_setprio 0
	s_setprio 1
	v_mfma_f32_16x16x32_bf16 v[48:51], v[166:169], v[182:185], v[48:51]
	v_mfma_f32_16x16x32_bf16 v[52:55], v[174:177], v[182:185], v[52:55]
	v_mfma_f32_16x16x32_bf16 v[32:35], v[166:169], v[190:193], v[32:35]
	v_mfma_f32_16x16x32_bf16 v[36:39], v[174:177], v[190:193], v[36:39]
	v_mfma_f32_16x16x32_bf16 v[16:19], v[166:169], v[198:201], v[16:19]
	v_mfma_f32_16x16x32_bf16 v[20:23], v[174:177], v[198:201], v[20:23]
	v_mfma_f32_16x16x32_bf16 v[0:3], v[166:169], v[206:209], v[0:3]
	v_mfma_f32_16x16x32_bf16 v[4:7], v[174:177], v[206:209], v[4:7]
	v_mfma_f32_16x16x32_bf16 v[48:51], v[170:173], v[186:189], v[48:51]
	v_mfma_f32_16x16x32_bf16 v[52:55], v[178:181], v[186:189], v[52:55]
	v_mfma_f32_16x16x32_bf16 v[32:35], v[170:173], v[194:197], v[32:35]
	v_mfma_f32_16x16x32_bf16 v[36:39], v[178:181], v[194:197], v[36:39]
	v_mfma_f32_16x16x32_bf16 v[16:19], v[170:173], v[202:205], v[16:19]
	v_mfma_f32_16x16x32_bf16 v[20:23], v[178:181], v[202:205], v[20:23]
	v_mfma_f32_16x16x32_bf16 v[0:3], v[170:173], v[210:213], v[0:3]
	v_mfma_f32_16x16x32_bf16 v[4:7], v[178:181], v[210:213], v[4:7]
	s_barrier
	s_setprio 0
	s_add_i32 s48, s48, 2
	s_add_u32 s16, s16, 0x100
	s_addc_u32 s17, s17, 0
	s_add_u32 s46, s46, 0x100
	s_addc_u32 s47, s47, 0
	s_cmpk_gt_u32 s48, 0x55
	s_cbranch_scc0 .LBB0_1566
	s_and_b64 vcc, exec, s[10:11]
	s_cbranch_vccz .LBB0_1569
	s_barrier
